# stack: merged K-loop waits + 4th-segment DMA address reuse via offset:128 (6 fewer VALU per K-loop iteration) + single-pass FoX cumsum + rows-ssq pointer in SGPR + attention kernel-params loads hoiste
# speedup vs baseline: 1.0218x; 1.0023x over previous
; #define PG8_STAGE(bufoff, gbase, voff) do { _Pragma("unroll") for (int _i = 0; _i < 2; ++_i) \
;         __builtin_amdgcn_global_load_lds((const unsigned*)((const char*)(gbase) + (voff)[_i]), (PG8_LAS unsigned*)(lds + (bufoff) + ldsw + _i * 8192), 16, 0, 0); } while (0)
; #define PG8_LDA(dst, b, h) do { _Pragma("unroll") for (int m = 0; m < 4; ++m) _Pragma("unroll") for (int k = 0; k < 2; ++k) dst[m][k] = *(const PG8_LAS bf16x8*)(lds + PG8_SA(b, h) + aoff + m * 2048 + k * 1024); } while (0)
; #define PG8_LDB(dst, b, h) do { _Pragma("unroll") for (int n = 0; n < 2; ++n) _Pragma("unroll") for (int k = 0; k < 2; ++k) dst[n][k] = *(const PG8_LAS bf16x8*)(lds + PG8_SB(b, h) + boff + n * 2048 + k * 1024); } while (0)
; #define PG8_MMA(ai, bj, At, Bt) do { __builtin_amdgcn_s_setprio(1); _Pragma("unroll") for (int m = 0; m < 4; ++m) _Pragma("unroll") for (int n = 0; n < 2; ++n) _Pragma("unroll") for (int k = 0; k < 2; ++k) \
;         acc[ai][bj][m][n] = __builtin_amdgcn_mfma_f32_16x16x32_bf16(Bt[n][k], At[m][k], acc[ai][bj][m][n], 0, 0, 0); __builtin_amdgcn_s_setprio(0); } while (0)
; #define PG8_WAIT_V(n) asm volatile("s_waitcnt vmcnt(" #n ")" ::: "memory")
; #define PG8_BAR __builtin_amdgcn_s_barrier()
; template <class Epi, class Sched, bool ALIGN_EPI = false, bool SP2 = false>
; __device__ __forceinline__ void gemm_phase(PG8_LAS unsigned char* lds, const Gemm g, const Sched& S, const Epi& E) {
;     ...
;         for (int t = 0; t < nt; t += 2) {
;             const bool last = (t == nt - 2);
;             const char* a1 = cA + (size_t)(t + 1) * kstep;
;             const char* a2 = last ? nA : cA + (size_t)(t + 2) * kstep; const char* b2 = last ? nB : cB + (size_t)(t + 2) * kstep;
;             const char* a3 = a2 + kstep; const char* b3 = b2 + kstep;
;             if (last && has_next) S.a_ready(nxt);
;             if constexpr (SP2) {
;             PG8_LDB(B0, 0, 0); PG8_LDB(B1, 0, 1); PG8_SCHED; PG8_LDA(At, 0, 0); PG8_STAGE(PG8_SA(1, 1), a1 + hstep, voffA);
;             PG8_WAIT_V(8); PG8_WAIT_L(0); PG8_BAR; PG8_MMA(0, 0, At, B0); PG8_MMA(0, 1, At, B1); PG8_BAR; PG8_SCHED;
;             PG8_LDA(At, 0, 1); PG8_STAGE(PG8_SB(0, 0), b2, voffB); PG8_STAGE(PG8_SB(0, 1), b2 + hstep, voffB); PG8_STAGE(PG8_SA(0, 0), a2, voffA);
;             PG8_WAIT_V(8); PG8_WAIT_L(0); PG8_BAR; PG8_MMA(1, 0, At, B0); PG8_MMA(1, 1, At, B1); PG8_BAR; PG8_SCHED;
.LBB0_304:
	v_add_u32_e32 v166, s54, v169
	v_add_u32_e32 v168, s55, v169
	ds_read_b128 v[162:165], v166
	ds_read_b128 v[182:185], v166 offset:1024
	ds_read_b128 v[186:189], v166 offset:2048
	ds_read_b128 v[190:193], v166 offset:3072
	ds_read_b128 v[194:197], v168
	ds_read_b128 v[198:201], v168 offset:1024
	ds_read_b128 v[202:205], v168 offset:2048
	ds_read_b128 v[206:209], v168 offset:3072
	s_cmp_eq_u32 s53, s10
	v_lshl_add_u64 v[172:173], v[160:161], 0, s[22:23]
	s_cselect_b64 vcc, -1, 0
	s_add_i32 s10, s10, 2
	v_cndmask_b32_e32 v173, v173, v153, vcc
	v_cndmask_b32_e32 v172, v172, v152, vcc
	v_cndmask_b32_e32 v245, v159, v155, vcc
	v_cndmask_b32_e32 v244, v158, v154, vcc
	s_mov_b32 m0, s56
	v_lshl_add_u64 v[246:247], v[160:161], 0, v[148:149]
	ds_read_b128 v[210:213], v179
	ds_read_b128 v[216:219], v179 offset:1024
	ds_read_b128 v[220:223], v179 offset:2048
	ds_read_b128 v[224:227], v179 offset:3072
	ds_read_b128 v[228:231], v179 offset:4096
	ds_read_b128 v[232:235], v179 offset:5120
	ds_read_b128 v[236:239], v179 offset:6144
	ds_read_b128 v[240:243], v179 offset:7168
	global_load_lds_dwordx4 v[246:247], off
	s_mov_b32 m0, s57
	v_lshl_add_u64 v[246:247], v[160:161], 0, v[146:147]
	global_load_lds_dwordx4 v[246:247], off
	s_waitcnt vmcnt(8) lgkmcnt(0)
	s_setprio 1
	s_barrier
	v_mfma_f32_16x16x32_bf16 v[124:127], v[162:165], v[210:213], v[124:127]
	v_mfma_f32_16x16x32_bf16 v[116:119], v[186:189], v[210:213], v[116:119]
	v_mfma_f32_16x16x32_bf16 v[108:111], v[162:165], v[220:223], v[108:111]
	v_mfma_f32_16x16x32_bf16 v[100:103], v[186:189], v[220:223], v[100:103]
	v_mfma_f32_16x16x32_bf16 v[92:95], v[162:165], v[228:231], v[92:95]
	v_mfma_f32_16x16x32_bf16 v[84:87], v[186:189], v[228:231], v[84:87]
	v_mfma_f32_16x16x32_bf16 v[76:79], v[162:165], v[236:239], v[76:79]
	v_mfma_f32_16x16x32_bf16 v[68:71], v[186:189], v[236:239], v[68:71]
	v_mfma_f32_16x16x32_bf16 v[124:127], v[182:185], v[216:219], v[124:127]
	v_mfma_f32_16x16x32_bf16 v[116:119], v[190:193], v[216:219], v[116:119]
	v_mfma_f32_16x16x32_bf16 v[108:111], v[182:185], v[224:227], v[108:111]
	v_mfma_f32_16x16x32_bf16 v[100:103], v[190:193], v[224:227], v[100:103]
	v_mfma_f32_16x16x32_bf16 v[92:95], v[182:185], v[232:235], v[92:95]
	v_mfma_f32_16x16x32_bf16 v[84:87], v[190:193], v[232:235], v[84:87]
	v_mfma_f32_16x16x32_bf16 v[76:79], v[182:185], v[240:243], v[76:79]
	v_mfma_f32_16x16x32_bf16 v[68:71], v[190:193], v[240:243], v[68:71]
	v_mfma_f32_16x16x32_bf16 v[120:123], v[194:197], v[210:213], v[120:123]
	v_mfma_f32_16x16x32_bf16 v[112:115], v[202:205], v[210:213], v[112:115]
	v_mfma_f32_16x16x32_bf16 v[104:107], v[194:197], v[220:223], v[104:107]
	v_mfma_f32_16x16x32_bf16 v[96:99], v[202:205], v[220:223], v[96:99]
	v_mfma_f32_16x16x32_bf16 v[88:91], v[194:197], v[228:231], v[88:91]
	v_mfma_f32_16x16x32_bf16 v[80:83], v[202:205], v[228:231], v[80:83]
	v_mfma_f32_16x16x32_bf16 v[72:75], v[194:197], v[236:239], v[72:75]
	v_mfma_f32_16x16x32_bf16 v[64:67], v[202:205], v[236:239], v[64:67]
	v_mfma_f32_16x16x32_bf16 v[120:123], v[198:201], v[216:219], v[120:123]
	v_mfma_f32_16x16x32_bf16 v[112:115], v[206:209], v[216:219], v[112:115]
	v_mfma_f32_16x16x32_bf16 v[104:107], v[198:201], v[224:227], v[104:107]
	v_mfma_f32_16x16x32_bf16 v[96:99], v[206:209], v[224:227], v[96:99]
	v_mfma_f32_16x16x32_bf16 v[88:91], v[198:201], v[232:235], v[88:91]
	v_mfma_f32_16x16x32_bf16 v[80:83], v[206:209], v[232:235], v[80:83]
	v_mfma_f32_16x16x32_bf16 v[72:75], v[198:201], v[240:243], v[72:75]
	v_mfma_f32_16x16x32_bf16 v[64:67], v[206:209], v[240:243], v[64:67]
	s_setprio 0
	s_barrier
	s_mov_b32 m0, s60
	v_lshl_add_u64 v[246:247], v[244:245], 0, v[138:139]
	ds_read_b128 v[210:213], v179 offset:16384
	ds_read_b128 v[216:219], v179 offset:17408
	ds_read_b128 v[220:223], v179 offset:18432
	ds_read_b128 v[224:227], v179 offset:19456
	ds_read_b128 v[228:231], v179 offset:20480
	ds_read_b128 v[232:235], v179 offset:21504
	ds_read_b128 v[236:239], v179 offset:22528
	ds_read_b128 v[240:243], v179 offset:23552
	global_load_lds_dwordx4 v[246:247], off
	v_lshl_add_u64 v[248:249], v[244:245], 0, v[134:135]
	s_mov_b32 m0, s61
	v_lshl_add_u64 v[244:245], v[244:245], 0, s[14:15]
	global_load_lds_dwordx4 v[248:249], off
	v_lshl_add_u64 v[250:251], v[244:245], 0, v[138:139]
	s_mov_b32 m0, s62
	v_lshl_add_u64 v[244:245], v[244:245], 0, v[134:135]
	global_load_lds_dwordx4 v[250:251], off
	s_add_i32 m0, s62, 0x2000
	v_lshl_add_u64 v[252:253], v[172:173], 0, v[140:141]
	global_load_lds_dwordx4 v[244:245], off
	s_mov_b32 m0, s46
	v_lshl_add_u64 v[214:215], v[172:173], 0, v[136:137]
	global_load_lds_dwordx4 v[252:253], off
	s_mov_b32 m0, s47
	s_nop 0
	global_load_lds_dwordx4 v[214:215], off
	s_waitcnt vmcnt(8) lgkmcnt(0)
	s_setprio 1
	s_barrier
; #define PG8_STAGE(bufoff, gbase, voff) do { _Pragma("unroll") for (int _i = 0; _i < 2; ++_i) \
;         __builtin_amdgcn_global_load_lds((const unsigned*)((const char*)(gbase) + (voff)[_i]), (PG8_LAS unsigned*)(lds + (bufoff) + ldsw + _i * 8192), 16, 0, 0); } while (0)
; #define PG8_LDA(dst, b, h) do { _Pragma("unroll") for (int m = 0; m < 4; ++m) _Pragma("unroll") for (int k = 0; k < 2; ++k) dst[m][k] = *(const PG8_LAS bf16x8*)(lds + PG8_SA(b, h) + aoff + m * 2048 + k * 1024); } while (0)
; #define PG8_LDB(dst, b, h) do { _Pragma("unroll") for (int n = 0; n < 2; ++n) _Pragma("unroll") for (int k = 0; k < 2; ++k) dst[n][k] = *(const PG8_LAS bf16x8*)(lds + PG8_SB(b, h) + boff + n * 2048 + k * 1024); } while (0)
; #define PG8_MMA(ai, bj, At, Bt) do { __builtin_amdgcn_s_setprio(1); _Pragma("unroll") for (int m = 0; m < 4; ++m) _Pragma("unroll") for (int n = 0; n < 2; ++n) _Pragma("unroll") for (int k = 0; k < 2; ++k) \
;         acc[ai][bj][m][n] = __builtin_amdgcn_mfma_f32_16x16x32_bf16(Bt[n][k], At[m][k], acc[ai][bj][m][n], 0, 0, 0); __builtin_amdgcn_s_setprio(0); } while (0)
; #define PG8_WAIT_V(n) asm volatile("s_waitcnt vmcnt(" #n ")" ::: "memory")
; #define PG8_WAIT_L(n) asm volatile("s_waitcnt lgkmcnt(" #n ")" ::: "memory")
; #define PG8_BAR __builtin_amdgcn_s_barrier()
; #define PG8_SCHED __builtin_amdgcn_sched_barrier(0)
; template <class Epi, class Sched, bool ALIGN_EPI = false, bool SP2 = false>
; __device__ __forceinline__ void gemm_phase(PG8_LAS unsigned char* lds, const Gemm g, const Sched& S, const Epi& E) {
;     ...
;             PG8_WAIT_V(8); PG8_WAIT_L(0); PG8_BAR; PG8_MMA(1, 0, At, B0); PG8_MMA(1, 1, At, B1); PG8_BAR; PG8_SCHED;
;             PG8_LDB(B0, 1, 0); PG8_LDB(B1, 1, 1); PG8_SCHED; PG8_LDA(At, 1, 0); PG8_STAGE(PG8_SA(0, 1), a2 + hstep, voffA);
;             PG8_WAIT_V(8); PG8_WAIT_L(0); PG8_BAR; PG8_MMA(0, 0, At, B0); PG8_MMA(0, 1, At, B1); PG8_BAR; PG8_SCHED;
	v_mfma_f32_16x16x32_bf16 v[60:63], v[162:165], v[210:213], v[60:63]
	v_mfma_f32_16x16x32_bf16 v[52:55], v[186:189], v[210:213], v[52:55]
	v_mfma_f32_16x16x32_bf16 v[44:47], v[162:165], v[220:223], v[44:47]
	v_mfma_f32_16x16x32_bf16 v[36:39], v[186:189], v[220:223], v[36:39]
	v_mfma_f32_16x16x32_bf16 v[28:31], v[162:165], v[228:231], v[28:31]
	v_mfma_f32_16x16x32_bf16 v[20:23], v[186:189], v[228:231], v[20:23]
	v_mfma_f32_16x16x32_bf16 v[12:15], v[162:165], v[236:239], v[12:15]
	v_mfma_f32_16x16x32_bf16 v[4:7], v[186:189], v[236:239], v[4:7]
	v_mfma_f32_16x16x32_bf16 v[60:63], v[182:185], v[216:219], v[60:63]
	v_mfma_f32_16x16x32_bf16 v[52:55], v[190:193], v[216:219], v[52:55]
	v_mfma_f32_16x16x32_bf16 v[44:47], v[182:185], v[224:227], v[44:47]
	v_mfma_f32_16x16x32_bf16 v[36:39], v[190:193], v[224:227], v[36:39]
	v_mfma_f32_16x16x32_bf16 v[28:31], v[182:185], v[232:235], v[28:31]
	v_mfma_f32_16x16x32_bf16 v[20:23], v[190:193], v[232:235], v[20:23]
	v_mfma_f32_16x16x32_bf16 v[12:15], v[182:185], v[240:243], v[12:15]
	v_mfma_f32_16x16x32_bf16 v[4:7], v[190:193], v[240:243], v[4:7]
	v_mfma_f32_16x16x32_bf16 v[56:59], v[194:197], v[210:213], v[56:59]
	v_mfma_f32_16x16x32_bf16 v[48:51], v[202:205], v[210:213], v[48:51]
	v_mfma_f32_16x16x32_bf16 v[40:43], v[194:197], v[220:223], v[40:43]
	v_mfma_f32_16x16x32_bf16 v[32:35], v[202:205], v[220:223], v[32:35]
	v_mfma_f32_16x16x32_bf16 v[24:27], v[194:197], v[228:231], v[24:27]
	v_mfma_f32_16x16x32_bf16 v[16:19], v[202:205], v[228:231], v[16:19]
	v_mfma_f32_16x16x32_bf16 v[8:11], v[194:197], v[236:239], v[8:11]
	v_mfma_f32_16x16x32_bf16 v[0:3], v[202:205], v[236:239], v[0:3]
	v_mfma_f32_16x16x32_bf16 v[56:59], v[198:201], v[216:219], v[56:59]
	v_mfma_f32_16x16x32_bf16 v[48:51], v[206:209], v[216:219], v[48:51]
	v_mfma_f32_16x16x32_bf16 v[40:43], v[198:201], v[224:227], v[40:43]
	v_mfma_f32_16x16x32_bf16 v[32:35], v[206:209], v[224:227], v[32:35]
	v_mfma_f32_16x16x32_bf16 v[24:27], v[198:201], v[232:235], v[24:27]
	v_mfma_f32_16x16x32_bf16 v[16:19], v[206:209], v[232:235], v[16:19]
	v_mfma_f32_16x16x32_bf16 v[8:11], v[198:201], v[240:243], v[8:11]
	v_mfma_f32_16x16x32_bf16 v[0:3], v[206:209], v[240:243], v[0:3]
	s_setprio 0
	s_barrier
	s_add_i32 s11, 0, 0x18000
	v_add_u32_e32 v166, s11, v169
	s_add_i32 s13, 0, 0x1c000
	ds_read_b128 v[162:165], v166
	ds_read_b128 v[182:185], v166 offset:1024
	ds_read_b128 v[186:189], v166 offset:2048
	ds_read_b128 v[190:193], v166 offset:3072
	v_add_u32_e32 v166, s13, v169
	ds_read_b128 v[194:197], v166
	ds_read_b128 v[198:201], v166 offset:1024
	ds_read_b128 v[202:205], v166 offset:2048
	ds_read_b128 v[206:209], v166 offset:3072
	v_lshl_add_u64 v[172:173], v[172:173], 0, s[14:15]
	s_mov_b32 m0, s48
	v_lshl_add_u64 v[170:171], v[172:173], 0, v[140:141]
	ds_read_b128 v[210:213], v179 offset:32768
	ds_read_b128 v[216:219], v179 offset:33792
	ds_read_b128 v[220:223], v179 offset:34816
	ds_read_b128 v[224:227], v179 offset:35840
	ds_read_b128 v[228:231], v179 offset:36864
	ds_read_b128 v[232:235], v179 offset:37888
	ds_read_b128 v[236:239], v179 offset:38912
	ds_read_b128 v[240:243], v179 offset:39936
	global_load_lds_dwordx4 v[170:171], off
	s_mov_b32 m0, s49
	v_lshl_add_u64 v[170:171], v[172:173], 0, v[136:137]
	global_load_lds_dwordx4 v[170:171], off
	s_waitcnt vmcnt(8) lgkmcnt(0)
	s_setprio 1
	s_barrier
; #define PG8_STAGE(bufoff, gbase, voff) do { _Pragma("unroll") for (int _i = 0; _i < 2; ++_i) \
;         __builtin_amdgcn_global_load_lds((const unsigned*)((const char*)(gbase) + (voff)[_i]), (PG8_LAS unsigned*)(lds + (bufoff) + ldsw + _i * 8192), 16, 0, 0); } while (0)
; #define PG8_LDA(dst, b, h) do { _Pragma("unroll") for (int m = 0; m < 4; ++m) _Pragma("unroll") for (int k = 0; k < 2; ++k) dst[m][k] = *(const PG8_LAS bf16x8*)(lds + PG8_SA(b, h) + aoff + m * 2048 + k * 1024); } while (0)
; #define PG8_MMA(ai, bj, At, Bt) do { __builtin_amdgcn_s_setprio(1); _Pragma("unroll") for (int m = 0; m < 4; ++m) _Pragma("unroll") for (int n = 0; n < 2; ++n) _Pragma("unroll") for (int k = 0; k < 2; ++k) \
;         acc[ai][bj][m][n] = __builtin_amdgcn_mfma_f32_16x16x32_bf16(Bt[n][k], At[m][k], acc[ai][bj][m][n], 0, 0, 0); __builtin_amdgcn_s_setprio(0); } while (0)
; #define PG8_WAIT_V(n) asm volatile("s_waitcnt vmcnt(" #n ")" ::: "memory")
; #define PG8_WAIT_L(n) asm volatile("s_waitcnt lgkmcnt(" #n ")" ::: "memory")
; #define PG8_BAR __builtin_amdgcn_s_barrier()
; #define PG8_SCHED __builtin_amdgcn_sched_barrier(0)
; template <class Epi, class Sched, bool ALIGN_EPI = false, bool SP2 = false>
; __device__ __forceinline__ void gemm_phase(PG8_LAS unsigned char* lds, const Gemm g, const Sched& S, const Epi& E) {
;     ...
;             PG8_WAIT_V(8); PG8_WAIT_L(0); PG8_BAR; PG8_MMA(0, 0, At, B0); PG8_MMA(0, 1, At, B1); PG8_BAR; PG8_SCHED;
;             PG8_LDA(At, 1, 1); PG8_STAGE(PG8_SB(1, 0), b3, voffB); PG8_STAGE(PG8_SB(1, 1), b3 + hstep, voffB); PG8_STAGE(PG8_SA(1, 0), a3, voffA);
;             PG8_WAIT_V(8); PG8_WAIT_L(0); PG8_BAR; PG8_MMA(1, 0, At, B0); PG8_MMA(1, 1, At, B1); PG8_BAR; PG8_SCHED;
	v_mfma_f32_16x16x32_bf16 v[124:127], v[162:165], v[210:213], v[124:127]
	v_mfma_f32_16x16x32_bf16 v[116:119], v[186:189], v[210:213], v[116:119]
	v_mfma_f32_16x16x32_bf16 v[108:111], v[162:165], v[220:223], v[108:111]
	v_mfma_f32_16x16x32_bf16 v[100:103], v[186:189], v[220:223], v[100:103]
	v_mfma_f32_16x16x32_bf16 v[92:95], v[162:165], v[228:231], v[92:95]
	v_mfma_f32_16x16x32_bf16 v[84:87], v[186:189], v[228:231], v[84:87]
	v_mfma_f32_16x16x32_bf16 v[76:79], v[162:165], v[236:239], v[76:79]
	v_mfma_f32_16x16x32_bf16 v[68:71], v[186:189], v[236:239], v[68:71]
	v_mfma_f32_16x16x32_bf16 v[124:127], v[182:185], v[216:219], v[124:127]
	v_mfma_f32_16x16x32_bf16 v[116:119], v[190:193], v[216:219], v[116:119]
	v_mfma_f32_16x16x32_bf16 v[108:111], v[182:185], v[224:227], v[108:111]
	v_mfma_f32_16x16x32_bf16 v[100:103], v[190:193], v[224:227], v[100:103]
	v_mfma_f32_16x16x32_bf16 v[92:95], v[182:185], v[232:235], v[92:95]
	v_mfma_f32_16x16x32_bf16 v[84:87], v[190:193], v[232:235], v[84:87]
	v_mfma_f32_16x16x32_bf16 v[76:79], v[182:185], v[240:243], v[76:79]
	v_mfma_f32_16x16x32_bf16 v[68:71], v[190:193], v[240:243], v[68:71]
	v_mfma_f32_16x16x32_bf16 v[120:123], v[194:197], v[210:213], v[120:123]
	v_mfma_f32_16x16x32_bf16 v[112:115], v[202:205], v[210:213], v[112:115]
	v_mfma_f32_16x16x32_bf16 v[104:107], v[194:197], v[220:223], v[104:107]
	v_mfma_f32_16x16x32_bf16 v[96:99], v[202:205], v[220:223], v[96:99]
	v_mfma_f32_16x16x32_bf16 v[88:91], v[194:197], v[228:231], v[88:91]
	v_mfma_f32_16x16x32_bf16 v[80:83], v[202:205], v[228:231], v[80:83]
	v_mfma_f32_16x16x32_bf16 v[72:75], v[194:197], v[236:239], v[72:75]
	v_mfma_f32_16x16x32_bf16 v[64:67], v[202:205], v[236:239], v[64:67]
	v_mfma_f32_16x16x32_bf16 v[120:123], v[198:201], v[216:219], v[120:123]
	v_mfma_f32_16x16x32_bf16 v[112:115], v[206:209], v[216:219], v[112:115]
	v_mfma_f32_16x16x32_bf16 v[104:107], v[198:201], v[224:227], v[104:107]
	v_mfma_f32_16x16x32_bf16 v[96:99], v[206:209], v[224:227], v[96:99]
	v_mfma_f32_16x16x32_bf16 v[88:91], v[198:201], v[232:235], v[88:91]
	v_mfma_f32_16x16x32_bf16 v[80:83], v[206:209], v[232:235], v[80:83]
	v_mfma_f32_16x16x32_bf16 v[72:75], v[198:201], v[240:243], v[72:75]
	v_mfma_f32_16x16x32_bf16 v[64:67], v[206:209], v[240:243], v[64:67]
	s_setprio 0
	s_barrier
	s_add_i32 s11, s11, s29
	s_add_i32 m0, s11, 0xffffff80
	ds_read_b128 v[210:213], v179 offset:49152
	ds_read_b128 v[216:219], v179 offset:50176
	ds_read_b128 v[220:223], v179 offset:51200
	ds_read_b128 v[224:227], v179 offset:52224
	global_load_lds_dwordx4 v[246:247], off offset:128
	s_add_i32 m0, s11, 0x1f80
	s_add_i32 s11, s13, s29
	global_load_lds_dwordx4 v[248:249], off offset:128
	s_add_i32 m0, s11, 0xffffff80
	ds_read_b128 v[240:243], v179 offset:56320
	global_load_lds_dwordx4 v[250:251], off offset:128
	s_add_i32 m0, s11, 0x1f80
	ds_read_b128 v[236:239], v179 offset:55296
	global_load_lds_dwordx4 v[244:245], off offset:128
	s_add_i32 m0, s50, 0xffffff80
	ds_read_b128 v[232:235], v179 offset:54272
	global_load_lds_dwordx4 v[252:253], off offset:128
	s_add_i32 m0, s51, 0xffffff80
	ds_read_b128 v[228:231], v179 offset:53248
	global_load_lds_dwordx4 v[214:215], off offset:128
	s_waitcnt vmcnt(8) lgkmcnt(0)
	s_setprio 1
	s_barrier
	v_mfma_f32_16x16x32_bf16 v[60:63], v[162:165], v[210:213], v[60:63]
	v_mfma_f32_16x16x32_bf16 v[52:55], v[186:189], v[210:213], v[52:55]
	v_mfma_f32_16x16x32_bf16 v[44:47], v[162:165], v[220:223], v[44:47]
	v_mfma_f32_16x16x32_bf16 v[36:39], v[186:189], v[220:223], v[36:39]
	v_mfma_f32_16x16x32_bf16 v[28:31], v[162:165], v[228:231], v[28:31]
	v_mfma_f32_16x16x32_bf16 v[20:23], v[186:189], v[228:231], v[20:23]
	v_mfma_f32_16x16x32_bf16 v[12:15], v[162:165], v[236:239], v[12:15]
	v_mfma_f32_16x16x32_bf16 v[4:7], v[186:189], v[236:239], v[4:7]
	v_mfma_f32_16x16x32_bf16 v[60:63], v[182:185], v[216:219], v[60:63]
	v_mfma_f32_16x16x32_bf16 v[52:55], v[190:193], v[216:219], v[52:55]
	v_mfma_f32_16x16x32_bf16 v[44:47], v[182:185], v[224:227], v[44:47]
	v_mfma_f32_16x16x32_bf16 v[36:39], v[190:193], v[224:227], v[36:39]
	v_mfma_f32_16x16x32_bf16 v[28:31], v[182:185], v[232:235], v[28:31]
	v_mfma_f32_16x16x32_bf16 v[20:23], v[190:193], v[232:235], v[20:23]
	v_mfma_f32_16x16x32_bf16 v[12:15], v[182:185], v[240:243], v[12:15]
	v_mfma_f32_16x16x32_bf16 v[4:7], v[190:193], v[240:243], v[4:7]
	v_mfma_f32_16x16x32_bf16 v[56:59], v[194:197], v[210:213], v[56:59]
	v_mfma_f32_16x16x32_bf16 v[48:51], v[202:205], v[210:213], v[48:51]
	v_mfma_f32_16x16x32_bf16 v[40:43], v[194:197], v[220:223], v[40:43]
	v_mfma_f32_16x16x32_bf16 v[32:35], v[202:205], v[220:223], v[32:35]
	v_mfma_f32_16x16x32_bf16 v[24:27], v[194:197], v[228:231], v[24:27]
	v_mfma_f32_16x16x32_bf16 v[16:19], v[202:205], v[228:231], v[16:19]
	v_mfma_f32_16x16x32_bf16 v[8:11], v[194:197], v[236:239], v[8:11]
	v_mfma_f32_16x16x32_bf16 v[0:3], v[202:205], v[236:239], v[0:3]
	v_mfma_f32_16x16x32_bf16 v[56:59], v[198:201], v[216:219], v[56:59]
	v_mfma_f32_16x16x32_bf16 v[48:51], v[206:209], v[216:219], v[48:51]
	v_mfma_f32_16x16x32_bf16 v[40:43], v[198:201], v[224:227], v[40:43]
	v_mfma_f32_16x16x32_bf16 v[32:35], v[206:209], v[224:227], v[32:35]
	v_mfma_f32_16x16x32_bf16 v[24:27], v[198:201], v[232:235], v[24:27]
	v_mfma_f32_16x16x32_bf16 v[16:19], v[206:209], v[232:235], v[16:19]
	v_mfma_f32_16x16x32_bf16 v[8:11], v[198:201], v[240:243], v[8:11]
	v_mfma_f32_16x16x32_bf16 v[0:3], v[206:209], v[240:243], v[0:3]
	s_setprio 0
	s_barrier
	v_lshl_add_u64 v[158:159], v[158:159], 0, s[26:27]
	s_cmp_ge_i32 s10, s52
	v_lshl_add_u64 v[160:161], v[160:161], 0, s[26:27]
	s_cbranch_scc0 .LBB0_304

; #define PG8_STAGE(bufoff, gbase, voff) do { _Pragma("unroll") for (int _i = 0; _i < 2; ++_i) \
;         __builtin_amdgcn_global_load_lds((const unsigned*)((const char*)(gbase) + (voff)[_i]), (PG8_LAS unsigned*)(lds + (bufoff) + ldsw + _i * 8192), 16, 0, 0); } while (0)
; #define PG8_LDA(dst, b, h) do { _Pragma("unroll") for (int m = 0; m < 4; ++m) _Pragma("unroll") for (int k = 0; k < 2; ++k) dst[m][k] = *(const PG8_LAS bf16x8*)(lds + PG8_SA(b, h) + aoff + m * 2048 + k * 1024); } while (0)
; #define PG8_LDB(dst, b, h) do { _Pragma("unroll") for (int n = 0; n < 2; ++n) _Pragma("unroll") for (int k = 0; k < 2; ++k) dst[n][k] = *(const PG8_LAS bf16x8*)(lds + PG8_SB(b, h) + boff + n * 2048 + k * 1024); } while (0)
; #define PG8_MMA(ai, bj, At, Bt) do { __builtin_amdgcn_s_setprio(1); _Pragma("unroll") for (int m = 0; m < 4; ++m) _Pragma("unroll") for (int n = 0; n < 2; ++n) _Pragma("unroll") for (int k = 0; k < 2; ++k) \
;         acc[ai][bj][m][n] = __builtin_amdgcn_mfma_f32_16x16x32_bf16(Bt[n][k], At[m][k], acc[ai][bj][m][n], 0, 0, 0); __builtin_amdgcn_s_setprio(0); } while (0)
; #define PG8_WAIT_V(n) asm volatile("s_waitcnt vmcnt(" #n ")" ::: "memory")
; #define PG8_BAR __builtin_amdgcn_s_barrier()
; template <class Epi, class Sched, bool ALIGN_EPI = false, bool SP2 = false>
; __device__ __forceinline__ void gemm_phase(PG8_LAS unsigned char* lds, const Gemm g, const Sched& S, const Epi& E) {
;     ...
;         for (int t = 0; t < nt; t += 2) {
;             const bool last = (t == nt - 2);
;             const char* a1 = cA + (size_t)(t + 1) * kstep;
;             const char* a2 = last ? nA : cA + (size_t)(t + 2) * kstep; const char* b2 = last ? nB : cB + (size_t)(t + 2) * kstep;
;             const char* a3 = a2 + kstep; const char* b3 = b2 + kstep;
;             if (last && has_next) S.a_ready(nxt);
;             if constexpr (SP2) {
;             PG8_LDB(B0, 0, 0); PG8_LDB(B1, 0, 1); PG8_SCHED; PG8_LDA(At, 0, 0); PG8_STAGE(PG8_SA(1, 1), a1 + hstep, voffA);
;             PG8_WAIT_V(8); PG8_WAIT_L(0); PG8_BAR; PG8_MMA(0, 0, At, B0); PG8_MMA(0, 1, At, B1); PG8_BAR; PG8_SCHED;
;             PG8_LDA(At, 0, 1); PG8_STAGE(PG8_SB(0, 0), b2, voffB); PG8_STAGE(PG8_SB(0, 1), b2 + hstep, voffB); PG8_STAGE(PG8_SA(0, 0), a2, voffA);
;             PG8_WAIT_V(8); PG8_WAIT_L(0); PG8_BAR; PG8_MMA(1, 0, At, B0); PG8_MMA(1, 1, At, B1); PG8_BAR; PG8_SCHED;
.LBB0_371:
	v_add_u32_e32 v148, s54, v201
	v_add_u32_e32 v190, s55, v201
	ds_read_b128 v[136:139], v148
	ds_read_b128 v[140:143], v148 offset:1024
	ds_read_b128 v[144:147], v148 offset:2048
	ds_read_b128 v[148:151], v148 offset:3072
	ds_read_b128 v[152:155], v190
	ds_read_b128 v[182:185], v190 offset:1024
	ds_read_b128 v[186:189], v190 offset:2048
	ds_read_b128 v[190:193], v190 offset:3072
	s_cmp_eq_u32 s48, s12
	v_lshl_add_u64 v[194:195], v[134:135], 0, s[22:23]
	s_cselect_b64 vcc, -1, 0
	s_add_i32 s12, s12, 2
	v_cndmask_b32_e32 v199, v195, v179, vcc
	v_cndmask_b32_e32 v198, v194, v178, vcc
	v_cndmask_b32_e32 v215, v133, v181, vcc
	v_cndmask_b32_e32 v214, v132, v180, vcc
	s_mov_b32 m0, s56
	v_lshl_add_u64 v[236:237], v[134:135], 0, v[174:175]
	ds_read_b128 v[194:197], v203
	ds_read_b128 v[206:209], v203 offset:1024
	ds_read_b128 v[210:213], v203 offset:2048
	ds_read_b128 v[216:219], v203 offset:3072
	ds_read_b128 v[220:223], v203 offset:4096
	ds_read_b128 v[224:227], v203 offset:5120
	ds_read_b128 v[228:231], v203 offset:6144
	ds_read_b128 v[232:235], v203 offset:7168
	global_load_lds_dwordx4 v[236:237], off
	s_mov_b32 m0, s57
	v_lshl_add_u64 v[236:237], v[134:135], 0, v[172:173]
	global_load_lds_dwordx4 v[236:237], off
	s_waitcnt vmcnt(8) lgkmcnt(0)
	s_setprio 1
	s_barrier
	v_mfma_f32_16x16x32_bf16 v[124:127], v[136:139], v[194:197], v[124:127]
	v_mfma_f32_16x16x32_bf16 v[128:131], v[144:147], v[194:197], v[128:131]
	v_mfma_f32_16x16x32_bf16 v[112:115], v[136:139], v[210:213], v[112:115]
	v_mfma_f32_16x16x32_bf16 v[108:111], v[144:147], v[210:213], v[108:111]
	v_mfma_f32_16x16x32_bf16 v[96:99], v[136:139], v[220:223], v[96:99]
	v_mfma_f32_16x16x32_bf16 v[92:95], v[144:147], v[220:223], v[92:95]
	v_mfma_f32_16x16x32_bf16 v[80:83], v[136:139], v[228:231], v[80:83]
	v_mfma_f32_16x16x32_bf16 v[76:79], v[144:147], v[228:231], v[76:79]
	v_mfma_f32_16x16x32_bf16 v[124:127], v[140:143], v[206:209], v[124:127]
	v_mfma_f32_16x16x32_bf16 v[128:131], v[148:151], v[206:209], v[128:131]
	v_mfma_f32_16x16x32_bf16 v[112:115], v[140:143], v[216:219], v[112:115]
	v_mfma_f32_16x16x32_bf16 v[108:111], v[148:151], v[216:219], v[108:111]
	v_mfma_f32_16x16x32_bf16 v[96:99], v[140:143], v[224:227], v[96:99]
	v_mfma_f32_16x16x32_bf16 v[92:95], v[148:151], v[224:227], v[92:95]
	v_mfma_f32_16x16x32_bf16 v[80:83], v[140:143], v[232:235], v[80:83]
	v_mfma_f32_16x16x32_bf16 v[76:79], v[148:151], v[232:235], v[76:79]
	v_mfma_f32_16x16x32_bf16 v[120:123], v[152:155], v[194:197], v[120:123]
	v_mfma_f32_16x16x32_bf16 v[116:119], v[186:189], v[194:197], v[116:119]
	v_mfma_f32_16x16x32_bf16 v[104:107], v[152:155], v[210:213], v[104:107]
	v_mfma_f32_16x16x32_bf16 v[100:103], v[186:189], v[210:213], v[100:103]
	v_mfma_f32_16x16x32_bf16 v[88:91], v[152:155], v[220:223], v[88:91]
	v_mfma_f32_16x16x32_bf16 v[84:87], v[186:189], v[220:223], v[84:87]
	v_mfma_f32_16x16x32_bf16 v[72:75], v[152:155], v[228:231], v[72:75]
	v_mfma_f32_16x16x32_bf16 v[68:71], v[186:189], v[228:231], v[68:71]
	v_mfma_f32_16x16x32_bf16 v[120:123], v[182:185], v[206:209], v[120:123]
	v_mfma_f32_16x16x32_bf16 v[116:119], v[190:193], v[206:209], v[116:119]
	v_mfma_f32_16x16x32_bf16 v[104:107], v[182:185], v[216:219], v[104:107]
	v_mfma_f32_16x16x32_bf16 v[100:103], v[190:193], v[216:219], v[100:103]
	v_mfma_f32_16x16x32_bf16 v[88:91], v[182:185], v[224:227], v[88:91]
	v_mfma_f32_16x16x32_bf16 v[84:87], v[190:193], v[224:227], v[84:87]
	v_mfma_f32_16x16x32_bf16 v[72:75], v[182:185], v[232:235], v[72:75]
	v_mfma_f32_16x16x32_bf16 v[68:71], v[190:193], v[232:235], v[68:71]
	s_setprio 0
	s_barrier
	s_mov_b32 m0, s58
	v_lshl_add_u64 v[236:237], v[214:215], 0, v[166:167]
	ds_read_b128 v[194:197], v203 offset:16384
	ds_read_b128 v[206:209], v203 offset:17408
	ds_read_b128 v[210:213], v203 offset:18432
	ds_read_b128 v[216:219], v203 offset:19456
	ds_read_b128 v[220:223], v203 offset:20480
	ds_read_b128 v[224:227], v203 offset:21504
	ds_read_b128 v[228:231], v203 offset:22528
	ds_read_b128 v[232:235], v203 offset:23552
	global_load_lds_dwordx4 v[236:237], off
	v_lshl_add_u64 v[238:239], v[214:215], 0, v[170:171]
	s_mov_b32 m0, s59
	v_lshl_add_u64 v[214:215], v[214:215], 0, s[14:15]
	s_add_i32 s13, s55, s30
	global_load_lds_dwordx4 v[238:239], off
	v_lshl_add_u64 v[240:241], v[214:215], 0, v[166:167]
	s_mov_b32 m0, s13
	v_lshl_add_u64 v[214:215], v[214:215], 0, v[170:171]
	global_load_lds_dwordx4 v[240:241], off
	s_add_i32 m0, s13, 0x2000
	v_lshl_add_u64 v[242:243], v[198:199], 0, v[164:165]
	global_load_lds_dwordx4 v[214:215], off
	s_mov_b32 m0, s31
	v_lshl_add_u64 v[244:245], v[198:199], 0, v[168:169]
	global_load_lds_dwordx4 v[242:243], off
	s_mov_b32 m0, s34
	s_nop 0
	global_load_lds_dwordx4 v[244:245], off
	s_waitcnt vmcnt(8) lgkmcnt(0)
	s_setprio 1
	s_barrier
; #define PG8_STAGE(bufoff, gbase, voff) do { _Pragma("unroll") for (int _i = 0; _i < 2; ++_i) \
;         __builtin_amdgcn_global_load_lds((const unsigned*)((const char*)(gbase) + (voff)[_i]), (PG8_LAS unsigned*)(lds + (bufoff) + ldsw + _i * 8192), 16, 0, 0); } while (0)
; #define PG8_LDA(dst, b, h) do { _Pragma("unroll") for (int m = 0; m < 4; ++m) _Pragma("unroll") for (int k = 0; k < 2; ++k) dst[m][k] = *(const PG8_LAS bf16x8*)(lds + PG8_SA(b, h) + aoff + m * 2048 + k * 1024); } while (0)
; #define PG8_LDB(dst, b, h) do { _Pragma("unroll") for (int n = 0; n < 2; ++n) _Pragma("unroll") for (int k = 0; k < 2; ++k) dst[n][k] = *(const PG8_LAS bf16x8*)(lds + PG8_SB(b, h) + boff + n * 2048 + k * 1024); } while (0)
; #define PG8_MMA(ai, bj, At, Bt) do { __builtin_amdgcn_s_setprio(1); _Pragma("unroll") for (int m = 0; m < 4; ++m) _Pragma("unroll") for (int n = 0; n < 2; ++n) _Pragma("unroll") for (int k = 0; k < 2; ++k) \
;         acc[ai][bj][m][n] = __builtin_amdgcn_mfma_f32_16x16x32_bf16(Bt[n][k], At[m][k], acc[ai][bj][m][n], 0, 0, 0); __builtin_amdgcn_s_setprio(0); } while (0)
; #define PG8_WAIT_V(n) asm volatile("s_waitcnt vmcnt(" #n ")" ::: "memory")
; #define PG8_WAIT_L(n) asm volatile("s_waitcnt lgkmcnt(" #n ")" ::: "memory")
; #define PG8_BAR __builtin_amdgcn_s_barrier()
; #define PG8_SCHED __builtin_amdgcn_sched_barrier(0)
; template <class Epi, class Sched, bool ALIGN_EPI = false, bool SP2 = false>
; __device__ __forceinline__ void gemm_phase(PG8_LAS unsigned char* lds, const Gemm g, const Sched& S, const Epi& E) {
;     ...
;             PG8_WAIT_V(8); PG8_WAIT_L(0); PG8_BAR; PG8_MMA(1, 0, At, B0); PG8_MMA(1, 1, At, B1); PG8_BAR; PG8_SCHED;
;             PG8_LDB(B0, 1, 0); PG8_LDB(B1, 1, 1); PG8_SCHED; PG8_LDA(At, 1, 0); PG8_STAGE(PG8_SA(0, 1), a2 + hstep, voffA);
;             PG8_WAIT_V(8); PG8_WAIT_L(0); PG8_BAR; PG8_MMA(0, 0, At, B0); PG8_MMA(0, 1, At, B1); PG8_BAR; PG8_SCHED;
	v_mfma_f32_16x16x32_bf16 v[64:67], v[136:139], v[194:197], v[64:67]
	v_mfma_f32_16x16x32_bf16 v[60:63], v[144:147], v[194:197], v[60:63]
	v_mfma_f32_16x16x32_bf16 v[48:51], v[136:139], v[210:213], v[48:51]
	v_mfma_f32_16x16x32_bf16 v[44:47], v[144:147], v[210:213], v[44:47]
	v_mfma_f32_16x16x32_bf16 v[32:35], v[136:139], v[220:223], v[32:35]
	v_mfma_f32_16x16x32_bf16 v[28:31], v[144:147], v[220:223], v[28:31]
	v_mfma_f32_16x16x32_bf16 v[16:19], v[136:139], v[228:231], v[16:19]
	v_mfma_f32_16x16x32_bf16 v[12:15], v[144:147], v[228:231], v[12:15]
	v_mfma_f32_16x16x32_bf16 v[64:67], v[140:143], v[206:209], v[64:67]
	v_mfma_f32_16x16x32_bf16 v[60:63], v[148:151], v[206:209], v[60:63]
	v_mfma_f32_16x16x32_bf16 v[48:51], v[140:143], v[216:219], v[48:51]
	v_mfma_f32_16x16x32_bf16 v[44:47], v[148:151], v[216:219], v[44:47]
	v_mfma_f32_16x16x32_bf16 v[32:35], v[140:143], v[224:227], v[32:35]
	v_mfma_f32_16x16x32_bf16 v[28:31], v[148:151], v[224:227], v[28:31]
	v_mfma_f32_16x16x32_bf16 v[16:19], v[140:143], v[232:235], v[16:19]
	v_mfma_f32_16x16x32_bf16 v[12:15], v[148:151], v[232:235], v[12:15]
	v_mfma_f32_16x16x32_bf16 v[56:59], v[152:155], v[194:197], v[56:59]
	v_mfma_f32_16x16x32_bf16 v[52:55], v[186:189], v[194:197], v[52:55]
	v_mfma_f32_16x16x32_bf16 v[40:43], v[152:155], v[210:213], v[40:43]
	v_mfma_f32_16x16x32_bf16 v[36:39], v[186:189], v[210:213], v[36:39]
	v_mfma_f32_16x16x32_bf16 v[24:27], v[152:155], v[220:223], v[24:27]
	v_mfma_f32_16x16x32_bf16 v[20:23], v[186:189], v[220:223], v[20:23]
	v_mfma_f32_16x16x32_bf16 v[8:11], v[152:155], v[228:231], v[8:11]
	v_mfma_f32_16x16x32_bf16 v[4:7], v[186:189], v[228:231], v[4:7]
	v_mfma_f32_16x16x32_bf16 v[56:59], v[182:185], v[206:209], v[56:59]
	v_mfma_f32_16x16x32_bf16 v[52:55], v[190:193], v[206:209], v[52:55]
	v_mfma_f32_16x16x32_bf16 v[40:43], v[182:185], v[216:219], v[40:43]
	v_mfma_f32_16x16x32_bf16 v[36:39], v[190:193], v[216:219], v[36:39]
	v_mfma_f32_16x16x32_bf16 v[24:27], v[182:185], v[224:227], v[24:27]
	v_mfma_f32_16x16x32_bf16 v[20:23], v[190:193], v[224:227], v[20:23]
	v_mfma_f32_16x16x32_bf16 v[8:11], v[182:185], v[232:235], v[8:11]
	v_mfma_f32_16x16x32_bf16 v[4:7], v[190:193], v[232:235], v[4:7]
	s_setprio 0
	s_barrier
	s_add_i32 s13, 0, 0x18000
	s_add_i32 s29, 0, 0x1c000
	v_add_u32_e32 v148, s13, v201
	v_add_u32_e32 v190, s29, v201
	ds_read_b128 v[136:139], v148
	ds_read_b128 v[140:143], v148 offset:1024
	ds_read_b128 v[144:147], v148 offset:2048
	ds_read_b128 v[148:151], v148 offset:3072
	ds_read_b128 v[152:155], v190
	ds_read_b128 v[182:185], v190 offset:1024
	ds_read_b128 v[186:189], v190 offset:2048
	ds_read_b128 v[190:193], v190 offset:3072
	v_lshl_add_u64 v[198:199], v[198:199], 0, s[14:15]
	s_mov_b32 m0, s35
	v_lshl_add_u64 v[246:247], v[198:199], 0, v[164:165]
	ds_read_b128 v[194:197], v203 offset:32768
	ds_read_b128 v[206:209], v203 offset:33792
	ds_read_b128 v[210:213], v203 offset:34816
	ds_read_b128 v[216:219], v203 offset:35840
	ds_read_b128 v[220:223], v203 offset:36864
	ds_read_b128 v[224:227], v203 offset:37888
	ds_read_b128 v[228:231], v203 offset:38912
	ds_read_b128 v[232:235], v203 offset:39936
	global_load_lds_dwordx4 v[246:247], off
	s_mov_b32 m0, s36
	v_lshl_add_u64 v[198:199], v[198:199], 0, v[168:169]
	global_load_lds_dwordx4 v[198:199], off
	s_waitcnt vmcnt(8) lgkmcnt(0)
	s_setprio 1
	s_barrier
; #define PG8_STAGE(bufoff, gbase, voff) do { _Pragma("unroll") for (int _i = 0; _i < 2; ++_i) \
;         __builtin_amdgcn_global_load_lds((const unsigned*)((const char*)(gbase) + (voff)[_i]), (PG8_LAS unsigned*)(lds + (bufoff) + ldsw + _i * 8192), 16, 0, 0); } while (0)
; #define PG8_LDA(dst, b, h) do { _Pragma("unroll") for (int m = 0; m < 4; ++m) _Pragma("unroll") for (int k = 0; k < 2; ++k) dst[m][k] = *(const PG8_LAS bf16x8*)(lds + PG8_SA(b, h) + aoff + m * 2048 + k * 1024); } while (0)
; #define PG8_MMA(ai, bj, At, Bt) do { __builtin_amdgcn_s_setprio(1); _Pragma("unroll") for (int m = 0; m < 4; ++m) _Pragma("unroll") for (int n = 0; n < 2; ++n) _Pragma("unroll") for (int k = 0; k < 2; ++k) \
;         acc[ai][bj][m][n] = __builtin_amdgcn_mfma_f32_16x16x32_bf16(Bt[n][k], At[m][k], acc[ai][bj][m][n], 0, 0, 0); __builtin_amdgcn_s_setprio(0); } while (0)
; #define PG8_WAIT_V(n) asm volatile("s_waitcnt vmcnt(" #n ")" ::: "memory")
; #define PG8_WAIT_L(n) asm volatile("s_waitcnt lgkmcnt(" #n ")" ::: "memory")
; #define PG8_BAR __builtin_amdgcn_s_barrier()
; #define PG8_SCHED __builtin_amdgcn_sched_barrier(0)
; template <class Epi, class Sched, bool ALIGN_EPI = false, bool SP2 = false>
; __device__ __forceinline__ void gemm_phase(PG8_LAS unsigned char* lds, const Gemm g, const Sched& S, const Epi& E) {
;     ...
;             PG8_WAIT_V(8); PG8_WAIT_L(0); PG8_BAR; PG8_MMA(0, 0, At, B0); PG8_MMA(0, 1, At, B1); PG8_BAR; PG8_SCHED;
;             PG8_LDA(At, 1, 1); PG8_STAGE(PG8_SB(1, 0), b3, voffB); PG8_STAGE(PG8_SB(1, 1), b3 + hstep, voffB); PG8_STAGE(PG8_SA(1, 0), a3, voffA);
;             PG8_WAIT_V(8); PG8_WAIT_L(0); PG8_BAR; PG8_MMA(1, 0, At, B0); PG8_MMA(1, 1, At, B1); PG8_BAR; PG8_SCHED;
	v_mfma_f32_16x16x32_bf16 v[124:127], v[136:139], v[194:197], v[124:127]
	v_mfma_f32_16x16x32_bf16 v[128:131], v[144:147], v[194:197], v[128:131]
	v_mfma_f32_16x16x32_bf16 v[112:115], v[136:139], v[210:213], v[112:115]
	v_mfma_f32_16x16x32_bf16 v[108:111], v[144:147], v[210:213], v[108:111]
	v_mfma_f32_16x16x32_bf16 v[96:99], v[136:139], v[220:223], v[96:99]
	v_mfma_f32_16x16x32_bf16 v[92:95], v[144:147], v[220:223], v[92:95]
	v_mfma_f32_16x16x32_bf16 v[80:83], v[136:139], v[228:231], v[80:83]
	v_mfma_f32_16x16x32_bf16 v[76:79], v[144:147], v[228:231], v[76:79]
	v_mfma_f32_16x16x32_bf16 v[124:127], v[140:143], v[206:209], v[124:127]
	v_mfma_f32_16x16x32_bf16 v[128:131], v[148:151], v[206:209], v[128:131]
	v_mfma_f32_16x16x32_bf16 v[112:115], v[140:143], v[216:219], v[112:115]
	v_mfma_f32_16x16x32_bf16 v[108:111], v[148:151], v[216:219], v[108:111]
	v_mfma_f32_16x16x32_bf16 v[96:99], v[140:143], v[224:227], v[96:99]
	v_mfma_f32_16x16x32_bf16 v[92:95], v[148:151], v[224:227], v[92:95]
	v_mfma_f32_16x16x32_bf16 v[80:83], v[140:143], v[232:235], v[80:83]
	v_mfma_f32_16x16x32_bf16 v[76:79], v[148:151], v[232:235], v[76:79]
	v_mfma_f32_16x16x32_bf16 v[120:123], v[152:155], v[194:197], v[120:123]
	v_mfma_f32_16x16x32_bf16 v[116:119], v[186:189], v[194:197], v[116:119]
	v_mfma_f32_16x16x32_bf16 v[104:107], v[152:155], v[210:213], v[104:107]
	v_mfma_f32_16x16x32_bf16 v[100:103], v[186:189], v[210:213], v[100:103]
	v_mfma_f32_16x16x32_bf16 v[88:91], v[152:155], v[220:223], v[88:91]
	v_mfma_f32_16x16x32_bf16 v[84:87], v[186:189], v[220:223], v[84:87]
	v_mfma_f32_16x16x32_bf16 v[72:75], v[152:155], v[228:231], v[72:75]
	v_mfma_f32_16x16x32_bf16 v[68:71], v[186:189], v[228:231], v[68:71]
	v_mfma_f32_16x16x32_bf16 v[120:123], v[182:185], v[206:209], v[120:123]
	v_mfma_f32_16x16x32_bf16 v[116:119], v[190:193], v[206:209], v[116:119]
	v_mfma_f32_16x16x32_bf16 v[104:107], v[182:185], v[216:219], v[104:107]
	v_mfma_f32_16x16x32_bf16 v[100:103], v[190:193], v[216:219], v[100:103]
	v_mfma_f32_16x16x32_bf16 v[88:91], v[182:185], v[224:227], v[88:91]
	v_mfma_f32_16x16x32_bf16 v[84:87], v[190:193], v[224:227], v[84:87]
	v_mfma_f32_16x16x32_bf16 v[72:75], v[182:185], v[232:235], v[72:75]
	v_mfma_f32_16x16x32_bf16 v[68:71], v[190:193], v[232:235], v[68:71]
	s_setprio 0
	s_barrier
	s_add_i32 s13, s13, s30
	s_add_i32 m0, s13, 0xffffff80
	ds_read_b128 v[194:197], v203 offset:49152
	ds_read_b128 v[206:209], v203 offset:50176
	ds_read_b128 v[210:213], v203 offset:51200
	ds_read_b128 v[216:219], v203 offset:52224
	global_load_lds_dwordx4 v[236:237], off offset:128
	s_add_i32 m0, s13, 0x1f80
	s_add_i32 s13, s29, s30
	global_load_lds_dwordx4 v[238:239], off offset:128
	s_add_i32 m0, s13, 0xffffff80
	ds_read_b128 v[232:235], v203 offset:56320
	global_load_lds_dwordx4 v[240:241], off offset:128
	s_add_i32 m0, s13, 0x1f80
	ds_read_b128 v[228:231], v203 offset:55296
	global_load_lds_dwordx4 v[214:215], off offset:128
	s_add_i32 m0, s37, 0xffffff80
	ds_read_b128 v[224:227], v203 offset:54272
	global_load_lds_dwordx4 v[242:243], off offset:128
	s_add_i32 m0, s41, 0xffffff80
	ds_read_b128 v[220:223], v203 offset:53248
	global_load_lds_dwordx4 v[244:245], off offset:128
	s_waitcnt vmcnt(8) lgkmcnt(0)
	s_setprio 1
	s_barrier
	v_mfma_f32_16x16x32_bf16 v[64:67], v[136:139], v[194:197], v[64:67]
	v_mfma_f32_16x16x32_bf16 v[60:63], v[144:147], v[194:197], v[60:63]
	v_mfma_f32_16x16x32_bf16 v[48:51], v[136:139], v[210:213], v[48:51]
	v_mfma_f32_16x16x32_bf16 v[44:47], v[144:147], v[210:213], v[44:47]
	v_mfma_f32_16x16x32_bf16 v[32:35], v[136:139], v[220:223], v[32:35]
	v_mfma_f32_16x16x32_bf16 v[28:31], v[144:147], v[220:223], v[28:31]
	v_mfma_f32_16x16x32_bf16 v[16:19], v[136:139], v[228:231], v[16:19]
	v_mfma_f32_16x16x32_bf16 v[12:15], v[144:147], v[228:231], v[12:15]
	v_mfma_f32_16x16x32_bf16 v[64:67], v[140:143], v[206:209], v[64:67]
	v_mfma_f32_16x16x32_bf16 v[60:63], v[148:151], v[206:209], v[60:63]
	v_mfma_f32_16x16x32_bf16 v[48:51], v[140:143], v[216:219], v[48:51]
	v_mfma_f32_16x16x32_bf16 v[44:47], v[148:151], v[216:219], v[44:47]
	v_mfma_f32_16x16x32_bf16 v[32:35], v[140:143], v[224:227], v[32:35]
	v_mfma_f32_16x16x32_bf16 v[28:31], v[148:151], v[224:227], v[28:31]
	v_mfma_f32_16x16x32_bf16 v[16:19], v[140:143], v[232:235], v[16:19]
	v_mfma_f32_16x16x32_bf16 v[12:15], v[148:151], v[232:235], v[12:15]
	v_mfma_f32_16x16x32_bf16 v[56:59], v[152:155], v[194:197], v[56:59]
	v_mfma_f32_16x16x32_bf16 v[52:55], v[186:189], v[194:197], v[52:55]
	v_mfma_f32_16x16x32_bf16 v[40:43], v[152:155], v[210:213], v[40:43]
	v_mfma_f32_16x16x32_bf16 v[36:39], v[186:189], v[210:213], v[36:39]
	v_mfma_f32_16x16x32_bf16 v[24:27], v[152:155], v[220:223], v[24:27]
	v_mfma_f32_16x16x32_bf16 v[20:23], v[186:189], v[220:223], v[20:23]
	v_mfma_f32_16x16x32_bf16 v[8:11], v[152:155], v[228:231], v[8:11]
	v_mfma_f32_16x16x32_bf16 v[4:7], v[186:189], v[228:231], v[4:7]
	v_mfma_f32_16x16x32_bf16 v[56:59], v[182:185], v[206:209], v[56:59]
	v_mfma_f32_16x16x32_bf16 v[52:55], v[190:193], v[206:209], v[52:55]
	v_mfma_f32_16x16x32_bf16 v[40:43], v[182:185], v[216:219], v[40:43]
	v_mfma_f32_16x16x32_bf16 v[36:39], v[190:193], v[216:219], v[36:39]
	v_mfma_f32_16x16x32_bf16 v[24:27], v[182:185], v[224:227], v[24:27]
	v_mfma_f32_16x16x32_bf16 v[20:23], v[190:193], v[224:227], v[20:23]
	v_mfma_f32_16x16x32_bf16 v[8:11], v[182:185], v[232:235], v[8:11]
	v_mfma_f32_16x16x32_bf16 v[4:7], v[190:193], v[232:235], v[4:7]
	s_setprio 0
	s_barrier
	v_lshl_add_u64 v[132:133], v[132:133], 0, s[26:27]
	s_cmp_ge_i32 s12, s47
	v_lshl_add_u64 v[134:135], v[134:135], 0, s[26:27]
	s_cbranch_scc0 .LBB0_371

; #define PG8_STAGE(bufoff, gbase, voff) do { _Pragma("unroll") for (int _i = 0; _i < 2; ++_i) \
;         __builtin_amdgcn_global_load_lds((const unsigned*)((const char*)(gbase) + (voff)[_i]), (PG8_LAS unsigned*)(lds + (bufoff) + ldsw + _i * 8192), 16, 0, 0); } while (0)
; #define PG8_LDA(dst, b, h) do { _Pragma("unroll") for (int m = 0; m < 4; ++m) _Pragma("unroll") for (int k = 0; k < 2; ++k) dst[m][k] = *(const PG8_LAS bf16x8*)(lds + PG8_SA(b, h) + aoff + m * 2048 + k * 1024); } while (0)
; #define PG8_MMA(ai, bj, At, Bt) do { __builtin_amdgcn_s_setprio(1); _Pragma("unroll") for (int m = 0; m < 4; ++m) _Pragma("unroll") for (int n = 0; n < 2; ++n) _Pragma("unroll") for (int k = 0; k < 2; ++k) \
;         acc[ai][bj][m][n] = __builtin_amdgcn_mfma_f32_16x16x32_bf16(Bt[n][k], At[m][k], acc[ai][bj][m][n], 0, 0, 0); __builtin_amdgcn_s_setprio(0); } while (0)
; #define PG8_WAIT_V(n) asm volatile("s_waitcnt vmcnt(" #n ")" ::: "memory")
; #define PG8_WAIT_L(n) asm volatile("s_waitcnt lgkmcnt(" #n ")" ::: "memory")
; #define PG8_BAR __builtin_amdgcn_s_barrier()
; #define PG8_SCHED __builtin_amdgcn_sched_barrier(0)
; template <class Epi, class Sched, bool ALIGN_EPI = false, bool SP2 = false>
; __device__ __forceinline__ void gemm_phase(PG8_LAS unsigned char* lds, const Gemm g, const Sched& S, const Epi& E) {
;     ...
;             PG8_LDA(At, 1, 1); PG8_STAGE(PG8_SB(1, 0), b3, voffB); PG8_STAGE(PG8_SB(1, 1), b3 + hstep, voffB); PG8_STAGE(PG8_SA(1, 0), a3, voffA);
;             PG8_WAIT_V(8); PG8_WAIT_L(0); PG8_BAR; PG8_MMA(1, 0, At, B0); PG8_MMA(1, 1, At, B1); PG8_BAR; PG8_SCHED;
.Lie_skipk2:
	s_setprio 0
	s_barrier
	s_add_i32 s13, s13, s37
	s_add_i32 m0, s13, 0xffffff80
	ds_read_b128 v[200:203], v216 offset:49152
	ds_read_b128 v[204:207], v216 offset:50176
	ds_read_b128 v[218:221], v216 offset:51200
	ds_read_b128 v[222:225], v216 offset:52224
	global_load_lds_dwordx4 v[214:215], off offset:128
	s_add_i32 m0, s13, 0x1f80
	s_add_i32 s13, s15, s37
	global_load_lds_dwordx4 v[242:243], off offset:128
	s_add_i32 m0, s13, 0xffffff80
	ds_read_b128 v[238:241], v216 offset:56320
	global_load_lds_dwordx4 v[244:245], off offset:128
	s_add_i32 m0, s13, 0x1f80
	ds_read_b128 v[234:237], v216 offset:55296
	global_load_lds_dwordx4 v[212:213], off offset:128
	s_add_i32 m0, s56, 0xffffff80
	ds_read_b128 v[230:233], v216 offset:54272
	global_load_lds_dwordx4 v[246:247], off offset:128
	s_add_i32 m0, s57, 0xffffff80
	ds_read_b128 v[226:229], v216 offset:53248
	global_load_lds_dwordx4 v[248:249], off offset:128
	s_waitcnt vmcnt(8) lgkmcnt(0)
	s_setprio 1
	s_barrier
	v_mfma_f32_16x16x32_bf16 v[60:63], v[132:135], v[200:203], v[60:63]
	v_mfma_f32_16x16x32_bf16 v[56:59], v[176:179], v[200:203], v[56:59]
	v_mfma_f32_16x16x32_bf16 v[44:47], v[132:135], v[218:221], v[44:47]
	v_mfma_f32_16x16x32_bf16 v[40:43], v[176:179], v[218:221], v[40:43]
	v_mfma_f32_16x16x32_bf16 v[28:31], v[132:135], v[226:229], v[28:31]
	v_mfma_f32_16x16x32_bf16 v[24:27], v[176:179], v[226:229], v[24:27]
	v_mfma_f32_16x16x32_bf16 v[12:15], v[132:135], v[234:237], v[12:15]
	v_mfma_f32_16x16x32_bf16 v[8:11], v[176:179], v[234:237], v[8:11]
	v_mfma_f32_16x16x32_bf16 v[60:63], v[136:139], v[204:207], v[60:63]
	v_mfma_f32_16x16x32_bf16 v[56:59], v[180:183], v[204:207], v[56:59]
	v_mfma_f32_16x16x32_bf16 v[44:47], v[136:139], v[222:225], v[44:47]
	v_mfma_f32_16x16x32_bf16 v[40:43], v[180:183], v[222:225], v[40:43]
	v_mfma_f32_16x16x32_bf16 v[28:31], v[136:139], v[230:233], v[28:31]
	v_mfma_f32_16x16x32_bf16 v[24:27], v[180:183], v[230:233], v[24:27]
	v_mfma_f32_16x16x32_bf16 v[12:15], v[136:139], v[238:241], v[12:15]
	v_mfma_f32_16x16x32_bf16 v[8:11], v[180:183], v[238:241], v[8:11]
	s_cmp_gt_u32 s75, 3
	s_cbranch_scc1 .Lie_skipk3
	v_mfma_f32_16x16x32_bf16 v[52:55], v[184:187], v[200:203], v[52:55]
	v_mfma_f32_16x16x32_bf16 v[48:51], v[192:195], v[200:203], v[48:51]
	v_mfma_f32_16x16x32_bf16 v[36:39], v[184:187], v[218:221], v[36:39]
	v_mfma_f32_16x16x32_bf16 v[32:35], v[192:195], v[218:221], v[32:35]
	v_mfma_f32_16x16x32_bf16 v[20:23], v[184:187], v[226:229], v[20:23]
	v_mfma_f32_16x16x32_bf16 v[16:19], v[192:195], v[226:229], v[16:19]
	v_mfma_f32_16x16x32_bf16 v[4:7], v[184:187], v[234:237], v[4:7]
	v_mfma_f32_16x16x32_bf16 v[0:3], v[192:195], v[234:237], v[0:3]
	v_mfma_f32_16x16x32_bf16 v[52:55], v[188:191], v[204:207], v[52:55]
	v_mfma_f32_16x16x32_bf16 v[48:51], v[196:199], v[204:207], v[48:51]
	v_mfma_f32_16x16x32_bf16 v[36:39], v[188:191], v[222:225], v[36:39]
	v_mfma_f32_16x16x32_bf16 v[32:35], v[196:199], v[222:225], v[32:35]
	v_mfma_f32_16x16x32_bf16 v[20:23], v[188:191], v[230:233], v[20:23]
	v_mfma_f32_16x16x32_bf16 v[16:19], v[196:199], v[230:233], v[16:19]
	v_mfma_f32_16x16x32_bf16 v[4:7], v[188:191], v[238:241], v[4:7]
	v_mfma_f32_16x16x32_bf16 v[0:3], v[196:199], v[238:241], v[0:3]

; #define PG8_STAGE(bufoff, gbase, voff) do { _Pragma("unroll") for (int _i = 0; _i < 2; ++_i) \
;         __builtin_amdgcn_global_load_lds((const unsigned*)((const char*)(gbase) + (voff)[_i]), (PG8_LAS unsigned*)(lds + (bufoff) + ldsw + _i * 8192), 16, 0, 0); } while (0)
; #define PG8_LDA(dst, b, h) do { _Pragma("unroll") for (int m = 0; m < 4; ++m) _Pragma("unroll") for (int k = 0; k < 2; ++k) dst[m][k] = *(const PG8_LAS bf16x8*)(lds + PG8_SA(b, h) + aoff + m * 2048 + k * 1024); } while (0)
; #define PG8_LDB(dst, b, h) do { _Pragma("unroll") for (int n = 0; n < 2; ++n) _Pragma("unroll") for (int k = 0; k < 2; ++k) dst[n][k] = *(const PG8_LAS bf16x8*)(lds + PG8_SB(b, h) + boff + n * 2048 + k * 1024); } while (0)
; #define PG8_MMA(ai, bj, At, Bt) do { __builtin_amdgcn_s_setprio(1); _Pragma("unroll") for (int m = 0; m < 4; ++m) _Pragma("unroll") for (int n = 0; n < 2; ++n) _Pragma("unroll") for (int k = 0; k < 2; ++k) \
;         acc[ai][bj][m][n] = __builtin_amdgcn_mfma_f32_16x16x32_bf16(Bt[n][k], At[m][k], acc[ai][bj][m][n], 0, 0, 0); __builtin_amdgcn_s_setprio(0); } while (0)
; #define PG8_WAIT_V(n) asm volatile("s_waitcnt vmcnt(" #n ")" ::: "memory")
; #define PG8_BAR __builtin_amdgcn_s_barrier()
; template <class Epi, class Sched, bool ALIGN_EPI = false, bool SP2 = false>
; __device__ __forceinline__ void gemm_phase(PG8_LAS unsigned char* lds, const Gemm g, const Sched& S, const Epi& E) {
;     ...
;         for (int t = 0; t < nt; t += 2) {
;             const bool last = (t == nt - 2);
;             const char* a1 = cA + (size_t)(t + 1) * kstep;
;             const char* a2 = last ? nA : cA + (size_t)(t + 2) * kstep; const char* b2 = last ? nB : cB + (size_t)(t + 2) * kstep;
;             const char* a3 = a2 + kstep; const char* b3 = b2 + kstep;
;             if (last && has_next) S.a_ready(nxt);
;             if constexpr (SP2) {
;             PG8_LDB(B0, 0, 0); PG8_LDB(B1, 0, 1); PG8_SCHED; PG8_LDA(At, 0, 0); PG8_STAGE(PG8_SA(1, 1), a1 + hstep, voffA);
;             PG8_WAIT_V(8); PG8_WAIT_L(0); PG8_BAR; PG8_MMA(0, 0, At, B0); PG8_MMA(0, 1, At, B1); PG8_BAR; PG8_SCHED;
;             PG8_LDA(At, 0, 1); PG8_STAGE(PG8_SB(0, 0), b2, voffB); PG8_STAGE(PG8_SB(0, 1), b2 + hstep, voffB); PG8_STAGE(PG8_SA(0, 0), a2, voffA);
;             PG8_WAIT_V(8); PG8_WAIT_L(0); PG8_BAR; PG8_MMA(1, 0, At, B0); PG8_MMA(1, 1, At, B1); PG8_BAR; PG8_SCHED;
.LBB0_635:
	v_add_u32_e32 v144, s64, v209
	v_add_u32_e32 v194, s65, v209
	ds_read_b128 v[92:95], v144
	ds_read_b128 v[128:131], v144 offset:1024
	ds_read_b128 v[132:135], v144 offset:2048
	ds_read_b128 v[144:147], v144 offset:3072
	ds_read_b128 v[148:151], v194
	ds_read_b128 v[152:155], v194 offset:1024
	ds_read_b128 v[190:193], v194 offset:2048
	ds_read_b128 v[194:197], v194 offset:3072
	s_cmp_eq_u32 s58, s10
	v_lshl_add_u64 v[198:199], v[90:91], 0, s[24:25]
	s_cselect_b64 vcc, -1, 0
	s_add_i32 s10, s10, 2
	v_cndmask_b32_e32 v207, v199, v187, vcc
	v_cndmask_b32_e32 v206, v198, v186, vcc
	v_cndmask_b32_e32 v215, v89, v189, vcc
	v_cndmask_b32_e32 v214, v88, v188, vcc
	v_lshl_add_u64 v[238:239], v[90:91], 0, v[180:181]
	s_add_i32 m0, s41, 0xc000
	ds_read_b128 v[198:201], v216
	ds_read_b128 v[202:205], v216 offset:1024
	ds_read_b128 v[210:213], v216 offset:2048
	ds_read_b128 v[218:221], v216 offset:3072
	ds_read_b128 v[222:225], v216 offset:4096
	ds_read_b128 v[226:229], v216 offset:5120
	ds_read_b128 v[230:233], v216 offset:6144
	ds_read_b128 v[234:237], v216 offset:7168
	global_load_lds_dwordx4 v[238:239], off
	s_add_i32 m0, s41, 0xe000
	v_lshl_add_u64 v[238:239], v[90:91], 0, v[178:179]
	global_load_lds_dwordx4 v[238:239], off
	s_waitcnt vmcnt(8) lgkmcnt(0)
	s_setprio 1
	s_barrier
	v_mfma_f32_16x16x32_bf16 v[140:143], v[92:95], v[198:201], v[140:143]
	v_mfma_f32_16x16x32_bf16 v[136:139], v[132:135], v[198:201], v[136:139]
	v_mfma_f32_16x16x32_bf16 v[116:119], v[92:95], v[210:213], v[116:119]
	v_mfma_f32_16x16x32_bf16 v[112:115], v[132:135], v[210:213], v[112:115]
	v_mfma_f32_16x16x32_bf16 v[100:103], v[92:95], v[222:225], v[100:103]
	v_mfma_f32_16x16x32_bf16 v[96:99], v[132:135], v[222:225], v[96:99]
	v_mfma_f32_16x16x32_bf16 v[76:79], v[92:95], v[230:233], v[76:79]
	v_mfma_f32_16x16x32_bf16 v[72:75], v[132:135], v[230:233], v[72:75]
	v_mfma_f32_16x16x32_bf16 v[140:143], v[128:131], v[202:205], v[140:143]
	v_mfma_f32_16x16x32_bf16 v[136:139], v[144:147], v[202:205], v[136:139]
	v_mfma_f32_16x16x32_bf16 v[116:119], v[128:131], v[218:221], v[116:119]
	v_mfma_f32_16x16x32_bf16 v[112:115], v[144:147], v[218:221], v[112:115]
	v_mfma_f32_16x16x32_bf16 v[100:103], v[128:131], v[226:229], v[100:103]
	v_mfma_f32_16x16x32_bf16 v[96:99], v[144:147], v[226:229], v[96:99]
	v_mfma_f32_16x16x32_bf16 v[76:79], v[128:131], v[234:237], v[76:79]
	v_mfma_f32_16x16x32_bf16 v[72:75], v[144:147], v[234:237], v[72:75]
	v_mfma_f32_16x16x32_bf16 v[124:127], v[148:151], v[198:201], v[124:127]
	v_mfma_f32_16x16x32_bf16 v[120:123], v[190:193], v[198:201], v[120:123]
	v_mfma_f32_16x16x32_bf16 v[108:111], v[148:151], v[210:213], v[108:111]
	v_mfma_f32_16x16x32_bf16 v[104:107], v[190:193], v[210:213], v[104:107]
	v_mfma_f32_16x16x32_bf16 v[84:87], v[148:151], v[222:225], v[84:87]
	v_mfma_f32_16x16x32_bf16 v[80:83], v[190:193], v[222:225], v[80:83]
	v_mfma_f32_16x16x32_bf16 v[68:71], v[148:151], v[230:233], v[68:71]
	v_mfma_f32_16x16x32_bf16 v[64:67], v[190:193], v[230:233], v[64:67]
	v_mfma_f32_16x16x32_bf16 v[124:127], v[152:155], v[202:205], v[124:127]
	v_mfma_f32_16x16x32_bf16 v[120:123], v[194:197], v[202:205], v[120:123]
	v_mfma_f32_16x16x32_bf16 v[108:111], v[152:155], v[218:221], v[108:111]
	v_mfma_f32_16x16x32_bf16 v[104:107], v[194:197], v[218:221], v[104:107]
	v_mfma_f32_16x16x32_bf16 v[84:87], v[152:155], v[226:229], v[84:87]
	v_mfma_f32_16x16x32_bf16 v[80:83], v[194:197], v[226:229], v[80:83]
	v_mfma_f32_16x16x32_bf16 v[68:71], v[152:155], v[234:237], v[68:71]
	v_mfma_f32_16x16x32_bf16 v[64:67], v[194:197], v[234:237], v[64:67]
	s_setprio 0
	s_barrier
	s_add_i32 s11, s64, s35
	v_lshl_add_u64 v[238:239], v[214:215], 0, v[168:169]
	s_mov_b32 m0, s11
	ds_read_b128 v[198:201], v216 offset:16384
	ds_read_b128 v[202:205], v216 offset:17408
	ds_read_b128 v[210:213], v216 offset:18432
	ds_read_b128 v[218:221], v216 offset:19456
	ds_read_b128 v[222:225], v216 offset:20480
	ds_read_b128 v[226:229], v216 offset:21504
	ds_read_b128 v[230:233], v216 offset:22528
	ds_read_b128 v[234:237], v216 offset:23552
	global_load_lds_dwordx4 v[238:239], off
	v_lshl_add_u64 v[240:241], v[214:215], 0, v[172:173]
	s_add_i32 m0, s11, 0x2000
	v_lshl_add_u64 v[214:215], v[214:215], 0, s[18:19]
	s_add_i32 s11, s65, s35
	global_load_lds_dwordx4 v[240:241], off
	v_lshl_add_u64 v[242:243], v[214:215], 0, v[168:169]
	s_mov_b32 m0, s11
	v_lshl_add_u64 v[214:215], v[214:215], 0, v[172:173]
	global_load_lds_dwordx4 v[242:243], off
	s_add_i32 m0, s11, 0x2000
	v_lshl_add_u64 v[244:245], v[206:207], 0, v[166:167]
	global_load_lds_dwordx4 v[214:215], off
	s_mov_b32 m0, s41
	v_lshl_add_u64 v[246:247], v[206:207], 0, v[170:171]
	global_load_lds_dwordx4 v[244:245], off
	s_mov_b32 m0, s50
	s_nop 0
	global_load_lds_dwordx4 v[246:247], off
	s_waitcnt vmcnt(8) lgkmcnt(0)
	s_setprio 1
	s_barrier
; #define PG8_STAGE(bufoff, gbase, voff) do { _Pragma("unroll") for (int _i = 0; _i < 2; ++_i) \
;         __builtin_amdgcn_global_load_lds((const unsigned*)((const char*)(gbase) + (voff)[_i]), (PG8_LAS unsigned*)(lds + (bufoff) + ldsw + _i * 8192), 16, 0, 0); } while (0)
; #define PG8_LDA(dst, b, h) do { _Pragma("unroll") for (int m = 0; m < 4; ++m) _Pragma("unroll") for (int k = 0; k < 2; ++k) dst[m][k] = *(const PG8_LAS bf16x8*)(lds + PG8_SA(b, h) + aoff + m * 2048 + k * 1024); } while (0)
; #define PG8_LDB(dst, b, h) do { _Pragma("unroll") for (int n = 0; n < 2; ++n) _Pragma("unroll") for (int k = 0; k < 2; ++k) dst[n][k] = *(const PG8_LAS bf16x8*)(lds + PG8_SB(b, h) + boff + n * 2048 + k * 1024); } while (0)
; #define PG8_MMA(ai, bj, At, Bt) do { __builtin_amdgcn_s_setprio(1); _Pragma("unroll") for (int m = 0; m < 4; ++m) _Pragma("unroll") for (int n = 0; n < 2; ++n) _Pragma("unroll") for (int k = 0; k < 2; ++k) \
;         acc[ai][bj][m][n] = __builtin_amdgcn_mfma_f32_16x16x32_bf16(Bt[n][k], At[m][k], acc[ai][bj][m][n], 0, 0, 0); __builtin_amdgcn_s_setprio(0); } while (0)
; #define PG8_WAIT_V(n) asm volatile("s_waitcnt vmcnt(" #n ")" ::: "memory")
; #define PG8_WAIT_L(n) asm volatile("s_waitcnt lgkmcnt(" #n ")" ::: "memory")
; #define PG8_BAR __builtin_amdgcn_s_barrier()
; #define PG8_SCHED __builtin_amdgcn_sched_barrier(0)
; template <class Epi, class Sched, bool ALIGN_EPI = false, bool SP2 = false>
; __device__ __forceinline__ void gemm_phase(PG8_LAS unsigned char* lds, const Gemm g, const Sched& S, const Epi& E) {
;     ...
;             PG8_WAIT_V(8); PG8_WAIT_L(0); PG8_BAR; PG8_MMA(1, 0, At, B0); PG8_MMA(1, 1, At, B1); PG8_BAR; PG8_SCHED;
;             PG8_LDB(B0, 1, 0); PG8_LDB(B1, 1, 1); PG8_SCHED; PG8_LDA(At, 1, 0); PG8_STAGE(PG8_SA(0, 1), a2 + hstep, voffA);
;             PG8_WAIT_V(8); PG8_WAIT_L(0); PG8_BAR; PG8_MMA(0, 0, At, B0); PG8_MMA(0, 1, At, B1); PG8_BAR; PG8_SCHED;
	v_mfma_f32_16x16x32_bf16 v[60:63], v[92:95], v[198:201], v[60:63]
	v_mfma_f32_16x16x32_bf16 v[56:59], v[132:135], v[198:201], v[56:59]
	v_mfma_f32_16x16x32_bf16 v[44:47], v[92:95], v[210:213], v[44:47]
	v_mfma_f32_16x16x32_bf16 v[40:43], v[132:135], v[210:213], v[40:43]
	v_mfma_f32_16x16x32_bf16 v[28:31], v[92:95], v[222:225], v[28:31]
	v_mfma_f32_16x16x32_bf16 v[24:27], v[132:135], v[222:225], v[24:27]
	v_mfma_f32_16x16x32_bf16 v[12:15], v[92:95], v[230:233], v[12:15]
	v_mfma_f32_16x16x32_bf16 v[8:11], v[132:135], v[230:233], v[8:11]
	v_mfma_f32_16x16x32_bf16 v[60:63], v[128:131], v[202:205], v[60:63]
	v_mfma_f32_16x16x32_bf16 v[56:59], v[144:147], v[202:205], v[56:59]
	v_mfma_f32_16x16x32_bf16 v[44:47], v[128:131], v[218:221], v[44:47]
	v_mfma_f32_16x16x32_bf16 v[40:43], v[144:147], v[218:221], v[40:43]
	v_mfma_f32_16x16x32_bf16 v[28:31], v[128:131], v[226:229], v[28:31]
	v_mfma_f32_16x16x32_bf16 v[24:27], v[144:147], v[226:229], v[24:27]
	v_mfma_f32_16x16x32_bf16 v[12:15], v[128:131], v[234:237], v[12:15]
	v_mfma_f32_16x16x32_bf16 v[8:11], v[144:147], v[234:237], v[8:11]
	v_mfma_f32_16x16x32_bf16 v[52:55], v[148:151], v[198:201], v[52:55]
	v_mfma_f32_16x16x32_bf16 v[48:51], v[190:193], v[198:201], v[48:51]
	v_mfma_f32_16x16x32_bf16 v[36:39], v[148:151], v[210:213], v[36:39]
	v_mfma_f32_16x16x32_bf16 v[32:35], v[190:193], v[210:213], v[32:35]
	v_mfma_f32_16x16x32_bf16 v[20:23], v[148:151], v[222:225], v[20:23]
	v_mfma_f32_16x16x32_bf16 v[16:19], v[190:193], v[222:225], v[16:19]
	v_mfma_f32_16x16x32_bf16 v[4:7], v[148:151], v[230:233], v[4:7]
	v_mfma_f32_16x16x32_bf16 v[0:3], v[190:193], v[230:233], v[0:3]
	v_mfma_f32_16x16x32_bf16 v[52:55], v[152:155], v[202:205], v[52:55]
	v_mfma_f32_16x16x32_bf16 v[48:51], v[194:197], v[202:205], v[48:51]
	v_mfma_f32_16x16x32_bf16 v[36:39], v[152:155], v[218:221], v[36:39]
	v_mfma_f32_16x16x32_bf16 v[32:35], v[194:197], v[218:221], v[32:35]
	v_mfma_f32_16x16x32_bf16 v[20:23], v[152:155], v[226:229], v[20:23]
	v_mfma_f32_16x16x32_bf16 v[16:19], v[194:197], v[226:229], v[16:19]
	v_mfma_f32_16x16x32_bf16 v[4:7], v[152:155], v[234:237], v[4:7]
	v_mfma_f32_16x16x32_bf16 v[0:3], v[194:197], v[234:237], v[0:3]
	s_setprio 0
	s_barrier
	s_add_i32 s11, 0, 0x18000
	s_add_i32 s14, 0, 0x1c000
	v_add_u32_e32 v144, s11, v209
	v_add_u32_e32 v194, s14, v209
	ds_read_b128 v[92:95], v144
	ds_read_b128 v[128:131], v144 offset:1024
	ds_read_b128 v[132:135], v144 offset:2048
	ds_read_b128 v[144:147], v144 offset:3072
	ds_read_b128 v[148:151], v194
	ds_read_b128 v[152:155], v194 offset:1024
	ds_read_b128 v[190:193], v194 offset:2048
	ds_read_b128 v[194:197], v194 offset:3072
	v_lshl_add_u64 v[206:207], v[206:207], 0, s[18:19]
	s_mov_b32 m0, s51
	v_lshl_add_u64 v[248:249], v[206:207], 0, v[166:167]
	ds_read_b128 v[198:201], v216 offset:32768
	ds_read_b128 v[202:205], v216 offset:33792
	ds_read_b128 v[210:213], v216 offset:34816
	ds_read_b128 v[218:221], v216 offset:35840
	ds_read_b128 v[222:225], v216 offset:36864
	ds_read_b128 v[226:229], v216 offset:37888
	ds_read_b128 v[230:233], v216 offset:38912
	ds_read_b128 v[234:237], v216 offset:39936
	global_load_lds_dwordx4 v[248:249], off
	s_mov_b32 m0, s52
	v_lshl_add_u64 v[206:207], v[206:207], 0, v[170:171]
	global_load_lds_dwordx4 v[206:207], off
	s_waitcnt vmcnt(8) lgkmcnt(0)
	s_setprio 1
	s_barrier
; #define PG8_STAGE(bufoff, gbase, voff) do { _Pragma("unroll") for (int _i = 0; _i < 2; ++_i) \
;         __builtin_amdgcn_global_load_lds((const unsigned*)((const char*)(gbase) + (voff)[_i]), (PG8_LAS unsigned*)(lds + (bufoff) + ldsw + _i * 8192), 16, 0, 0); } while (0)
; #define PG8_LDA(dst, b, h) do { _Pragma("unroll") for (int m = 0; m < 4; ++m) _Pragma("unroll") for (int k = 0; k < 2; ++k) dst[m][k] = *(const PG8_LAS bf16x8*)(lds + PG8_SA(b, h) + aoff + m * 2048 + k * 1024); } while (0)
; #define PG8_MMA(ai, bj, At, Bt) do { __builtin_amdgcn_s_setprio(1); _Pragma("unroll") for (int m = 0; m < 4; ++m) _Pragma("unroll") for (int n = 0; n < 2; ++n) _Pragma("unroll") for (int k = 0; k < 2; ++k) \
;         acc[ai][bj][m][n] = __builtin_amdgcn_mfma_f32_16x16x32_bf16(Bt[n][k], At[m][k], acc[ai][bj][m][n], 0, 0, 0); __builtin_amdgcn_s_setprio(0); } while (0)
; #define PG8_WAIT_V(n) asm volatile("s_waitcnt vmcnt(" #n ")" ::: "memory")
; #define PG8_WAIT_L(n) asm volatile("s_waitcnt lgkmcnt(" #n ")" ::: "memory")
; #define PG8_BAR __builtin_amdgcn_s_barrier()
; #define PG8_SCHED __builtin_amdgcn_sched_barrier(0)
; template <class Epi, class Sched, bool ALIGN_EPI = false, bool SP2 = false>
; __device__ __forceinline__ void gemm_phase(PG8_LAS unsigned char* lds, const Gemm g, const Sched& S, const Epi& E) {
;     ...
;         for (int t = 0; t < nt; t += 2) {
;     ...
;             PG8_WAIT_V(8); PG8_WAIT_L(0); PG8_BAR; PG8_MMA(0, 0, At, B0); PG8_MMA(0, 1, At, B1); PG8_BAR; PG8_SCHED;
;             PG8_LDA(At, 1, 1); PG8_STAGE(PG8_SB(1, 0), b3, voffB); PG8_STAGE(PG8_SB(1, 1), b3 + hstep, voffB); PG8_STAGE(PG8_SA(1, 0), a3, voffA);
;             PG8_WAIT_V(8); PG8_WAIT_L(0); PG8_BAR; PG8_MMA(1, 0, At, B0); PG8_MMA(1, 1, At, B1); PG8_BAR; PG8_SCHED;
	v_mfma_f32_16x16x32_bf16 v[140:143], v[92:95], v[198:201], v[140:143]
	v_mfma_f32_16x16x32_bf16 v[136:139], v[132:135], v[198:201], v[136:139]
	v_mfma_f32_16x16x32_bf16 v[116:119], v[92:95], v[210:213], v[116:119]
	v_mfma_f32_16x16x32_bf16 v[112:115], v[132:135], v[210:213], v[112:115]
	v_mfma_f32_16x16x32_bf16 v[100:103], v[92:95], v[222:225], v[100:103]
	v_mfma_f32_16x16x32_bf16 v[96:99], v[132:135], v[222:225], v[96:99]
	v_mfma_f32_16x16x32_bf16 v[76:79], v[92:95], v[230:233], v[76:79]
	v_mfma_f32_16x16x32_bf16 v[72:75], v[132:135], v[230:233], v[72:75]
	v_mfma_f32_16x16x32_bf16 v[140:143], v[128:131], v[202:205], v[140:143]
	v_mfma_f32_16x16x32_bf16 v[136:139], v[144:147], v[202:205], v[136:139]
	v_mfma_f32_16x16x32_bf16 v[116:119], v[128:131], v[218:221], v[116:119]
	v_mfma_f32_16x16x32_bf16 v[112:115], v[144:147], v[218:221], v[112:115]
	v_mfma_f32_16x16x32_bf16 v[100:103], v[128:131], v[226:229], v[100:103]
	v_mfma_f32_16x16x32_bf16 v[96:99], v[144:147], v[226:229], v[96:99]
	v_mfma_f32_16x16x32_bf16 v[76:79], v[128:131], v[234:237], v[76:79]
	v_mfma_f32_16x16x32_bf16 v[72:75], v[144:147], v[234:237], v[72:75]
	v_mfma_f32_16x16x32_bf16 v[124:127], v[148:151], v[198:201], v[124:127]
	v_mfma_f32_16x16x32_bf16 v[120:123], v[190:193], v[198:201], v[120:123]
	v_mfma_f32_16x16x32_bf16 v[108:111], v[148:151], v[210:213], v[108:111]
	v_mfma_f32_16x16x32_bf16 v[104:107], v[190:193], v[210:213], v[104:107]
	v_mfma_f32_16x16x32_bf16 v[84:87], v[148:151], v[222:225], v[84:87]
	v_mfma_f32_16x16x32_bf16 v[80:83], v[190:193], v[222:225], v[80:83]
	v_mfma_f32_16x16x32_bf16 v[68:71], v[148:151], v[230:233], v[68:71]
	v_mfma_f32_16x16x32_bf16 v[64:67], v[190:193], v[230:233], v[64:67]
	v_mfma_f32_16x16x32_bf16 v[124:127], v[152:155], v[202:205], v[124:127]
	v_mfma_f32_16x16x32_bf16 v[120:123], v[194:197], v[202:205], v[120:123]
	v_mfma_f32_16x16x32_bf16 v[108:111], v[152:155], v[218:221], v[108:111]
	v_mfma_f32_16x16x32_bf16 v[104:107], v[194:197], v[218:221], v[104:107]
	v_mfma_f32_16x16x32_bf16 v[84:87], v[152:155], v[226:229], v[84:87]
	v_mfma_f32_16x16x32_bf16 v[80:83], v[194:197], v[226:229], v[80:83]
	v_mfma_f32_16x16x32_bf16 v[68:71], v[152:155], v[234:237], v[68:71]
	v_mfma_f32_16x16x32_bf16 v[64:67], v[194:197], v[234:237], v[64:67]
	s_setprio 0
	s_barrier
	s_add_i32 s11, s11, s35
	s_add_i32 m0, s11, 0xffffff80
	ds_read_b128 v[198:201], v216 offset:49152
	ds_read_b128 v[202:205], v216 offset:50176
	ds_read_b128 v[210:213], v216 offset:51200
	ds_read_b128 v[218:221], v216 offset:52224
	global_load_lds_dwordx4 v[238:239], off offset:128
	s_add_i32 m0, s11, 0x1f80
	s_add_i32 s11, s14, s35
	global_load_lds_dwordx4 v[240:241], off offset:128
	s_add_i32 m0, s11, 0xffffff80
	ds_read_b128 v[234:237], v216 offset:56320
	global_load_lds_dwordx4 v[242:243], off offset:128
	s_add_i32 m0, s11, 0x1f80
	ds_read_b128 v[230:233], v216 offset:55296
	global_load_lds_dwordx4 v[214:215], off offset:128
	s_add_i32 m0, s54, 0xffffff80
	ds_read_b128 v[226:229], v216 offset:54272
	global_load_lds_dwordx4 v[244:245], off offset:128
	s_add_i32 m0, s55, 0xffffff80
	ds_read_b128 v[222:225], v216 offset:53248
	global_load_lds_dwordx4 v[246:247], off offset:128
	s_waitcnt vmcnt(8) lgkmcnt(0)
	s_setprio 1
	s_barrier
	v_mfma_f32_16x16x32_bf16 v[60:63], v[92:95], v[198:201], v[60:63]
	v_mfma_f32_16x16x32_bf16 v[56:59], v[132:135], v[198:201], v[56:59]
	v_mfma_f32_16x16x32_bf16 v[44:47], v[92:95], v[210:213], v[44:47]
	v_mfma_f32_16x16x32_bf16 v[40:43], v[132:135], v[210:213], v[40:43]
	v_mfma_f32_16x16x32_bf16 v[28:31], v[92:95], v[222:225], v[28:31]
	v_mfma_f32_16x16x32_bf16 v[24:27], v[132:135], v[222:225], v[24:27]
	v_mfma_f32_16x16x32_bf16 v[12:15], v[92:95], v[230:233], v[12:15]
	v_mfma_f32_16x16x32_bf16 v[8:11], v[132:135], v[230:233], v[8:11]
	v_mfma_f32_16x16x32_bf16 v[60:63], v[128:131], v[202:205], v[60:63]
	v_mfma_f32_16x16x32_bf16 v[56:59], v[144:147], v[202:205], v[56:59]
	v_mfma_f32_16x16x32_bf16 v[44:47], v[128:131], v[218:221], v[44:47]
	v_mfma_f32_16x16x32_bf16 v[40:43], v[144:147], v[218:221], v[40:43]
	v_mfma_f32_16x16x32_bf16 v[28:31], v[128:131], v[226:229], v[28:31]
	v_mfma_f32_16x16x32_bf16 v[24:27], v[144:147], v[226:229], v[24:27]
	v_mfma_f32_16x16x32_bf16 v[12:15], v[128:131], v[234:237], v[12:15]
	v_mfma_f32_16x16x32_bf16 v[8:11], v[144:147], v[234:237], v[8:11]
	v_mfma_f32_16x16x32_bf16 v[52:55], v[148:151], v[198:201], v[52:55]
	v_mfma_f32_16x16x32_bf16 v[48:51], v[190:193], v[198:201], v[48:51]
	v_mfma_f32_16x16x32_bf16 v[36:39], v[148:151], v[210:213], v[36:39]
	v_mfma_f32_16x16x32_bf16 v[32:35], v[190:193], v[210:213], v[32:35]
	v_mfma_f32_16x16x32_bf16 v[20:23], v[148:151], v[222:225], v[20:23]
	v_mfma_f32_16x16x32_bf16 v[16:19], v[190:193], v[222:225], v[16:19]
	v_mfma_f32_16x16x32_bf16 v[4:7], v[148:151], v[230:233], v[4:7]
	v_mfma_f32_16x16x32_bf16 v[0:3], v[190:193], v[230:233], v[0:3]
	v_mfma_f32_16x16x32_bf16 v[52:55], v[152:155], v[202:205], v[52:55]
	v_mfma_f32_16x16x32_bf16 v[48:51], v[194:197], v[202:205], v[48:51]
	v_mfma_f32_16x16x32_bf16 v[36:39], v[152:155], v[218:221], v[36:39]
	v_mfma_f32_16x16x32_bf16 v[32:35], v[194:197], v[218:221], v[32:35]
	v_mfma_f32_16x16x32_bf16 v[20:23], v[152:155], v[226:229], v[20:23]
	v_mfma_f32_16x16x32_bf16 v[16:19], v[194:197], v[226:229], v[16:19]
	v_mfma_f32_16x16x32_bf16 v[4:7], v[152:155], v[234:237], v[4:7]
	v_mfma_f32_16x16x32_bf16 v[0:3], v[194:197], v[234:237], v[0:3]
	s_setprio 0
	s_barrier
	v_lshl_add_u64 v[88:89], v[88:89], 0, s[30:31]
	s_cmp_ge_i32 s10, s57
	v_lshl_add_u64 v[90:91], v[90:91], 0, s[30:31]
	s_cbranch_scc0 .LBB0_635

; #define PG8_STAGE(bufoff, gbase, voff) do { _Pragma("unroll") for (int _i = 0; _i < 2; ++_i) \
;         __builtin_amdgcn_global_load_lds((const unsigned*)((const char*)(gbase) + (voff)[_i]), (PG8_LAS unsigned*)(lds + (bufoff) + ldsw + _i * 8192), 16, 0, 0); } while (0)
; #define PG8_LDA(dst, b, h) do { _Pragma("unroll") for (int m = 0; m < 4; ++m) _Pragma("unroll") for (int k = 0; k < 2; ++k) dst[m][k] = *(const PG8_LAS bf16x8*)(lds + PG8_SA(b, h) + aoff + m * 2048 + k * 1024); } while (0)
; #define PG8_LDB(dst, b, h) do { _Pragma("unroll") for (int n = 0; n < 2; ++n) _Pragma("unroll") for (int k = 0; k < 2; ++k) dst[n][k] = *(const PG8_LAS bf16x8*)(lds + PG8_SB(b, h) + boff + n * 2048 + k * 1024); } while (0)
; #define PG8_MMA(ai, bj, At, Bt) do { __builtin_amdgcn_s_setprio(1); _Pragma("unroll") for (int m = 0; m < 4; ++m) _Pragma("unroll") for (int n = 0; n < 2; ++n) _Pragma("unroll") for (int k = 0; k < 2; ++k) \
;         acc[ai][bj][m][n] = __builtin_amdgcn_mfma_f32_16x16x32_bf16(Bt[n][k], At[m][k], acc[ai][bj][m][n], 0, 0, 0); __builtin_amdgcn_s_setprio(0); } while (0)
; #define PG8_BAR __builtin_amdgcn_s_barrier()
; template <class Epi, class Sched, bool ALIGN_EPI = false, bool SP2 = false>
; __device__ __forceinline__ void gemm_phase(PG8_LAS unsigned char* lds, const Gemm g, const Sched& S, const Epi& E) {
;     ...
;         const bool has_next = S.next(ui + 1, nxt);
;         const char* nA = has_next ? (const char*)g.A + (size_t)nxt.pm * tstep : cA; const char* nB = has_next ? (const char*)g.Bt + (size_t)nxt.pn * tstep : cB;
;         for (int t = 0; t < nt; t += 2) {
;             const bool last = (t == nt - 2);
;             const char* a1 = cA + (size_t)(t + 1) * kstep;
;             const char* a2 = last ? nA : cA + (size_t)(t + 2) * kstep; const char* b2 = last ? nB : cB + (size_t)(t + 2) * kstep;
;             const char* a3 = a2 + kstep; const char* b3 = b2 + kstep;
;             if (last && has_next) S.a_ready(nxt);
;             if constexpr (SP2) {
;             PG8_LDB(B0, 0, 0); PG8_LDB(B1, 0, 1); PG8_SCHED; PG8_LDA(At, 0, 0); PG8_STAGE(PG8_SA(1, 1), a1 + hstep, voffA);
;             PG8_WAIT_V(8); PG8_WAIT_L(0); PG8_BAR; PG8_MMA(0, 0, At, B0); PG8_MMA(0, 1, At, B1); PG8_BAR; PG8_SCHED;
;             PG8_LDA(At, 0, 1); PG8_STAGE(PG8_SB(0, 0), b2, voffB); PG8_STAGE(PG8_SB(0, 1), b2 + hstep, voffB); PG8_STAGE(PG8_SA(0, 0), a2, voffA);
.LBB0_722:
	v_add_u32_e32 v144, s59, v183
	v_add_u32_e32 v170, s60, v183
	ds_read_b128 v[116:119], v144
	ds_read_b128 v[136:139], v144 offset:1024
	ds_read_b128 v[140:143], v144 offset:2048
	ds_read_b128 v[144:147], v144 offset:3072
	ds_read_b128 v[148:151], v170
	ds_read_b128 v[188:191], v170 offset:1024
	ds_read_b128 v[192:195], v170 offset:2048
	ds_read_b128 v[198:201], v170 offset:3072
	s_cmp_eq_u32 s53, s8
	v_lshl_add_u64 v[204:205], v[114:115], 0, s[18:19]
	s_cselect_b64 vcc, -1, 0
	s_add_i32 s8, s8, 2
	v_cndmask_b32_e32 v213, v205, v185, vcc
	v_cndmask_b32_e32 v212, v204, v184, vcc
	v_cndmask_b32_e32 v215, v113, v187, vcc
	v_cndmask_b32_e32 v214, v112, v186, vcc
	v_lshl_add_u64 v[240:241], v[114:115], 0, v[178:179]
	s_add_i32 m0, s34, 0xc000
	ds_read_b128 v[204:207], v202
	ds_read_b128 v[208:211], v202 offset:1024
	ds_read_b128 v[216:219], v202 offset:2048
	ds_read_b128 v[220:223], v202 offset:3072
	ds_read_b128 v[224:227], v202 offset:4096
	ds_read_b128 v[228:231], v202 offset:5120
	ds_read_b128 v[232:235], v202 offset:6144
	ds_read_b128 v[236:239], v202 offset:7168
	global_load_lds_dwordx4 v[240:241], off
	s_add_i32 m0, s34, 0xe000
	v_lshl_add_u64 v[240:241], v[114:115], 0, v[176:177]
	global_load_lds_dwordx4 v[240:241], off
	s_waitcnt vmcnt(8) lgkmcnt(0)
	s_setprio 1
	s_barrier
	v_mfma_f32_16x16x32_bf16 v[132:135], v[116:119], v[204:207], v[132:135]
	v_mfma_f32_16x16x32_bf16 v[128:131], v[140:143], v[204:207], v[128:131]
	v_mfma_f32_16x16x32_bf16 v[108:111], v[116:119], v[216:219], v[108:111]
	v_mfma_f32_16x16x32_bf16 v[104:107], v[140:143], v[216:219], v[104:107]
	v_mfma_f32_16x16x32_bf16 v[92:95], v[116:119], v[224:227], v[92:95]
	v_mfma_f32_16x16x32_bf16 v[88:91], v[140:143], v[224:227], v[88:91]
	v_mfma_f32_16x16x32_bf16 v[76:79], v[116:119], v[232:235], v[76:79]
	v_mfma_f32_16x16x32_bf16 v[72:75], v[140:143], v[232:235], v[72:75]
	v_mfma_f32_16x16x32_bf16 v[132:135], v[136:139], v[208:211], v[132:135]
	v_mfma_f32_16x16x32_bf16 v[128:131], v[144:147], v[208:211], v[128:131]
	v_mfma_f32_16x16x32_bf16 v[108:111], v[136:139], v[220:223], v[108:111]
	v_mfma_f32_16x16x32_bf16 v[104:107], v[144:147], v[220:223], v[104:107]
	v_mfma_f32_16x16x32_bf16 v[92:95], v[136:139], v[228:231], v[92:95]
	v_mfma_f32_16x16x32_bf16 v[88:91], v[144:147], v[228:231], v[88:91]
	v_mfma_f32_16x16x32_bf16 v[76:79], v[136:139], v[236:239], v[76:79]
	v_mfma_f32_16x16x32_bf16 v[72:75], v[144:147], v[236:239], v[72:75]
	v_mfma_f32_16x16x32_bf16 v[124:127], v[148:151], v[204:207], v[124:127]
	v_mfma_f32_16x16x32_bf16 v[120:123], v[192:195], v[204:207], v[120:123]
	v_mfma_f32_16x16x32_bf16 v[100:103], v[148:151], v[216:219], v[100:103]
	v_mfma_f32_16x16x32_bf16 v[96:99], v[192:195], v[216:219], v[96:99]
	v_mfma_f32_16x16x32_bf16 v[84:87], v[148:151], v[224:227], v[84:87]
	v_mfma_f32_16x16x32_bf16 v[80:83], v[192:195], v[224:227], v[80:83]
	v_mfma_f32_16x16x32_bf16 v[68:71], v[148:151], v[232:235], v[68:71]
	v_mfma_f32_16x16x32_bf16 v[64:67], v[192:195], v[232:235], v[64:67]
	v_mfma_f32_16x16x32_bf16 v[124:127], v[188:191], v[208:211], v[124:127]
	v_mfma_f32_16x16x32_bf16 v[120:123], v[198:201], v[208:211], v[120:123]
	v_mfma_f32_16x16x32_bf16 v[100:103], v[188:191], v[220:223], v[100:103]
	v_mfma_f32_16x16x32_bf16 v[96:99], v[198:201], v[220:223], v[96:99]
	v_mfma_f32_16x16x32_bf16 v[84:87], v[188:191], v[228:231], v[84:87]
	v_mfma_f32_16x16x32_bf16 v[80:83], v[198:201], v[228:231], v[80:83]
	v_mfma_f32_16x16x32_bf16 v[68:71], v[188:191], v[236:239], v[68:71]
	v_mfma_f32_16x16x32_bf16 v[64:67], v[198:201], v[236:239], v[64:67]
	s_setprio 0
	s_barrier
	s_add_i32 s9, s59, s29
	v_lshl_add_u64 v[240:241], v[214:215], 0, v[164:165]
	s_mov_b32 m0, s9
	ds_read_b128 v[204:207], v202 offset:16384
	ds_read_b128 v[208:211], v202 offset:17408
	ds_read_b128 v[216:219], v202 offset:18432
	ds_read_b128 v[220:223], v202 offset:19456
	ds_read_b128 v[224:227], v202 offset:20480
	ds_read_b128 v[228:231], v202 offset:21504
	ds_read_b128 v[232:235], v202 offset:22528
	ds_read_b128 v[236:239], v202 offset:23552
	global_load_lds_dwordx4 v[240:241], off
	v_lshl_add_u64 v[242:243], v[214:215], 0, v[168:169]
	s_add_i32 m0, s9, 0x2000
	v_lshl_add_u64 v[214:215], v[214:215], 0, s[12:13]
	s_add_i32 s9, s60, s29
	global_load_lds_dwordx4 v[242:243], off
	v_lshl_add_u64 v[244:245], v[214:215], 0, v[164:165]
	s_mov_b32 m0, s9
	v_lshl_add_u64 v[214:215], v[214:215], 0, v[168:169]
	global_load_lds_dwordx4 v[244:245], off
	s_add_i32 m0, s9, 0x2000
	v_lshl_add_u64 v[246:247], v[212:213], 0, v[162:163]
	global_load_lds_dwordx4 v[214:215], off
	s_mov_b32 m0, s34
	v_lshl_add_u64 v[248:249], v[212:213], 0, v[166:167]
	global_load_lds_dwordx4 v[246:247], off
	s_mov_b32 m0, s36
	s_nop 0
	global_load_lds_dwordx4 v[248:249], off
	s_waitcnt vmcnt(8) lgkmcnt(0)
	s_setprio 1
	s_barrier
; #define PG8_STAGE(bufoff, gbase, voff) do { _Pragma("unroll") for (int _i = 0; _i < 2; ++_i) \
;         __builtin_amdgcn_global_load_lds((const unsigned*)((const char*)(gbase) + (voff)[_i]), (PG8_LAS unsigned*)(lds + (bufoff) + ldsw + _i * 8192), 16, 0, 0); } while (0)
; #define PG8_LDA(dst, b, h) do { _Pragma("unroll") for (int m = 0; m < 4; ++m) _Pragma("unroll") for (int k = 0; k < 2; ++k) dst[m][k] = *(const PG8_LAS bf16x8*)(lds + PG8_SA(b, h) + aoff + m * 2048 + k * 1024); } while (0)
; #define PG8_LDB(dst, b, h) do { _Pragma("unroll") for (int n = 0; n < 2; ++n) _Pragma("unroll") for (int k = 0; k < 2; ++k) dst[n][k] = *(const PG8_LAS bf16x8*)(lds + PG8_SB(b, h) + boff + n * 2048 + k * 1024); } while (0)
; #define PG8_MMA(ai, bj, At, Bt) do { __builtin_amdgcn_s_setprio(1); _Pragma("unroll") for (int m = 0; m < 4; ++m) _Pragma("unroll") for (int n = 0; n < 2; ++n) _Pragma("unroll") for (int k = 0; k < 2; ++k) \
;         acc[ai][bj][m][n] = __builtin_amdgcn_mfma_f32_16x16x32_bf16(Bt[n][k], At[m][k], acc[ai][bj][m][n], 0, 0, 0); __builtin_amdgcn_s_setprio(0); } while (0)
; #define PG8_WAIT_V(n) asm volatile("s_waitcnt vmcnt(" #n ")" ::: "memory")
; #define PG8_WAIT_L(n) asm volatile("s_waitcnt lgkmcnt(" #n ")" ::: "memory")
; #define PG8_BAR __builtin_amdgcn_s_barrier()
; #define PG8_SCHED __builtin_amdgcn_sched_barrier(0)
; template <class Epi, class Sched, bool ALIGN_EPI = false, bool SP2 = false>
; __device__ __forceinline__ void gemm_phase(PG8_LAS unsigned char* lds, const Gemm g, const Sched& S, const Epi& E) {
;     ...
;             PG8_WAIT_V(8); PG8_WAIT_L(0); PG8_BAR; PG8_MMA(1, 0, At, B0); PG8_MMA(1, 1, At, B1); PG8_BAR; PG8_SCHED;
;             PG8_LDB(B0, 1, 0); PG8_LDB(B1, 1, 1); PG8_SCHED; PG8_LDA(At, 1, 0); PG8_STAGE(PG8_SA(0, 1), a2 + hstep, voffA);
;             PG8_WAIT_V(8); PG8_WAIT_L(0); PG8_BAR; PG8_MMA(0, 0, At, B0); PG8_MMA(0, 1, At, B1); PG8_BAR; PG8_SCHED;
	v_mfma_f32_16x16x32_bf16 v[60:63], v[116:119], v[204:207], v[60:63]
	v_mfma_f32_16x16x32_bf16 v[56:59], v[140:143], v[204:207], v[56:59]
	v_mfma_f32_16x16x32_bf16 v[44:47], v[116:119], v[216:219], v[44:47]
	v_mfma_f32_16x16x32_bf16 v[40:43], v[140:143], v[216:219], v[40:43]
	v_mfma_f32_16x16x32_bf16 v[28:31], v[116:119], v[224:227], v[28:31]
	v_mfma_f32_16x16x32_bf16 v[24:27], v[140:143], v[224:227], v[24:27]
	v_mfma_f32_16x16x32_bf16 v[12:15], v[116:119], v[232:235], v[12:15]
	v_mfma_f32_16x16x32_bf16 v[8:11], v[140:143], v[232:235], v[8:11]
	v_mfma_f32_16x16x32_bf16 v[60:63], v[136:139], v[208:211], v[60:63]
	v_mfma_f32_16x16x32_bf16 v[56:59], v[144:147], v[208:211], v[56:59]
	v_mfma_f32_16x16x32_bf16 v[44:47], v[136:139], v[220:223], v[44:47]
	v_mfma_f32_16x16x32_bf16 v[40:43], v[144:147], v[220:223], v[40:43]
	v_mfma_f32_16x16x32_bf16 v[28:31], v[136:139], v[228:231], v[28:31]
	v_mfma_f32_16x16x32_bf16 v[24:27], v[144:147], v[228:231], v[24:27]
	v_mfma_f32_16x16x32_bf16 v[12:15], v[136:139], v[236:239], v[12:15]
	v_mfma_f32_16x16x32_bf16 v[8:11], v[144:147], v[236:239], v[8:11]
	v_mfma_f32_16x16x32_bf16 v[52:55], v[148:151], v[204:207], v[52:55]
	v_mfma_f32_16x16x32_bf16 v[48:51], v[192:195], v[204:207], v[48:51]
	v_mfma_f32_16x16x32_bf16 v[36:39], v[148:151], v[216:219], v[36:39]
	v_mfma_f32_16x16x32_bf16 v[32:35], v[192:195], v[216:219], v[32:35]
	v_mfma_f32_16x16x32_bf16 v[20:23], v[148:151], v[224:227], v[20:23]
	v_mfma_f32_16x16x32_bf16 v[16:19], v[192:195], v[224:227], v[16:19]
	v_mfma_f32_16x16x32_bf16 v[4:7], v[148:151], v[232:235], v[4:7]
	v_mfma_f32_16x16x32_bf16 v[0:3], v[192:195], v[232:235], v[0:3]
	v_mfma_f32_16x16x32_bf16 v[52:55], v[188:191], v[208:211], v[52:55]
	v_mfma_f32_16x16x32_bf16 v[48:51], v[198:201], v[208:211], v[48:51]
	v_mfma_f32_16x16x32_bf16 v[36:39], v[188:191], v[220:223], v[36:39]
	v_mfma_f32_16x16x32_bf16 v[32:35], v[198:201], v[220:223], v[32:35]
	v_mfma_f32_16x16x32_bf16 v[20:23], v[188:191], v[228:231], v[20:23]
	v_mfma_f32_16x16x32_bf16 v[16:19], v[198:201], v[228:231], v[16:19]
	v_mfma_f32_16x16x32_bf16 v[4:7], v[188:191], v[236:239], v[4:7]
	v_mfma_f32_16x16x32_bf16 v[0:3], v[198:201], v[236:239], v[0:3]
	s_setprio 0
	s_barrier
	s_add_i32 s9, 0, 0x18000
	s_add_i32 s10, 0, 0x1c000
	v_add_u32_e32 v144, s9, v183
	v_add_u32_e32 v170, s10, v183
	ds_read_b128 v[116:119], v144
	ds_read_b128 v[136:139], v144 offset:1024
	ds_read_b128 v[140:143], v144 offset:2048
	ds_read_b128 v[144:147], v144 offset:3072
	ds_read_b128 v[148:151], v170
	ds_read_b128 v[188:191], v170 offset:1024
	ds_read_b128 v[192:195], v170 offset:2048
	ds_read_b128 v[198:201], v170 offset:3072
	v_lshl_add_u64 v[212:213], v[212:213], 0, s[12:13]
	s_mov_b32 m0, s37
	v_lshl_add_u64 v[250:251], v[212:213], 0, v[162:163]
	ds_read_b128 v[204:207], v202 offset:32768
	ds_read_b128 v[208:211], v202 offset:33792
	ds_read_b128 v[216:219], v202 offset:34816
	ds_read_b128 v[220:223], v202 offset:35840
	ds_read_b128 v[224:227], v202 offset:36864
	ds_read_b128 v[228:231], v202 offset:37888
	ds_read_b128 v[232:235], v202 offset:38912
	ds_read_b128 v[236:239], v202 offset:39936
	global_load_lds_dwordx4 v[250:251], off
	s_mov_b32 m0, s41
	v_lshl_add_u64 v[212:213], v[212:213], 0, v[166:167]
	global_load_lds_dwordx4 v[212:213], off
	s_waitcnt vmcnt(8) lgkmcnt(0)
	s_setprio 1
	s_barrier
; #define PG8_STAGE(bufoff, gbase, voff) do { _Pragma("unroll") for (int _i = 0; _i < 2; ++_i) \
;         __builtin_amdgcn_global_load_lds((const unsigned*)((const char*)(gbase) + (voff)[_i]), (PG8_LAS unsigned*)(lds + (bufoff) + ldsw + _i * 8192), 16, 0, 0); } while (0)
; #define PG8_LDA(dst, b, h) do { _Pragma("unroll") for (int m = 0; m < 4; ++m) _Pragma("unroll") for (int k = 0; k < 2; ++k) dst[m][k] = *(const PG8_LAS bf16x8*)(lds + PG8_SA(b, h) + aoff + m * 2048 + k * 1024); } while (0)
; #define PG8_MMA(ai, bj, At, Bt) do { __builtin_amdgcn_s_setprio(1); _Pragma("unroll") for (int m = 0; m < 4; ++m) _Pragma("unroll") for (int n = 0; n < 2; ++n) _Pragma("unroll") for (int k = 0; k < 2; ++k) \
;         acc[ai][bj][m][n] = __builtin_amdgcn_mfma_f32_16x16x32_bf16(Bt[n][k], At[m][k], acc[ai][bj][m][n], 0, 0, 0); __builtin_amdgcn_s_setprio(0); } while (0)
; #define PG8_WAIT_V(n) asm volatile("s_waitcnt vmcnt(" #n ")" ::: "memory")
; #define PG8_WAIT_L(n) asm volatile("s_waitcnt lgkmcnt(" #n ")" ::: "memory")
; #define PG8_BAR __builtin_amdgcn_s_barrier()
; #define PG8_SCHED __builtin_amdgcn_sched_barrier(0)
; template <class Epi, class Sched, bool ALIGN_EPI = false, bool SP2 = false>
; __device__ __forceinline__ void gemm_phase(PG8_LAS unsigned char* lds, const Gemm g, const Sched& S, const Epi& E) {
;     ...
;         for (int t = 0; t < nt; t += 2) {
;     ...
;             PG8_WAIT_V(8); PG8_WAIT_L(0); PG8_BAR; PG8_MMA(0, 0, At, B0); PG8_MMA(0, 1, At, B1); PG8_BAR; PG8_SCHED;
;             PG8_LDA(At, 1, 1); PG8_STAGE(PG8_SB(1, 0), b3, voffB); PG8_STAGE(PG8_SB(1, 1), b3 + hstep, voffB); PG8_STAGE(PG8_SA(1, 0), a3, voffA);
;             PG8_WAIT_V(8); PG8_WAIT_L(0); PG8_BAR; PG8_MMA(1, 0, At, B0); PG8_MMA(1, 1, At, B1); PG8_BAR; PG8_SCHED;
	v_mfma_f32_16x16x32_bf16 v[132:135], v[116:119], v[204:207], v[132:135]
	v_mfma_f32_16x16x32_bf16 v[128:131], v[140:143], v[204:207], v[128:131]
	v_mfma_f32_16x16x32_bf16 v[108:111], v[116:119], v[216:219], v[108:111]
	v_mfma_f32_16x16x32_bf16 v[104:107], v[140:143], v[216:219], v[104:107]
	v_mfma_f32_16x16x32_bf16 v[92:95], v[116:119], v[224:227], v[92:95]
	v_mfma_f32_16x16x32_bf16 v[88:91], v[140:143], v[224:227], v[88:91]
	v_mfma_f32_16x16x32_bf16 v[76:79], v[116:119], v[232:235], v[76:79]
	v_mfma_f32_16x16x32_bf16 v[72:75], v[140:143], v[232:235], v[72:75]
	v_mfma_f32_16x16x32_bf16 v[132:135], v[136:139], v[208:211], v[132:135]
	v_mfma_f32_16x16x32_bf16 v[128:131], v[144:147], v[208:211], v[128:131]
	v_mfma_f32_16x16x32_bf16 v[108:111], v[136:139], v[220:223], v[108:111]
	v_mfma_f32_16x16x32_bf16 v[104:107], v[144:147], v[220:223], v[104:107]
	v_mfma_f32_16x16x32_bf16 v[92:95], v[136:139], v[228:231], v[92:95]
	v_mfma_f32_16x16x32_bf16 v[88:91], v[144:147], v[228:231], v[88:91]
	v_mfma_f32_16x16x32_bf16 v[76:79], v[136:139], v[236:239], v[76:79]
	v_mfma_f32_16x16x32_bf16 v[72:75], v[144:147], v[236:239], v[72:75]
	v_mfma_f32_16x16x32_bf16 v[124:127], v[148:151], v[204:207], v[124:127]
	v_mfma_f32_16x16x32_bf16 v[120:123], v[192:195], v[204:207], v[120:123]
	v_mfma_f32_16x16x32_bf16 v[100:103], v[148:151], v[216:219], v[100:103]
	v_mfma_f32_16x16x32_bf16 v[96:99], v[192:195], v[216:219], v[96:99]
	v_mfma_f32_16x16x32_bf16 v[84:87], v[148:151], v[224:227], v[84:87]
	v_mfma_f32_16x16x32_bf16 v[80:83], v[192:195], v[224:227], v[80:83]
	v_mfma_f32_16x16x32_bf16 v[68:71], v[148:151], v[232:235], v[68:71]
	v_mfma_f32_16x16x32_bf16 v[64:67], v[192:195], v[232:235], v[64:67]
	v_mfma_f32_16x16x32_bf16 v[124:127], v[188:191], v[208:211], v[124:127]
	v_mfma_f32_16x16x32_bf16 v[120:123], v[198:201], v[208:211], v[120:123]
	v_mfma_f32_16x16x32_bf16 v[100:103], v[188:191], v[220:223], v[100:103]
	v_mfma_f32_16x16x32_bf16 v[96:99], v[198:201], v[220:223], v[96:99]
	v_mfma_f32_16x16x32_bf16 v[84:87], v[188:191], v[228:231], v[84:87]
	v_mfma_f32_16x16x32_bf16 v[80:83], v[198:201], v[228:231], v[80:83]
	v_mfma_f32_16x16x32_bf16 v[68:71], v[188:191], v[236:239], v[68:71]
	v_mfma_f32_16x16x32_bf16 v[64:67], v[198:201], v[236:239], v[64:67]
	s_setprio 0
	s_barrier
	s_add_i32 s9, s9, s29
	s_add_i32 m0, s9, 0xffffff80
	ds_read_b128 v[204:207], v202 offset:49152
	ds_read_b128 v[208:211], v202 offset:50176
	ds_read_b128 v[216:219], v202 offset:51200
	ds_read_b128 v[220:223], v202 offset:52224
	global_load_lds_dwordx4 v[240:241], off offset:128
	s_add_i32 m0, s9, 0x1f80
	s_add_i32 s9, s10, s29
	global_load_lds_dwordx4 v[242:243], off offset:128
	s_add_i32 m0, s9, 0xffffff80
	ds_read_b128 v[236:239], v202 offset:56320
	global_load_lds_dwordx4 v[244:245], off offset:128
	s_add_i32 m0, s9, 0x1f80
	ds_read_b128 v[232:235], v202 offset:55296
	global_load_lds_dwordx4 v[214:215], off offset:128
	s_add_i32 m0, s49, 0xffffff80
	ds_read_b128 v[228:231], v202 offset:54272
	global_load_lds_dwordx4 v[246:247], off offset:128
	s_add_i32 m0, s50, 0xffffff80
	ds_read_b128 v[224:227], v202 offset:53248
	global_load_lds_dwordx4 v[248:249], off offset:128
	s_waitcnt vmcnt(8) lgkmcnt(0)
	s_setprio 1
	s_barrier
	v_mfma_f32_16x16x32_bf16 v[60:63], v[116:119], v[204:207], v[60:63]
	v_mfma_f32_16x16x32_bf16 v[56:59], v[140:143], v[204:207], v[56:59]
	v_mfma_f32_16x16x32_bf16 v[44:47], v[116:119], v[216:219], v[44:47]
	v_mfma_f32_16x16x32_bf16 v[40:43], v[140:143], v[216:219], v[40:43]
	v_mfma_f32_16x16x32_bf16 v[28:31], v[116:119], v[224:227], v[28:31]
	v_mfma_f32_16x16x32_bf16 v[24:27], v[140:143], v[224:227], v[24:27]
	v_mfma_f32_16x16x32_bf16 v[12:15], v[116:119], v[232:235], v[12:15]
	v_mfma_f32_16x16x32_bf16 v[8:11], v[140:143], v[232:235], v[8:11]
	v_mfma_f32_16x16x32_bf16 v[60:63], v[136:139], v[208:211], v[60:63]
	v_mfma_f32_16x16x32_bf16 v[56:59], v[144:147], v[208:211], v[56:59]
	v_mfma_f32_16x16x32_bf16 v[44:47], v[136:139], v[220:223], v[44:47]
	v_mfma_f32_16x16x32_bf16 v[40:43], v[144:147], v[220:223], v[40:43]
	v_mfma_f32_16x16x32_bf16 v[28:31], v[136:139], v[228:231], v[28:31]
	v_mfma_f32_16x16x32_bf16 v[24:27], v[144:147], v[228:231], v[24:27]
	v_mfma_f32_16x16x32_bf16 v[12:15], v[136:139], v[236:239], v[12:15]
	v_mfma_f32_16x16x32_bf16 v[8:11], v[144:147], v[236:239], v[8:11]
	v_mfma_f32_16x16x32_bf16 v[52:55], v[148:151], v[204:207], v[52:55]
	v_mfma_f32_16x16x32_bf16 v[48:51], v[192:195], v[204:207], v[48:51]
	v_mfma_f32_16x16x32_bf16 v[36:39], v[148:151], v[216:219], v[36:39]
	v_mfma_f32_16x16x32_bf16 v[32:35], v[192:195], v[216:219], v[32:35]
	v_mfma_f32_16x16x32_bf16 v[20:23], v[148:151], v[224:227], v[20:23]
	v_mfma_f32_16x16x32_bf16 v[16:19], v[192:195], v[224:227], v[16:19]
	v_mfma_f32_16x16x32_bf16 v[4:7], v[148:151], v[232:235], v[4:7]
	v_mfma_f32_16x16x32_bf16 v[0:3], v[192:195], v[232:235], v[0:3]
	v_mfma_f32_16x16x32_bf16 v[52:55], v[188:191], v[208:211], v[52:55]
	v_mfma_f32_16x16x32_bf16 v[48:51], v[198:201], v[208:211], v[48:51]
	v_mfma_f32_16x16x32_bf16 v[36:39], v[188:191], v[220:223], v[36:39]
	v_mfma_f32_16x16x32_bf16 v[32:35], v[198:201], v[220:223], v[32:35]
	v_mfma_f32_16x16x32_bf16 v[20:23], v[188:191], v[228:231], v[20:23]
	v_mfma_f32_16x16x32_bf16 v[16:19], v[198:201], v[228:231], v[16:19]
	v_mfma_f32_16x16x32_bf16 v[4:7], v[188:191], v[236:239], v[4:7]
	v_mfma_f32_16x16x32_bf16 v[0:3], v[198:201], v[236:239], v[0:3]
	s_setprio 0
	s_barrier
	v_lshl_add_u64 v[112:113], v[112:113], 0, s[26:27]
	s_cmp_ge_i32 s8, s51
	v_lshl_add_u64 v[114:115], v[114:115], 0, s[26:27]
	s_cbranch_scc0 .LBB0_722

; #define PG8_STAGE(bufoff, gbase, voff) do { _Pragma("unroll") for (int _i = 0; _i < 2; ++_i) \
;         __builtin_amdgcn_global_load_lds((const unsigned*)((const char*)(gbase) + (voff)[_i]), (PG8_LAS unsigned*)(lds + (bufoff) + ldsw + _i * 8192), 16, 0, 0); } while (0)
; #define PG8_LDA(dst, b, h) do { _Pragma("unroll") for (int m = 0; m < 4; ++m) _Pragma("unroll") for (int k = 0; k < 2; ++k) dst[m][k] = *(const PG8_LAS bf16x8*)(lds + PG8_SA(b, h) + aoff + m * 2048 + k * 1024); } while (0)
; #define PG8_LDB(dst, b, h) do { _Pragma("unroll") for (int n = 0; n < 2; ++n) _Pragma("unroll") for (int k = 0; k < 2; ++k) dst[n][k] = *(const PG8_LAS bf16x8*)(lds + PG8_SB(b, h) + boff + n * 2048 + k * 1024); } while (0)
; #define PG8_MMA(ai, bj, At, Bt) do { __builtin_amdgcn_s_setprio(1); _Pragma("unroll") for (int m = 0; m < 4; ++m) _Pragma("unroll") for (int n = 0; n < 2; ++n) _Pragma("unroll") for (int k = 0; k < 2; ++k) \
;         acc[ai][bj][m][n] = __builtin_amdgcn_mfma_f32_16x16x32_bf16(Bt[n][k], At[m][k], acc[ai][bj][m][n], 0, 0, 0); __builtin_amdgcn_s_setprio(0); } while (0)
; #define PG8_BAR __builtin_amdgcn_s_barrier()
; template <class Epi, class Sched, bool ALIGN_EPI = false, bool SP2 = false>
; __device__ __forceinline__ void gemm_phase(PG8_LAS unsigned char* lds, const Gemm g, const Sched& S, const Epi& E) {
;     ...
;         const bool has_next = S.next(ui + 1, nxt);
;         const char* nA = has_next ? (const char*)g.A + (size_t)nxt.pm * tstep : cA; const char* nB = has_next ? (const char*)g.Bt + (size_t)nxt.pn * tstep : cB;
;         for (int t = 0; t < nt; t += 2) {
;             const bool last = (t == nt - 2);
;             const char* a1 = cA + (size_t)(t + 1) * kstep;
;             const char* a2 = last ? nA : cA + (size_t)(t + 2) * kstep; const char* b2 = last ? nB : cB + (size_t)(t + 2) * kstep;
;             const char* a3 = a2 + kstep; const char* b3 = b2 + kstep;
;             if (last && has_next) S.a_ready(nxt);
;             if constexpr (SP2) {
;             PG8_LDB(B0, 0, 0); PG8_LDB(B1, 0, 1); PG8_SCHED; PG8_LDA(At, 0, 0); PG8_STAGE(PG8_SA(1, 1), a1 + hstep, voffA);
;             PG8_WAIT_V(8); PG8_WAIT_L(0); PG8_BAR; PG8_MMA(0, 0, At, B0); PG8_MMA(0, 1, At, B1); PG8_BAR; PG8_SCHED;
;             PG8_LDA(At, 0, 1); PG8_STAGE(PG8_SB(0, 0), b2, voffB); PG8_STAGE(PG8_SB(0, 1), b2 + hstep, voffB); PG8_STAGE(PG8_SA(0, 0), a2, voffA);
.LBB0_940:
	v_add_u32_e32 v188, s55, v199
	ds_read_b128 v[132:135], v201
	ds_read_b128 v[136:139], v201 offset:1024
	ds_read_b128 v[140:143], v201 offset:2048
	ds_read_b128 v[144:147], v201 offset:3072
	ds_read_b128 v[148:151], v188
	ds_read_b128 v[180:183], v188 offset:1024
	ds_read_b128 v[184:187], v188 offset:2048
	ds_read_b128 v[188:191], v188 offset:3072
	s_cmp_eq_u32 s48, s12
	v_lshl_add_u64 v[192:193], v[130:131], 0, s[22:23]
	s_cselect_b64 vcc, -1, 0
	s_add_i32 s12, s12, 2
	v_cndmask_b32_e32 v197, v193, v177, vcc
	v_cndmask_b32_e32 v196, v192, v176, vcc
	v_cndmask_b32_e32 v213, v129, v179, vcc
	v_cndmask_b32_e32 v212, v128, v178, vcc
	s_mov_b32 m0, s56
	v_lshl_add_u64 v[214:215], v[130:131], 0, v[172:173]
	ds_read_b128 v[192:195], v202
	ds_read_b128 v[204:207], v202 offset:1024
	ds_read_b128 v[208:211], v202 offset:2048
	ds_read_b128 v[216:219], v202 offset:3072
	ds_read_b128 v[220:223], v202 offset:4096
	ds_read_b128 v[224:227], v202 offset:5120
	ds_read_b128 v[228:231], v202 offset:6144
	ds_read_b128 v[232:235], v202 offset:7168
	global_load_lds_dwordx4 v[214:215], off
	s_mov_b32 m0, s57
	v_lshl_add_u64 v[214:215], v[130:131], 0, v[170:171]
	global_load_lds_dwordx4 v[214:215], off
	s_waitcnt vmcnt(8) lgkmcnt(0)
	s_setprio 1
	s_barrier
	v_mfma_f32_16x16x32_bf16 v[120:123], v[132:135], v[192:195], v[120:123]
	v_mfma_f32_16x16x32_bf16 v[124:127], v[140:143], v[192:195], v[124:127]
	v_mfma_f32_16x16x32_bf16 v[108:111], v[132:135], v[208:211], v[108:111]
	v_mfma_f32_16x16x32_bf16 v[104:107], v[140:143], v[208:211], v[104:107]
	v_mfma_f32_16x16x32_bf16 v[92:95], v[132:135], v[220:223], v[92:95]
	v_mfma_f32_16x16x32_bf16 v[88:91], v[140:143], v[220:223], v[88:91]
	v_mfma_f32_16x16x32_bf16 v[76:79], v[132:135], v[228:231], v[76:79]
	v_mfma_f32_16x16x32_bf16 v[72:75], v[140:143], v[228:231], v[72:75]
	v_mfma_f32_16x16x32_bf16 v[120:123], v[136:139], v[204:207], v[120:123]
	v_mfma_f32_16x16x32_bf16 v[124:127], v[144:147], v[204:207], v[124:127]
	v_mfma_f32_16x16x32_bf16 v[108:111], v[136:139], v[216:219], v[108:111]
	v_mfma_f32_16x16x32_bf16 v[104:107], v[144:147], v[216:219], v[104:107]
	v_mfma_f32_16x16x32_bf16 v[92:95], v[136:139], v[224:227], v[92:95]
	v_mfma_f32_16x16x32_bf16 v[88:91], v[144:147], v[224:227], v[88:91]
	v_mfma_f32_16x16x32_bf16 v[76:79], v[136:139], v[232:235], v[76:79]
	v_mfma_f32_16x16x32_bf16 v[72:75], v[144:147], v[232:235], v[72:75]
	v_mfma_f32_16x16x32_bf16 v[116:119], v[148:151], v[192:195], v[116:119]
	v_mfma_f32_16x16x32_bf16 v[112:115], v[184:187], v[192:195], v[112:115]
	v_mfma_f32_16x16x32_bf16 v[100:103], v[148:151], v[208:211], v[100:103]
	v_mfma_f32_16x16x32_bf16 v[96:99], v[184:187], v[208:211], v[96:99]
	v_mfma_f32_16x16x32_bf16 v[84:87], v[148:151], v[220:223], v[84:87]
	v_mfma_f32_16x16x32_bf16 v[80:83], v[184:187], v[220:223], v[80:83]
	v_mfma_f32_16x16x32_bf16 v[68:71], v[148:151], v[228:231], v[68:71]
	v_mfma_f32_16x16x32_bf16 v[64:67], v[184:187], v[228:231], v[64:67]
	v_mfma_f32_16x16x32_bf16 v[116:119], v[180:183], v[204:207], v[116:119]
	v_mfma_f32_16x16x32_bf16 v[112:115], v[188:191], v[204:207], v[112:115]
	v_mfma_f32_16x16x32_bf16 v[100:103], v[180:183], v[216:219], v[100:103]
	v_mfma_f32_16x16x32_bf16 v[96:99], v[188:191], v[216:219], v[96:99]
	v_mfma_f32_16x16x32_bf16 v[84:87], v[180:183], v[224:227], v[84:87]
	v_mfma_f32_16x16x32_bf16 v[80:83], v[188:191], v[224:227], v[80:83]
	v_mfma_f32_16x16x32_bf16 v[68:71], v[180:183], v[232:235], v[68:71]
	v_mfma_f32_16x16x32_bf16 v[64:67], v[188:191], v[232:235], v[64:67]
	s_setprio 0
	s_barrier
	s_mov_b32 m0, s58
	v_lshl_add_u64 v[214:215], v[212:213], 0, v[164:165]
	ds_read_b128 v[192:195], v202 offset:16384
	ds_read_b128 v[204:207], v202 offset:17408
	ds_read_b128 v[208:211], v202 offset:18432
	ds_read_b128 v[216:219], v202 offset:19456
	ds_read_b128 v[220:223], v202 offset:20480
	ds_read_b128 v[224:227], v202 offset:21504
	ds_read_b128 v[228:231], v202 offset:22528
	ds_read_b128 v[232:235], v202 offset:23552
	global_load_lds_dwordx4 v[214:215], off
	v_lshl_add_u64 v[236:237], v[212:213], 0, v[168:169]
	s_mov_b32 m0, s59
	v_lshl_add_u64 v[212:213], v[212:213], 0, s[14:15]
	s_add_i32 s13, s55, s30
	global_load_lds_dwordx4 v[236:237], off
	v_lshl_add_u64 v[238:239], v[212:213], 0, v[164:165]
	s_mov_b32 m0, s13
	v_lshl_add_u64 v[212:213], v[212:213], 0, v[168:169]
	global_load_lds_dwordx4 v[238:239], off
	s_add_i32 m0, s13, 0x2000
	v_lshl_add_u64 v[240:241], v[196:197], 0, v[162:163]
	global_load_lds_dwordx4 v[212:213], off
	s_mov_b32 m0, s31
	v_lshl_add_u64 v[242:243], v[196:197], 0, v[166:167]
	global_load_lds_dwordx4 v[240:241], off
	s_mov_b32 m0, s34
	s_nop 0
	global_load_lds_dwordx4 v[242:243], off
	s_waitcnt vmcnt(8) lgkmcnt(0)
	s_setprio 1
	s_barrier
; #define PG8_STAGE(bufoff, gbase, voff) do { _Pragma("unroll") for (int _i = 0; _i < 2; ++_i) \
;         __builtin_amdgcn_global_load_lds((const unsigned*)((const char*)(gbase) + (voff)[_i]), (PG8_LAS unsigned*)(lds + (bufoff) + ldsw + _i * 8192), 16, 0, 0); } while (0)
; #define PG8_LDA(dst, b, h) do { _Pragma("unroll") for (int m = 0; m < 4; ++m) _Pragma("unroll") for (int k = 0; k < 2; ++k) dst[m][k] = *(const PG8_LAS bf16x8*)(lds + PG8_SA(b, h) + aoff + m * 2048 + k * 1024); } while (0)
; #define PG8_LDB(dst, b, h) do { _Pragma("unroll") for (int n = 0; n < 2; ++n) _Pragma("unroll") for (int k = 0; k < 2; ++k) dst[n][k] = *(const PG8_LAS bf16x8*)(lds + PG8_SB(b, h) + boff + n * 2048 + k * 1024); } while (0)
; #define PG8_MMA(ai, bj, At, Bt) do { __builtin_amdgcn_s_setprio(1); _Pragma("unroll") for (int m = 0; m < 4; ++m) _Pragma("unroll") for (int n = 0; n < 2; ++n) _Pragma("unroll") for (int k = 0; k < 2; ++k) \
;         acc[ai][bj][m][n] = __builtin_amdgcn_mfma_f32_16x16x32_bf16(Bt[n][k], At[m][k], acc[ai][bj][m][n], 0, 0, 0); __builtin_amdgcn_s_setprio(0); } while (0)
; #define PG8_WAIT_V(n) asm volatile("s_waitcnt vmcnt(" #n ")" ::: "memory")
; #define PG8_WAIT_L(n) asm volatile("s_waitcnt lgkmcnt(" #n ")" ::: "memory")
; #define PG8_BAR __builtin_amdgcn_s_barrier()
; #define PG8_SCHED __builtin_amdgcn_sched_barrier(0)
; template <class Epi, class Sched, bool ALIGN_EPI = false, bool SP2 = false>
; __device__ __forceinline__ void gemm_phase(PG8_LAS unsigned char* lds, const Gemm g, const Sched& S, const Epi& E) {
;     ...
;             PG8_WAIT_V(8); PG8_WAIT_L(0); PG8_BAR; PG8_MMA(1, 0, At, B0); PG8_MMA(1, 1, At, B1); PG8_BAR; PG8_SCHED;
;             PG8_LDB(B0, 1, 0); PG8_LDB(B1, 1, 1); PG8_SCHED; PG8_LDA(At, 1, 0); PG8_STAGE(PG8_SA(0, 1), a2 + hstep, voffA);
;             PG8_WAIT_V(8); PG8_WAIT_L(0); PG8_BAR; PG8_MMA(0, 0, At, B0); PG8_MMA(0, 1, At, B1); PG8_BAR; PG8_SCHED;
	v_mfma_f32_16x16x32_bf16 v[60:63], v[132:135], v[192:195], v[60:63]
	v_mfma_f32_16x16x32_bf16 v[56:59], v[140:143], v[192:195], v[56:59]
	v_mfma_f32_16x16x32_bf16 v[44:47], v[132:135], v[208:211], v[44:47]
	v_mfma_f32_16x16x32_bf16 v[40:43], v[140:143], v[208:211], v[40:43]
	v_mfma_f32_16x16x32_bf16 v[28:31], v[132:135], v[220:223], v[28:31]
	v_mfma_f32_16x16x32_bf16 v[24:27], v[140:143], v[220:223], v[24:27]
	v_mfma_f32_16x16x32_bf16 v[12:15], v[132:135], v[228:231], v[12:15]
	v_mfma_f32_16x16x32_bf16 v[8:11], v[140:143], v[228:231], v[8:11]
	v_mfma_f32_16x16x32_bf16 v[60:63], v[136:139], v[204:207], v[60:63]
	v_mfma_f32_16x16x32_bf16 v[56:59], v[144:147], v[204:207], v[56:59]
	v_mfma_f32_16x16x32_bf16 v[44:47], v[136:139], v[216:219], v[44:47]
	v_mfma_f32_16x16x32_bf16 v[40:43], v[144:147], v[216:219], v[40:43]
	v_mfma_f32_16x16x32_bf16 v[28:31], v[136:139], v[224:227], v[28:31]
	v_mfma_f32_16x16x32_bf16 v[24:27], v[144:147], v[224:227], v[24:27]
	v_mfma_f32_16x16x32_bf16 v[12:15], v[136:139], v[232:235], v[12:15]
	v_mfma_f32_16x16x32_bf16 v[8:11], v[144:147], v[232:235], v[8:11]
	v_mfma_f32_16x16x32_bf16 v[52:55], v[148:151], v[192:195], v[52:55]
	v_mfma_f32_16x16x32_bf16 v[48:51], v[184:187], v[192:195], v[48:51]
	v_mfma_f32_16x16x32_bf16 v[36:39], v[148:151], v[208:211], v[36:39]
	v_mfma_f32_16x16x32_bf16 v[32:35], v[184:187], v[208:211], v[32:35]
	v_mfma_f32_16x16x32_bf16 v[20:23], v[148:151], v[220:223], v[20:23]
	v_mfma_f32_16x16x32_bf16 v[16:19], v[184:187], v[220:223], v[16:19]
	v_mfma_f32_16x16x32_bf16 v[4:7], v[148:151], v[228:231], v[4:7]
	v_mfma_f32_16x16x32_bf16 v[0:3], v[184:187], v[228:231], v[0:3]
	v_mfma_f32_16x16x32_bf16 v[52:55], v[180:183], v[204:207], v[52:55]
	v_mfma_f32_16x16x32_bf16 v[48:51], v[188:191], v[204:207], v[48:51]
	v_mfma_f32_16x16x32_bf16 v[36:39], v[180:183], v[216:219], v[36:39]
	v_mfma_f32_16x16x32_bf16 v[32:35], v[188:191], v[216:219], v[32:35]
	v_mfma_f32_16x16x32_bf16 v[20:23], v[180:183], v[224:227], v[20:23]
	v_mfma_f32_16x16x32_bf16 v[16:19], v[188:191], v[224:227], v[16:19]
	v_mfma_f32_16x16x32_bf16 v[4:7], v[180:183], v[232:235], v[4:7]
	v_mfma_f32_16x16x32_bf16 v[0:3], v[188:191], v[232:235], v[0:3]
	s_setprio 0
	s_barrier
	s_add_i32 s13, 0, 0x18000
	s_add_i32 s29, 0, 0x1c000
	v_add_u32_e32 v144, s13, v199
	v_add_u32_e32 v188, s29, v199
	ds_read_b128 v[132:135], v144
	ds_read_b128 v[136:139], v144 offset:1024
	ds_read_b128 v[140:143], v144 offset:2048
	ds_read_b128 v[144:147], v144 offset:3072
	ds_read_b128 v[148:151], v188
	ds_read_b128 v[180:183], v188 offset:1024
	ds_read_b128 v[184:187], v188 offset:2048
	ds_read_b128 v[188:191], v188 offset:3072
	v_lshl_add_u64 v[196:197], v[196:197], 0, s[14:15]
	s_mov_b32 m0, s35
	v_lshl_add_u64 v[244:245], v[196:197], 0, v[162:163]
	ds_read_b128 v[192:195], v202 offset:32768
	ds_read_b128 v[204:207], v202 offset:33792
	ds_read_b128 v[208:211], v202 offset:34816
	ds_read_b128 v[216:219], v202 offset:35840
	ds_read_b128 v[220:223], v202 offset:36864
	ds_read_b128 v[224:227], v202 offset:37888
	ds_read_b128 v[228:231], v202 offset:38912
	ds_read_b128 v[232:235], v202 offset:39936
	global_load_lds_dwordx4 v[244:245], off
	s_mov_b32 m0, s36
	v_lshl_add_u64 v[196:197], v[196:197], 0, v[166:167]
	global_load_lds_dwordx4 v[196:197], off
	s_waitcnt vmcnt(8) lgkmcnt(0)
	s_setprio 1
	s_barrier
; #define PG8_STAGE(bufoff, gbase, voff) do { _Pragma("unroll") for (int _i = 0; _i < 2; ++_i) \
;         __builtin_amdgcn_global_load_lds((const unsigned*)((const char*)(gbase) + (voff)[_i]), (PG8_LAS unsigned*)(lds + (bufoff) + ldsw + _i * 8192), 16, 0, 0); } while (0)
; #define PG8_LDA(dst, b, h) do { _Pragma("unroll") for (int m = 0; m < 4; ++m) _Pragma("unroll") for (int k = 0; k < 2; ++k) dst[m][k] = *(const PG8_LAS bf16x8*)(lds + PG8_SA(b, h) + aoff + m * 2048 + k * 1024); } while (0)
; #define PG8_MMA(ai, bj, At, Bt) do { __builtin_amdgcn_s_setprio(1); _Pragma("unroll") for (int m = 0; m < 4; ++m) _Pragma("unroll") for (int n = 0; n < 2; ++n) _Pragma("unroll") for (int k = 0; k < 2; ++k) \
;         acc[ai][bj][m][n] = __builtin_amdgcn_mfma_f32_16x16x32_bf16(Bt[n][k], At[m][k], acc[ai][bj][m][n], 0, 0, 0); __builtin_amdgcn_s_setprio(0); } while (0)
; #define PG8_WAIT_V(n) asm volatile("s_waitcnt vmcnt(" #n ")" ::: "memory")
; #define PG8_WAIT_L(n) asm volatile("s_waitcnt lgkmcnt(" #n ")" ::: "memory")
; #define PG8_BAR __builtin_amdgcn_s_barrier()
; #define PG8_SCHED __builtin_amdgcn_sched_barrier(0)
; template <class Epi, class Sched, bool ALIGN_EPI = false, bool SP2 = false>
; __device__ __forceinline__ void gemm_phase(PG8_LAS unsigned char* lds, const Gemm g, const Sched& S, const Epi& E) {
;     ...
;         for (int t = 0; t < nt; t += 2) {
;     ...
;             PG8_WAIT_V(8); PG8_WAIT_L(0); PG8_BAR; PG8_MMA(0, 0, At, B0); PG8_MMA(0, 1, At, B1); PG8_BAR; PG8_SCHED;
;             PG8_LDA(At, 1, 1); PG8_STAGE(PG8_SB(1, 0), b3, voffB); PG8_STAGE(PG8_SB(1, 1), b3 + hstep, voffB); PG8_STAGE(PG8_SA(1, 0), a3, voffA);
;             PG8_WAIT_V(8); PG8_WAIT_L(0); PG8_BAR; PG8_MMA(1, 0, At, B0); PG8_MMA(1, 1, At, B1); PG8_BAR; PG8_SCHED;
	v_mfma_f32_16x16x32_bf16 v[120:123], v[132:135], v[192:195], v[120:123]
	v_mfma_f32_16x16x32_bf16 v[124:127], v[140:143], v[192:195], v[124:127]
	v_mfma_f32_16x16x32_bf16 v[108:111], v[132:135], v[208:211], v[108:111]
	v_mfma_f32_16x16x32_bf16 v[104:107], v[140:143], v[208:211], v[104:107]
	v_mfma_f32_16x16x32_bf16 v[92:95], v[132:135], v[220:223], v[92:95]
	v_mfma_f32_16x16x32_bf16 v[88:91], v[140:143], v[220:223], v[88:91]
	v_mfma_f32_16x16x32_bf16 v[76:79], v[132:135], v[228:231], v[76:79]
	v_mfma_f32_16x16x32_bf16 v[72:75], v[140:143], v[228:231], v[72:75]
	v_mfma_f32_16x16x32_bf16 v[120:123], v[136:139], v[204:207], v[120:123]
	v_mfma_f32_16x16x32_bf16 v[124:127], v[144:147], v[204:207], v[124:127]
	v_mfma_f32_16x16x32_bf16 v[108:111], v[136:139], v[216:219], v[108:111]
	v_mfma_f32_16x16x32_bf16 v[104:107], v[144:147], v[216:219], v[104:107]
	v_mfma_f32_16x16x32_bf16 v[92:95], v[136:139], v[224:227], v[92:95]
	v_mfma_f32_16x16x32_bf16 v[88:91], v[144:147], v[224:227], v[88:91]
	v_mfma_f32_16x16x32_bf16 v[76:79], v[136:139], v[232:235], v[76:79]
	v_mfma_f32_16x16x32_bf16 v[72:75], v[144:147], v[232:235], v[72:75]
	v_mfma_f32_16x16x32_bf16 v[116:119], v[148:151], v[192:195], v[116:119]
	v_mfma_f32_16x16x32_bf16 v[112:115], v[184:187], v[192:195], v[112:115]
	v_mfma_f32_16x16x32_bf16 v[100:103], v[148:151], v[208:211], v[100:103]
	v_mfma_f32_16x16x32_bf16 v[96:99], v[184:187], v[208:211], v[96:99]
	v_mfma_f32_16x16x32_bf16 v[84:87], v[148:151], v[220:223], v[84:87]
	v_mfma_f32_16x16x32_bf16 v[80:83], v[184:187], v[220:223], v[80:83]
	v_mfma_f32_16x16x32_bf16 v[68:71], v[148:151], v[228:231], v[68:71]
	v_mfma_f32_16x16x32_bf16 v[64:67], v[184:187], v[228:231], v[64:67]
	v_mfma_f32_16x16x32_bf16 v[116:119], v[180:183], v[204:207], v[116:119]
	v_mfma_f32_16x16x32_bf16 v[112:115], v[188:191], v[204:207], v[112:115]
	v_mfma_f32_16x16x32_bf16 v[100:103], v[180:183], v[216:219], v[100:103]
	v_mfma_f32_16x16x32_bf16 v[96:99], v[188:191], v[216:219], v[96:99]
	v_mfma_f32_16x16x32_bf16 v[84:87], v[180:183], v[224:227], v[84:87]
	v_mfma_f32_16x16x32_bf16 v[80:83], v[188:191], v[224:227], v[80:83]
	v_mfma_f32_16x16x32_bf16 v[68:71], v[180:183], v[232:235], v[68:71]
	v_mfma_f32_16x16x32_bf16 v[64:67], v[188:191], v[232:235], v[64:67]
	s_setprio 0
	s_barrier
	s_add_i32 s13, s13, s30
	s_add_i32 m0, s13, 0xffffff80
	ds_read_b128 v[192:195], v202 offset:49152
	ds_read_b128 v[204:207], v202 offset:50176
	ds_read_b128 v[208:211], v202 offset:51200
	ds_read_b128 v[216:219], v202 offset:52224
	global_load_lds_dwordx4 v[214:215], off offset:128
	s_add_i32 m0, s13, 0x1f80
	s_add_i32 s13, s29, s30
	global_load_lds_dwordx4 v[236:237], off offset:128
	s_add_i32 m0, s13, 0xffffff80
	ds_read_b128 v[232:235], v202 offset:56320
	global_load_lds_dwordx4 v[238:239], off offset:128
	s_add_i32 m0, s13, 0x1f80
	ds_read_b128 v[228:231], v202 offset:55296
	global_load_lds_dwordx4 v[212:213], off offset:128
	s_add_i32 m0, s37, 0xffffff80
	ds_read_b128 v[224:227], v202 offset:54272
	global_load_lds_dwordx4 v[240:241], off offset:128
	s_add_i32 m0, s41, 0xffffff80
	ds_read_b128 v[220:223], v202 offset:53248
	global_load_lds_dwordx4 v[242:243], off offset:128
	s_waitcnt vmcnt(8) lgkmcnt(0)
	s_setprio 1
	s_barrier
	v_mfma_f32_16x16x32_bf16 v[60:63], v[132:135], v[192:195], v[60:63]
	v_mfma_f32_16x16x32_bf16 v[56:59], v[140:143], v[192:195], v[56:59]
	v_mfma_f32_16x16x32_bf16 v[44:47], v[132:135], v[208:211], v[44:47]
	v_mfma_f32_16x16x32_bf16 v[40:43], v[140:143], v[208:211], v[40:43]
	v_mfma_f32_16x16x32_bf16 v[28:31], v[132:135], v[220:223], v[28:31]
	v_mfma_f32_16x16x32_bf16 v[24:27], v[140:143], v[220:223], v[24:27]
	v_mfma_f32_16x16x32_bf16 v[12:15], v[132:135], v[228:231], v[12:15]
	v_mfma_f32_16x16x32_bf16 v[8:11], v[140:143], v[228:231], v[8:11]
	v_mfma_f32_16x16x32_bf16 v[60:63], v[136:139], v[204:207], v[60:63]
	v_mfma_f32_16x16x32_bf16 v[56:59], v[144:147], v[204:207], v[56:59]
	v_mfma_f32_16x16x32_bf16 v[44:47], v[136:139], v[216:219], v[44:47]
	v_mfma_f32_16x16x32_bf16 v[40:43], v[144:147], v[216:219], v[40:43]
	v_mfma_f32_16x16x32_bf16 v[28:31], v[136:139], v[224:227], v[28:31]
	v_mfma_f32_16x16x32_bf16 v[24:27], v[144:147], v[224:227], v[24:27]
	v_mfma_f32_16x16x32_bf16 v[12:15], v[136:139], v[232:235], v[12:15]
	v_mfma_f32_16x16x32_bf16 v[8:11], v[144:147], v[232:235], v[8:11]
	v_mfma_f32_16x16x32_bf16 v[52:55], v[148:151], v[192:195], v[52:55]
	v_mfma_f32_16x16x32_bf16 v[48:51], v[184:187], v[192:195], v[48:51]
	v_mfma_f32_16x16x32_bf16 v[36:39], v[148:151], v[208:211], v[36:39]
	v_mfma_f32_16x16x32_bf16 v[32:35], v[184:187], v[208:211], v[32:35]
	v_mfma_f32_16x16x32_bf16 v[20:23], v[148:151], v[220:223], v[20:23]
	v_mfma_f32_16x16x32_bf16 v[16:19], v[184:187], v[220:223], v[16:19]
	v_mfma_f32_16x16x32_bf16 v[4:7], v[148:151], v[228:231], v[4:7]
	v_mfma_f32_16x16x32_bf16 v[0:3], v[184:187], v[228:231], v[0:3]
	v_mfma_f32_16x16x32_bf16 v[52:55], v[180:183], v[204:207], v[52:55]
	v_mfma_f32_16x16x32_bf16 v[48:51], v[188:191], v[204:207], v[48:51]
	v_mfma_f32_16x16x32_bf16 v[36:39], v[180:183], v[216:219], v[36:39]
	v_mfma_f32_16x16x32_bf16 v[32:35], v[188:191], v[216:219], v[32:35]
	v_mfma_f32_16x16x32_bf16 v[20:23], v[180:183], v[224:227], v[20:23]
	v_mfma_f32_16x16x32_bf16 v[16:19], v[188:191], v[224:227], v[16:19]
	v_mfma_f32_16x16x32_bf16 v[4:7], v[180:183], v[232:235], v[4:7]
	v_mfma_f32_16x16x32_bf16 v[0:3], v[188:191], v[232:235], v[0:3]
	s_setprio 0
	s_barrier
	v_lshl_add_u64 v[128:129], v[128:129], 0, s[26:27]
	s_cmp_ge_i32 s12, s47
	v_lshl_add_u64 v[130:131], v[130:131], 0, s[26:27]
	s_cbranch_scc0 .LBB0_940

; #define PG8_STAGE(bufoff, gbase, voff) do { _Pragma("unroll") for (int _i = 0; _i < 2; ++_i) \
;         __builtin_amdgcn_global_load_lds((const unsigned*)((const char*)(gbase) + (voff)[_i]), (PG8_LAS unsigned*)(lds + (bufoff) + ldsw + _i * 8192), 16, 0, 0); } while (0)
; #define PG8_LDA(dst, b, h) do { _Pragma("unroll") for (int m = 0; m < 4; ++m) _Pragma("unroll") for (int k = 0; k < 2; ++k) dst[m][k] = *(const PG8_LAS bf16x8*)(lds + PG8_SA(b, h) + aoff + m * 2048 + k * 1024); } while (0)
; #define PG8_LDB(dst, b, h) do { _Pragma("unroll") for (int n = 0; n < 2; ++n) _Pragma("unroll") for (int k = 0; k < 2; ++k) dst[n][k] = *(const PG8_LAS bf16x8*)(lds + PG8_SB(b, h) + boff + n * 2048 + k * 1024); } while (0)
; #define PG8_MMA(ai, bj, At, Bt) do { __builtin_amdgcn_s_setprio(1); _Pragma("unroll") for (int m = 0; m < 4; ++m) _Pragma("unroll") for (int n = 0; n < 2; ++n) _Pragma("unroll") for (int k = 0; k < 2; ++k) \
;         acc[ai][bj][m][n] = __builtin_amdgcn_mfma_f32_16x16x32_bf16(Bt[n][k], At[m][k], acc[ai][bj][m][n], 0, 0, 0); __builtin_amdgcn_s_setprio(0); } while (0)
; #define PG8_BAR __builtin_amdgcn_s_barrier()
; template <class Epi, class Sched, bool ALIGN_EPI = false, bool SP2 = false>
; __device__ __forceinline__ void gemm_phase(PG8_LAS unsigned char* lds, const Gemm g, const Sched& S, const Epi& E) {
;     ...
;         const bool has_next = S.next(ui + 1, nxt);
;         const char* nA = has_next ? (const char*)g.A + (size_t)nxt.pm * tstep : cA; const char* nB = has_next ? (const char*)g.Bt + (size_t)nxt.pn * tstep : cB;
;         for (int t = 0; t < nt; t += 2) {
;             const bool last = (t == nt - 2);
;             const char* a1 = cA + (size_t)(t + 1) * kstep;
;             const char* a2 = last ? nA : cA + (size_t)(t + 2) * kstep; const char* b2 = last ? nB : cB + (size_t)(t + 2) * kstep;
;             const char* a3 = a2 + kstep; const char* b3 = b2 + kstep;
;             if (last && has_next) S.a_ready(nxt);
;             if constexpr (SP2) {
;             PG8_LDB(B0, 0, 0); PG8_LDB(B1, 0, 1); PG8_SCHED; PG8_LDA(At, 0, 0); PG8_STAGE(PG8_SA(1, 1), a1 + hstep, voffA);
;             PG8_WAIT_V(8); PG8_WAIT_L(0); PG8_BAR; PG8_MMA(0, 0, At, B0); PG8_MMA(0, 1, At, B1); PG8_BAR; PG8_SCHED;
;             PG8_LDA(At, 0, 1); PG8_STAGE(PG8_SB(0, 0), b2, voffB); PG8_STAGE(PG8_SB(0, 1), b2 + hstep, voffB); PG8_STAGE(PG8_SA(0, 0), a2, voffA);
.LBB0_1021:
	v_add_u32_e32 v166, s55, v169
	v_add_u32_e32 v168, s56, v169
	ds_read_b128 v[162:165], v166
	ds_read_b128 v[182:185], v166 offset:1024
	ds_read_b128 v[186:189], v166 offset:2048
	ds_read_b128 v[190:193], v166 offset:3072
	ds_read_b128 v[194:197], v168
	ds_read_b128 v[198:201], v168 offset:1024
	ds_read_b128 v[202:205], v168 offset:2048
	ds_read_b128 v[206:209], v168 offset:3072
	s_cmp_eq_u32 s54, s10
	v_lshl_add_u64 v[172:173], v[160:161], 0, s[22:23]
	s_cselect_b64 vcc, -1, 0
	s_add_i32 s10, s10, 2
	v_cndmask_b32_e32 v173, v173, v153, vcc
	v_cndmask_b32_e32 v172, v172, v152, vcc
	v_cndmask_b32_e32 v215, v159, v155, vcc
	v_cndmask_b32_e32 v214, v158, v154, vcc
	s_mov_b32 m0, s57
	v_lshl_add_u64 v[244:245], v[160:161], 0, v[148:149]
	ds_read_b128 v[210:213], v179
	ds_read_b128 v[216:219], v179 offset:1024
	ds_read_b128 v[220:223], v179 offset:2048
	ds_read_b128 v[224:227], v179 offset:3072
	ds_read_b128 v[228:231], v179 offset:4096
	ds_read_b128 v[232:235], v179 offset:5120
	ds_read_b128 v[236:239], v179 offset:6144
	ds_read_b128 v[240:243], v179 offset:7168
	global_load_lds_dwordx4 v[244:245], off
	s_mov_b32 m0, s58
	v_lshl_add_u64 v[244:245], v[160:161], 0, v[146:147]
	global_load_lds_dwordx4 v[244:245], off
	s_waitcnt vmcnt(8) lgkmcnt(0)
	s_setprio 1
	s_barrier
	v_mfma_f32_16x16x32_bf16 v[124:127], v[162:165], v[210:213], v[124:127]
	v_mfma_f32_16x16x32_bf16 v[116:119], v[186:189], v[210:213], v[116:119]
	v_mfma_f32_16x16x32_bf16 v[108:111], v[162:165], v[220:223], v[108:111]
	v_mfma_f32_16x16x32_bf16 v[100:103], v[186:189], v[220:223], v[100:103]
	v_mfma_f32_16x16x32_bf16 v[92:95], v[162:165], v[228:231], v[92:95]
	v_mfma_f32_16x16x32_bf16 v[84:87], v[186:189], v[228:231], v[84:87]
	v_mfma_f32_16x16x32_bf16 v[76:79], v[162:165], v[236:239], v[76:79]
	v_mfma_f32_16x16x32_bf16 v[68:71], v[186:189], v[236:239], v[68:71]
	v_mfma_f32_16x16x32_bf16 v[124:127], v[182:185], v[216:219], v[124:127]
	v_mfma_f32_16x16x32_bf16 v[116:119], v[190:193], v[216:219], v[116:119]
	v_mfma_f32_16x16x32_bf16 v[108:111], v[182:185], v[224:227], v[108:111]
	v_mfma_f32_16x16x32_bf16 v[100:103], v[190:193], v[224:227], v[100:103]
	v_mfma_f32_16x16x32_bf16 v[92:95], v[182:185], v[232:235], v[92:95]
	v_mfma_f32_16x16x32_bf16 v[84:87], v[190:193], v[232:235], v[84:87]
	v_mfma_f32_16x16x32_bf16 v[76:79], v[182:185], v[240:243], v[76:79]
	v_mfma_f32_16x16x32_bf16 v[68:71], v[190:193], v[240:243], v[68:71]
	v_mfma_f32_16x16x32_bf16 v[120:123], v[194:197], v[210:213], v[120:123]
	v_mfma_f32_16x16x32_bf16 v[112:115], v[202:205], v[210:213], v[112:115]
	v_mfma_f32_16x16x32_bf16 v[104:107], v[194:197], v[220:223], v[104:107]
	v_mfma_f32_16x16x32_bf16 v[96:99], v[202:205], v[220:223], v[96:99]
	v_mfma_f32_16x16x32_bf16 v[88:91], v[194:197], v[228:231], v[88:91]
	v_mfma_f32_16x16x32_bf16 v[80:83], v[202:205], v[228:231], v[80:83]
	v_mfma_f32_16x16x32_bf16 v[72:75], v[194:197], v[236:239], v[72:75]
	v_mfma_f32_16x16x32_bf16 v[64:67], v[202:205], v[236:239], v[64:67]
	v_mfma_f32_16x16x32_bf16 v[120:123], v[198:201], v[216:219], v[120:123]
	v_mfma_f32_16x16x32_bf16 v[112:115], v[206:209], v[216:219], v[112:115]
	v_mfma_f32_16x16x32_bf16 v[104:107], v[198:201], v[224:227], v[104:107]
	v_mfma_f32_16x16x32_bf16 v[96:99], v[206:209], v[224:227], v[96:99]
	v_mfma_f32_16x16x32_bf16 v[88:91], v[198:201], v[232:235], v[88:91]
	v_mfma_f32_16x16x32_bf16 v[80:83], v[206:209], v[232:235], v[80:83]
	v_mfma_f32_16x16x32_bf16 v[72:75], v[198:201], v[240:243], v[72:75]
	v_mfma_f32_16x16x32_bf16 v[64:67], v[206:209], v[240:243], v[64:67]
	s_setprio 0
	s_barrier
	s_mov_b32 m0, s61
	v_lshl_add_u64 v[244:245], v[214:215], 0, v[138:139]
	ds_read_b128 v[210:213], v179 offset:16384
	ds_read_b128 v[216:219], v179 offset:17408
	ds_read_b128 v[220:223], v179 offset:18432
	ds_read_b128 v[224:227], v179 offset:19456
	ds_read_b128 v[228:231], v179 offset:20480
	ds_read_b128 v[232:235], v179 offset:21504
	ds_read_b128 v[236:239], v179 offset:22528
	ds_read_b128 v[240:243], v179 offset:23552
	global_load_lds_dwordx4 v[244:245], off
	v_lshl_add_u64 v[246:247], v[214:215], 0, v[134:135]
	s_mov_b32 m0, s62
	v_lshl_add_u64 v[214:215], v[214:215], 0, s[14:15]
	global_load_lds_dwordx4 v[246:247], off
	v_lshl_add_u64 v[248:249], v[214:215], 0, v[138:139]
	s_mov_b32 m0, s63
	v_lshl_add_u64 v[214:215], v[214:215], 0, v[134:135]
	global_load_lds_dwordx4 v[248:249], off
	s_add_i32 m0, s63, 0x2000
	v_lshl_add_u64 v[250:251], v[172:173], 0, v[140:141]
	global_load_lds_dwordx4 v[214:215], off
	s_mov_b32 m0, s46
	v_lshl_add_u64 v[252:253], v[172:173], 0, v[136:137]
	global_load_lds_dwordx4 v[250:251], off
	s_mov_b32 m0, s47
	s_nop 0
	global_load_lds_dwordx4 v[252:253], off
	s_waitcnt vmcnt(8) lgkmcnt(0)
	s_setprio 1
	s_barrier
; #define PG8_STAGE(bufoff, gbase, voff) do { _Pragma("unroll") for (int _i = 0; _i < 2; ++_i) \
;         __builtin_amdgcn_global_load_lds((const unsigned*)((const char*)(gbase) + (voff)[_i]), (PG8_LAS unsigned*)(lds + (bufoff) + ldsw + _i * 8192), 16, 0, 0); } while (0)
; #define PG8_LDA(dst, b, h) do { _Pragma("unroll") for (int m = 0; m < 4; ++m) _Pragma("unroll") for (int k = 0; k < 2; ++k) dst[m][k] = *(const PG8_LAS bf16x8*)(lds + PG8_SA(b, h) + aoff + m * 2048 + k * 1024); } while (0)
; #define PG8_LDB(dst, b, h) do { _Pragma("unroll") for (int n = 0; n < 2; ++n) _Pragma("unroll") for (int k = 0; k < 2; ++k) dst[n][k] = *(const PG8_LAS bf16x8*)(lds + PG8_SB(b, h) + boff + n * 2048 + k * 1024); } while (0)
; #define PG8_MMA(ai, bj, At, Bt) do { __builtin_amdgcn_s_setprio(1); _Pragma("unroll") for (int m = 0; m < 4; ++m) _Pragma("unroll") for (int n = 0; n < 2; ++n) _Pragma("unroll") for (int k = 0; k < 2; ++k) \
;         acc[ai][bj][m][n] = __builtin_amdgcn_mfma_f32_16x16x32_bf16(Bt[n][k], At[m][k], acc[ai][bj][m][n], 0, 0, 0); __builtin_amdgcn_s_setprio(0); } while (0)
; #define PG8_WAIT_V(n) asm volatile("s_waitcnt vmcnt(" #n ")" ::: "memory")
; #define PG8_WAIT_L(n) asm volatile("s_waitcnt lgkmcnt(" #n ")" ::: "memory")
; #define PG8_BAR __builtin_amdgcn_s_barrier()
; #define PG8_SCHED __builtin_amdgcn_sched_barrier(0)
; template <class Epi, class Sched, bool ALIGN_EPI = false, bool SP2 = false>
; __device__ __forceinline__ void gemm_phase(PG8_LAS unsigned char* lds, const Gemm g, const Sched& S, const Epi& E) {
;     ...
;             PG8_WAIT_V(8); PG8_WAIT_L(0); PG8_BAR; PG8_MMA(1, 0, At, B0); PG8_MMA(1, 1, At, B1); PG8_BAR; PG8_SCHED;
;             PG8_LDB(B0, 1, 0); PG8_LDB(B1, 1, 1); PG8_SCHED; PG8_LDA(At, 1, 0); PG8_STAGE(PG8_SA(0, 1), a2 + hstep, voffA);
;             PG8_WAIT_V(8); PG8_WAIT_L(0); PG8_BAR; PG8_MMA(0, 0, At, B0); PG8_MMA(0, 1, At, B1); PG8_BAR; PG8_SCHED;
	v_mfma_f32_16x16x32_bf16 v[60:63], v[162:165], v[210:213], v[60:63]
	v_mfma_f32_16x16x32_bf16 v[52:55], v[186:189], v[210:213], v[52:55]
	v_mfma_f32_16x16x32_bf16 v[44:47], v[162:165], v[220:223], v[44:47]
	v_mfma_f32_16x16x32_bf16 v[36:39], v[186:189], v[220:223], v[36:39]
	v_mfma_f32_16x16x32_bf16 v[28:31], v[162:165], v[228:231], v[28:31]
	v_mfma_f32_16x16x32_bf16 v[20:23], v[186:189], v[228:231], v[20:23]
	v_mfma_f32_16x16x32_bf16 v[12:15], v[162:165], v[236:239], v[12:15]
	v_mfma_f32_16x16x32_bf16 v[4:7], v[186:189], v[236:239], v[4:7]
	v_mfma_f32_16x16x32_bf16 v[60:63], v[182:185], v[216:219], v[60:63]
	v_mfma_f32_16x16x32_bf16 v[52:55], v[190:193], v[216:219], v[52:55]
	v_mfma_f32_16x16x32_bf16 v[44:47], v[182:185], v[224:227], v[44:47]
	v_mfma_f32_16x16x32_bf16 v[36:39], v[190:193], v[224:227], v[36:39]
	v_mfma_f32_16x16x32_bf16 v[28:31], v[182:185], v[232:235], v[28:31]
	v_mfma_f32_16x16x32_bf16 v[20:23], v[190:193], v[232:235], v[20:23]
	v_mfma_f32_16x16x32_bf16 v[12:15], v[182:185], v[240:243], v[12:15]
	v_mfma_f32_16x16x32_bf16 v[4:7], v[190:193], v[240:243], v[4:7]
	v_mfma_f32_16x16x32_bf16 v[56:59], v[194:197], v[210:213], v[56:59]
	v_mfma_f32_16x16x32_bf16 v[48:51], v[202:205], v[210:213], v[48:51]
	v_mfma_f32_16x16x32_bf16 v[40:43], v[194:197], v[220:223], v[40:43]
	v_mfma_f32_16x16x32_bf16 v[32:35], v[202:205], v[220:223], v[32:35]
	v_mfma_f32_16x16x32_bf16 v[24:27], v[194:197], v[228:231], v[24:27]
	v_mfma_f32_16x16x32_bf16 v[16:19], v[202:205], v[228:231], v[16:19]
	v_mfma_f32_16x16x32_bf16 v[8:11], v[194:197], v[236:239], v[8:11]
	v_mfma_f32_16x16x32_bf16 v[0:3], v[202:205], v[236:239], v[0:3]
	v_mfma_f32_16x16x32_bf16 v[56:59], v[198:201], v[216:219], v[56:59]
	v_mfma_f32_16x16x32_bf16 v[48:51], v[206:209], v[216:219], v[48:51]
	v_mfma_f32_16x16x32_bf16 v[40:43], v[198:201], v[224:227], v[40:43]
	v_mfma_f32_16x16x32_bf16 v[32:35], v[206:209], v[224:227], v[32:35]
	v_mfma_f32_16x16x32_bf16 v[24:27], v[198:201], v[232:235], v[24:27]
	v_mfma_f32_16x16x32_bf16 v[16:19], v[206:209], v[232:235], v[16:19]
	v_mfma_f32_16x16x32_bf16 v[8:11], v[198:201], v[240:243], v[8:11]
	v_mfma_f32_16x16x32_bf16 v[0:3], v[206:209], v[240:243], v[0:3]
	s_setprio 0
	s_barrier
	s_add_i32 s11, 0, 0x18000
	v_add_u32_e32 v166, s11, v169
	s_add_i32 s13, 0, 0x1c000
	ds_read_b128 v[162:165], v166
	ds_read_b128 v[182:185], v166 offset:1024
	ds_read_b128 v[186:189], v166 offset:2048
	ds_read_b128 v[190:193], v166 offset:3072
	v_add_u32_e32 v166, s13, v169
	ds_read_b128 v[194:197], v166
	ds_read_b128 v[198:201], v166 offset:1024
	ds_read_b128 v[202:205], v166 offset:2048
	ds_read_b128 v[206:209], v166 offset:3072
	v_lshl_add_u64 v[172:173], v[172:173], 0, s[14:15]
	s_mov_b32 m0, s48
	v_lshl_add_u64 v[170:171], v[172:173], 0, v[140:141]
	ds_read_b128 v[210:213], v179 offset:32768
	ds_read_b128 v[216:219], v179 offset:33792
	ds_read_b128 v[220:223], v179 offset:34816
	ds_read_b128 v[224:227], v179 offset:35840
	ds_read_b128 v[228:231], v179 offset:36864
	ds_read_b128 v[232:235], v179 offset:37888
	ds_read_b128 v[236:239], v179 offset:38912
	ds_read_b128 v[240:243], v179 offset:39936
	global_load_lds_dwordx4 v[170:171], off
	s_mov_b32 m0, s49
	v_lshl_add_u64 v[170:171], v[172:173], 0, v[136:137]
	global_load_lds_dwordx4 v[170:171], off
	s_waitcnt vmcnt(8) lgkmcnt(0)
	s_setprio 1
	s_barrier
; #define PG8_STAGE(bufoff, gbase, voff) do { _Pragma("unroll") for (int _i = 0; _i < 2; ++_i) \
;         __builtin_amdgcn_global_load_lds((const unsigned*)((const char*)(gbase) + (voff)[_i]), (PG8_LAS unsigned*)(lds + (bufoff) + ldsw + _i * 8192), 16, 0, 0); } while (0)
; #define PG8_LDA(dst, b, h) do { _Pragma("unroll") for (int m = 0; m < 4; ++m) _Pragma("unroll") for (int k = 0; k < 2; ++k) dst[m][k] = *(const PG8_LAS bf16x8*)(lds + PG8_SA(b, h) + aoff + m * 2048 + k * 1024); } while (0)
; #define PG8_MMA(ai, bj, At, Bt) do { __builtin_amdgcn_s_setprio(1); _Pragma("unroll") for (int m = 0; m < 4; ++m) _Pragma("unroll") for (int n = 0; n < 2; ++n) _Pragma("unroll") for (int k = 0; k < 2; ++k) \
;         acc[ai][bj][m][n] = __builtin_amdgcn_mfma_f32_16x16x32_bf16(Bt[n][k], At[m][k], acc[ai][bj][m][n], 0, 0, 0); __builtin_amdgcn_s_setprio(0); } while (0)
; #define PG8_WAIT_V(n) asm volatile("s_waitcnt vmcnt(" #n ")" ::: "memory")
; #define PG8_WAIT_L(n) asm volatile("s_waitcnt lgkmcnt(" #n ")" ::: "memory")
; #define PG8_BAR __builtin_amdgcn_s_barrier()
; #define PG8_SCHED __builtin_amdgcn_sched_barrier(0)
; template <class Epi, class Sched, bool ALIGN_EPI = false, bool SP2 = false>
; __device__ __forceinline__ void gemm_phase(PG8_LAS unsigned char* lds, const Gemm g, const Sched& S, const Epi& E) {
;     ...
;         for (int t = 0; t < nt; t += 2) {
;     ...
;             PG8_WAIT_V(8); PG8_WAIT_L(0); PG8_BAR; PG8_MMA(0, 0, At, B0); PG8_MMA(0, 1, At, B1); PG8_BAR; PG8_SCHED;
;             PG8_LDA(At, 1, 1); PG8_STAGE(PG8_SB(1, 0), b3, voffB); PG8_STAGE(PG8_SB(1, 1), b3 + hstep, voffB); PG8_STAGE(PG8_SA(1, 0), a3, voffA);
;             PG8_WAIT_V(8); PG8_WAIT_L(0); PG8_BAR; PG8_MMA(1, 0, At, B0); PG8_MMA(1, 1, At, B1); PG8_BAR; PG8_SCHED;
	v_mfma_f32_16x16x32_bf16 v[124:127], v[162:165], v[210:213], v[124:127]
	v_mfma_f32_16x16x32_bf16 v[116:119], v[186:189], v[210:213], v[116:119]
	v_mfma_f32_16x16x32_bf16 v[108:111], v[162:165], v[220:223], v[108:111]
	v_mfma_f32_16x16x32_bf16 v[100:103], v[186:189], v[220:223], v[100:103]
	v_mfma_f32_16x16x32_bf16 v[92:95], v[162:165], v[228:231], v[92:95]
	v_mfma_f32_16x16x32_bf16 v[84:87], v[186:189], v[228:231], v[84:87]
	v_mfma_f32_16x16x32_bf16 v[76:79], v[162:165], v[236:239], v[76:79]
	v_mfma_f32_16x16x32_bf16 v[68:71], v[186:189], v[236:239], v[68:71]
	v_mfma_f32_16x16x32_bf16 v[124:127], v[182:185], v[216:219], v[124:127]
	v_mfma_f32_16x16x32_bf16 v[116:119], v[190:193], v[216:219], v[116:119]
	v_mfma_f32_16x16x32_bf16 v[108:111], v[182:185], v[224:227], v[108:111]
	v_mfma_f32_16x16x32_bf16 v[100:103], v[190:193], v[224:227], v[100:103]
	v_mfma_f32_16x16x32_bf16 v[92:95], v[182:185], v[232:235], v[92:95]
	v_mfma_f32_16x16x32_bf16 v[84:87], v[190:193], v[232:235], v[84:87]
	v_mfma_f32_16x16x32_bf16 v[76:79], v[182:185], v[240:243], v[76:79]
	v_mfma_f32_16x16x32_bf16 v[68:71], v[190:193], v[240:243], v[68:71]
	v_mfma_f32_16x16x32_bf16 v[120:123], v[194:197], v[210:213], v[120:123]
	v_mfma_f32_16x16x32_bf16 v[112:115], v[202:205], v[210:213], v[112:115]
	v_mfma_f32_16x16x32_bf16 v[104:107], v[194:197], v[220:223], v[104:107]
	v_mfma_f32_16x16x32_bf16 v[96:99], v[202:205], v[220:223], v[96:99]
	v_mfma_f32_16x16x32_bf16 v[88:91], v[194:197], v[228:231], v[88:91]
	v_mfma_f32_16x16x32_bf16 v[80:83], v[202:205], v[228:231], v[80:83]
	v_mfma_f32_16x16x32_bf16 v[72:75], v[194:197], v[236:239], v[72:75]
	v_mfma_f32_16x16x32_bf16 v[64:67], v[202:205], v[236:239], v[64:67]
	v_mfma_f32_16x16x32_bf16 v[120:123], v[198:201], v[216:219], v[120:123]
	v_mfma_f32_16x16x32_bf16 v[112:115], v[206:209], v[216:219], v[112:115]
	v_mfma_f32_16x16x32_bf16 v[104:107], v[198:201], v[224:227], v[104:107]
	v_mfma_f32_16x16x32_bf16 v[96:99], v[206:209], v[224:227], v[96:99]
	v_mfma_f32_16x16x32_bf16 v[88:91], v[198:201], v[232:235], v[88:91]
	v_mfma_f32_16x16x32_bf16 v[80:83], v[206:209], v[232:235], v[80:83]
	v_mfma_f32_16x16x32_bf16 v[72:75], v[198:201], v[240:243], v[72:75]
	v_mfma_f32_16x16x32_bf16 v[64:67], v[206:209], v[240:243], v[64:67]
	s_setprio 0
	s_barrier
	s_add_i32 s11, s11, s29
	s_add_i32 m0, s11, 0xffffff80
	ds_read_b128 v[210:213], v179 offset:49152
	ds_read_b128 v[216:219], v179 offset:50176
	ds_read_b128 v[220:223], v179 offset:51200
	ds_read_b128 v[224:227], v179 offset:52224
	global_load_lds_dwordx4 v[244:245], off offset:128
	s_add_i32 m0, s11, 0x1f80
	s_add_i32 s11, s13, s29
	global_load_lds_dwordx4 v[246:247], off offset:128
	s_add_i32 m0, s11, 0xffffff80
	ds_read_b128 v[240:243], v179 offset:56320
	global_load_lds_dwordx4 v[248:249], off offset:128
	s_add_i32 m0, s11, 0x1f80
	ds_read_b128 v[236:239], v179 offset:55296
	global_load_lds_dwordx4 v[214:215], off offset:128
	s_add_i32 m0, s50, 0xffffff80
	ds_read_b128 v[232:235], v179 offset:54272
	global_load_lds_dwordx4 v[250:251], off offset:128
	s_add_i32 m0, s51, 0xffffff80
	ds_read_b128 v[228:231], v179 offset:53248
	global_load_lds_dwordx4 v[252:253], off offset:128
	s_waitcnt vmcnt(8) lgkmcnt(0)
	s_setprio 1
	s_barrier
	v_mfma_f32_16x16x32_bf16 v[60:63], v[162:165], v[210:213], v[60:63]
	v_mfma_f32_16x16x32_bf16 v[52:55], v[186:189], v[210:213], v[52:55]
	v_mfma_f32_16x16x32_bf16 v[44:47], v[162:165], v[220:223], v[44:47]
	v_mfma_f32_16x16x32_bf16 v[36:39], v[186:189], v[220:223], v[36:39]
	v_mfma_f32_16x16x32_bf16 v[28:31], v[162:165], v[228:231], v[28:31]
	v_mfma_f32_16x16x32_bf16 v[20:23], v[186:189], v[228:231], v[20:23]
	v_mfma_f32_16x16x32_bf16 v[12:15], v[162:165], v[236:239], v[12:15]
	v_mfma_f32_16x16x32_bf16 v[4:7], v[186:189], v[236:239], v[4:7]
	v_mfma_f32_16x16x32_bf16 v[60:63], v[182:185], v[216:219], v[60:63]
	v_mfma_f32_16x16x32_bf16 v[52:55], v[190:193], v[216:219], v[52:55]
	v_mfma_f32_16x16x32_bf16 v[44:47], v[182:185], v[224:227], v[44:47]
	v_mfma_f32_16x16x32_bf16 v[36:39], v[190:193], v[224:227], v[36:39]
	v_mfma_f32_16x16x32_bf16 v[28:31], v[182:185], v[232:235], v[28:31]
	v_mfma_f32_16x16x32_bf16 v[20:23], v[190:193], v[232:235], v[20:23]
	v_mfma_f32_16x16x32_bf16 v[12:15], v[182:185], v[240:243], v[12:15]
	v_mfma_f32_16x16x32_bf16 v[4:7], v[190:193], v[240:243], v[4:7]
	v_mfma_f32_16x16x32_bf16 v[56:59], v[194:197], v[210:213], v[56:59]
	v_mfma_f32_16x16x32_bf16 v[48:51], v[202:205], v[210:213], v[48:51]
	v_mfma_f32_16x16x32_bf16 v[40:43], v[194:197], v[220:223], v[40:43]
	v_mfma_f32_16x16x32_bf16 v[32:35], v[202:205], v[220:223], v[32:35]
	v_mfma_f32_16x16x32_bf16 v[24:27], v[194:197], v[228:231], v[24:27]
	v_mfma_f32_16x16x32_bf16 v[16:19], v[202:205], v[228:231], v[16:19]
	v_mfma_f32_16x16x32_bf16 v[8:11], v[194:197], v[236:239], v[8:11]
	v_mfma_f32_16x16x32_bf16 v[0:3], v[202:205], v[236:239], v[0:3]
	v_mfma_f32_16x16x32_bf16 v[56:59], v[198:201], v[216:219], v[56:59]
	v_mfma_f32_16x16x32_bf16 v[48:51], v[206:209], v[216:219], v[48:51]
	v_mfma_f32_16x16x32_bf16 v[40:43], v[198:201], v[224:227], v[40:43]
	v_mfma_f32_16x16x32_bf16 v[32:35], v[206:209], v[224:227], v[32:35]
	v_mfma_f32_16x16x32_bf16 v[24:27], v[198:201], v[232:235], v[24:27]
	v_mfma_f32_16x16x32_bf16 v[16:19], v[206:209], v[232:235], v[16:19]
	v_mfma_f32_16x16x32_bf16 v[8:11], v[198:201], v[240:243], v[8:11]
	v_mfma_f32_16x16x32_bf16 v[0:3], v[206:209], v[240:243], v[0:3]
	s_setprio 0
	s_barrier
	v_lshl_add_u64 v[158:159], v[158:159], 0, s[26:27]
	s_cmp_ge_i32 s10, s52
	v_lshl_add_u64 v[160:161], v[160:161], 0, s[26:27]
	s_cbranch_scc0 .LBB0_1021

; #define PG8_STAGE(bufoff, gbase, voff) do { _Pragma("unroll") for (int _i = 0; _i < 2; ++_i) \
;         __builtin_amdgcn_global_load_lds((const unsigned*)((const char*)(gbase) + (voff)[_i]), (PG8_LAS unsigned*)(lds + (bufoff) + ldsw + _i * 8192), 16, 0, 0); } while (0)
; #define PG8_LDA(dst, b, h) do { _Pragma("unroll") for (int m = 0; m < 4; ++m) _Pragma("unroll") for (int k = 0; k < 2; ++k) dst[m][k] = *(const PG8_LAS bf16x8*)(lds + PG8_SA(b, h) + aoff + m * 2048 + k * 1024); } while (0)
; #define PG8_LDB(dst, b, h) do { _Pragma("unroll") for (int n = 0; n < 2; ++n) _Pragma("unroll") for (int k = 0; k < 2; ++k) dst[n][k] = *(const PG8_LAS bf16x8*)(lds + PG8_SB(b, h) + boff + n * 2048 + k * 1024); } while (0)
; #define PG8_MMA(ai, bj, At, Bt) do { __builtin_amdgcn_s_setprio(1); _Pragma("unroll") for (int m = 0; m < 4; ++m) _Pragma("unroll") for (int n = 0; n < 2; ++n) _Pragma("unroll") for (int k = 0; k < 2; ++k) \
;         acc[ai][bj][m][n] = __builtin_amdgcn_mfma_f32_16x16x32_bf16(Bt[n][k], At[m][k], acc[ai][bj][m][n], 0, 0, 0); __builtin_amdgcn_s_setprio(0); } while (0)
; #define PG8_BAR __builtin_amdgcn_s_barrier()
; template <class Epi, class Sched, bool ALIGN_EPI = false, bool SP2 = false>
; __device__ __forceinline__ void gemm_phase(PG8_LAS unsigned char* lds, const Gemm g, const Sched& S, const Epi& E) {
;     ...
;         const bool has_next = S.next(ui + 1, nxt);
;         const char* nA = has_next ? (const char*)g.A + (size_t)nxt.pm * tstep : cA; const char* nB = has_next ? (const char*)g.Bt + (size_t)nxt.pn * tstep : cB;
;         for (int t = 0; t < nt; t += 2) {
;             const bool last = (t == nt - 2);
;             const char* a1 = cA + (size_t)(t + 1) * kstep;
;             const char* a2 = last ? nA : cA + (size_t)(t + 2) * kstep; const char* b2 = last ? nB : cB + (size_t)(t + 2) * kstep;
;             const char* a3 = a2 + kstep; const char* b3 = b2 + kstep;
;             if (last && has_next) S.a_ready(nxt);
;             if constexpr (SP2) {
;             PG8_LDB(B0, 0, 0); PG8_LDB(B1, 0, 1); PG8_SCHED; PG8_LDA(At, 0, 0); PG8_STAGE(PG8_SA(1, 1), a1 + hstep, voffA);
;             PG8_WAIT_V(8); PG8_WAIT_L(0); PG8_BAR; PG8_MMA(0, 0, At, B0); PG8_MMA(0, 1, At, B1); PG8_BAR; PG8_SCHED;
;             PG8_LDA(At, 0, 1); PG8_STAGE(PG8_SB(0, 0), b2, voffB); PG8_STAGE(PG8_SB(0, 1), b2 + hstep, voffB); PG8_STAGE(PG8_SA(0, 0), a2, voffA);
.LBB0_1169:
	v_add_u32_e32 v192, s52, v161
	ds_read_b128 v[164:167], v162
	ds_read_b128 v[168:171], v162 offset:1024
	ds_read_b128 v[172:175], v162 offset:2048
	ds_read_b128 v[176:179], v162 offset:3072
	ds_read_b128 v[180:183], v192
	ds_read_b128 v[184:187], v192 offset:1024
	ds_read_b128 v[188:191], v192 offset:2048
	ds_read_b128 v[192:195], v192 offset:3072
	s_cmp_eq_u32 s51, s10
	v_lshl_add_u64 v[196:197], v[158:159], 0, s[24:25]
	s_cselect_b64 vcc, -1, 0
	s_add_i32 s10, s10, 2
	v_cndmask_b32_e32 v213, v197, v151, vcc
	v_cndmask_b32_e32 v212, v196, v150, vcc
	v_cndmask_b32_e32 v215, v155, v153, vcc
	v_cndmask_b32_e32 v214, v154, v152, vcc
	s_mov_b32 m0, s54
	v_lshl_add_u64 v[232:233], v[158:159], 0, v[146:147]
	ds_read_b128 v[196:199], v163
	ds_read_b128 v[200:203], v163 offset:1024
	ds_read_b128 v[204:207], v163 offset:2048
	ds_read_b128 v[208:211], v163 offset:3072
	ds_read_b128 v[216:219], v163 offset:4096
	ds_read_b128 v[220:223], v163 offset:5120
	ds_read_b128 v[224:227], v163 offset:6144
	ds_read_b128 v[228:231], v163 offset:7168
	global_load_lds_dwordx4 v[232:233], off
	s_mov_b32 m0, s55
	v_lshl_add_u64 v[232:233], v[158:159], 0, v[144:145]
	global_load_lds_dwordx4 v[232:233], off
	s_waitcnt vmcnt(8) lgkmcnt(0)
	s_setprio 1
	s_barrier
	v_mfma_f32_16x16x32_bf16 v[124:127], v[164:167], v[196:199], v[124:127]
	v_mfma_f32_16x16x32_bf16 v[120:123], v[172:175], v[196:199], v[120:123]
	v_mfma_f32_16x16x32_bf16 v[108:111], v[164:167], v[204:207], v[108:111]
	v_mfma_f32_16x16x32_bf16 v[104:107], v[172:175], v[204:207], v[104:107]
	v_mfma_f32_16x16x32_bf16 v[92:95], v[164:167], v[216:219], v[92:95]
	v_mfma_f32_16x16x32_bf16 v[88:91], v[172:175], v[216:219], v[88:91]
	v_mfma_f32_16x16x32_bf16 v[76:79], v[164:167], v[224:227], v[76:79]
	v_mfma_f32_16x16x32_bf16 v[72:75], v[172:175], v[224:227], v[72:75]
	v_mfma_f32_16x16x32_bf16 v[124:127], v[168:171], v[200:203], v[124:127]
	v_mfma_f32_16x16x32_bf16 v[120:123], v[176:179], v[200:203], v[120:123]
	v_mfma_f32_16x16x32_bf16 v[108:111], v[168:171], v[208:211], v[108:111]
	v_mfma_f32_16x16x32_bf16 v[104:107], v[176:179], v[208:211], v[104:107]
	v_mfma_f32_16x16x32_bf16 v[92:95], v[168:171], v[220:223], v[92:95]
	v_mfma_f32_16x16x32_bf16 v[88:91], v[176:179], v[220:223], v[88:91]
	v_mfma_f32_16x16x32_bf16 v[76:79], v[168:171], v[228:231], v[76:79]
	v_mfma_f32_16x16x32_bf16 v[72:75], v[176:179], v[228:231], v[72:75]
	v_mfma_f32_16x16x32_bf16 v[116:119], v[180:183], v[196:199], v[116:119]
	v_mfma_f32_16x16x32_bf16 v[112:115], v[188:191], v[196:199], v[112:115]
	v_mfma_f32_16x16x32_bf16 v[100:103], v[180:183], v[204:207], v[100:103]
	v_mfma_f32_16x16x32_bf16 v[96:99], v[188:191], v[204:207], v[96:99]
	v_mfma_f32_16x16x32_bf16 v[84:87], v[180:183], v[216:219], v[84:87]
	v_mfma_f32_16x16x32_bf16 v[80:83], v[188:191], v[216:219], v[80:83]
	v_mfma_f32_16x16x32_bf16 v[68:71], v[180:183], v[224:227], v[68:71]
	v_mfma_f32_16x16x32_bf16 v[64:67], v[188:191], v[224:227], v[64:67]
	v_mfma_f32_16x16x32_bf16 v[116:119], v[184:187], v[200:203], v[116:119]
	v_mfma_f32_16x16x32_bf16 v[112:115], v[192:195], v[200:203], v[112:115]
	v_mfma_f32_16x16x32_bf16 v[100:103], v[184:187], v[208:211], v[100:103]
	v_mfma_f32_16x16x32_bf16 v[96:99], v[192:195], v[208:211], v[96:99]
	v_mfma_f32_16x16x32_bf16 v[84:87], v[184:187], v[220:223], v[84:87]
	v_mfma_f32_16x16x32_bf16 v[80:83], v[192:195], v[220:223], v[80:83]
	v_mfma_f32_16x16x32_bf16 v[68:71], v[184:187], v[228:231], v[68:71]
	v_mfma_f32_16x16x32_bf16 v[64:67], v[192:195], v[228:231], v[64:67]
	s_setprio 0
	s_barrier
	s_mov_b32 m0, s56
	v_lshl_add_u64 v[232:233], v[214:215], 0, v[138:139]
	ds_read_b128 v[196:199], v163 offset:16384
	ds_read_b128 v[200:203], v163 offset:17408
	ds_read_b128 v[204:207], v163 offset:18432
	ds_read_b128 v[208:211], v163 offset:19456
	ds_read_b128 v[216:219], v163 offset:20480
	ds_read_b128 v[220:223], v163 offset:21504
	ds_read_b128 v[224:227], v163 offset:22528
	ds_read_b128 v[228:231], v163 offset:23552
	global_load_lds_dwordx4 v[232:233], off
	v_lshl_add_u64 v[234:235], v[214:215], 0, v[134:135]
	s_mov_b32 m0, s57
	v_lshl_add_u64 v[214:215], v[214:215], 0, s[14:15]
	global_load_lds_dwordx4 v[234:235], off
	v_lshl_add_u64 v[236:237], v[214:215], 0, v[138:139]
	s_mov_b32 m0, s58
	v_lshl_add_u64 v[214:215], v[214:215], 0, v[134:135]
	global_load_lds_dwordx4 v[236:237], off
	s_mov_b32 m0, s59
	v_lshl_add_u64 v[238:239], v[212:213], 0, v[140:141]
	global_load_lds_dwordx4 v[214:215], off
	s_mov_b32 m0, s37
	v_lshl_add_u64 v[240:241], v[212:213], 0, v[136:137]
	global_load_lds_dwordx4 v[238:239], off
	s_mov_b32 m0, s41
	s_nop 0
	global_load_lds_dwordx4 v[240:241], off
	s_waitcnt vmcnt(8) lgkmcnt(0)
	s_setprio 1
	s_barrier
; #define PG8_STAGE(bufoff, gbase, voff) do { _Pragma("unroll") for (int _i = 0; _i < 2; ++_i) \
;         __builtin_amdgcn_global_load_lds((const unsigned*)((const char*)(gbase) + (voff)[_i]), (PG8_LAS unsigned*)(lds + (bufoff) + ldsw + _i * 8192), 16, 0, 0); } while (0)
; #define PG8_LDA(dst, b, h) do { _Pragma("unroll") for (int m = 0; m < 4; ++m) _Pragma("unroll") for (int k = 0; k < 2; ++k) dst[m][k] = *(const PG8_LAS bf16x8*)(lds + PG8_SA(b, h) + aoff + m * 2048 + k * 1024); } while (0)
; #define PG8_LDB(dst, b, h) do { _Pragma("unroll") for (int n = 0; n < 2; ++n) _Pragma("unroll") for (int k = 0; k < 2; ++k) dst[n][k] = *(const PG8_LAS bf16x8*)(lds + PG8_SB(b, h) + boff + n * 2048 + k * 1024); } while (0)
; #define PG8_MMA(ai, bj, At, Bt) do { __builtin_amdgcn_s_setprio(1); _Pragma("unroll") for (int m = 0; m < 4; ++m) _Pragma("unroll") for (int n = 0; n < 2; ++n) _Pragma("unroll") for (int k = 0; k < 2; ++k) \
;         acc[ai][bj][m][n] = __builtin_amdgcn_mfma_f32_16x16x32_bf16(Bt[n][k], At[m][k], acc[ai][bj][m][n], 0, 0, 0); __builtin_amdgcn_s_setprio(0); } while (0)
; #define PG8_WAIT_V(n) asm volatile("s_waitcnt vmcnt(" #n ")" ::: "memory")
; #define PG8_WAIT_L(n) asm volatile("s_waitcnt lgkmcnt(" #n ")" ::: "memory")
; #define PG8_BAR __builtin_amdgcn_s_barrier()
; #define PG8_SCHED __builtin_amdgcn_sched_barrier(0)
; template <class Epi, class Sched, bool ALIGN_EPI = false, bool SP2 = false>
; __device__ __forceinline__ void gemm_phase(PG8_LAS unsigned char* lds, const Gemm g, const Sched& S, const Epi& E) {
;     ...
;             PG8_WAIT_V(8); PG8_WAIT_L(0); PG8_BAR; PG8_MMA(1, 0, At, B0); PG8_MMA(1, 1, At, B1); PG8_BAR; PG8_SCHED;
;             PG8_LDB(B0, 1, 0); PG8_LDB(B1, 1, 1); PG8_SCHED; PG8_LDA(At, 1, 0); PG8_STAGE(PG8_SA(0, 1), a2 + hstep, voffA);
;             PG8_WAIT_V(8); PG8_WAIT_L(0); PG8_BAR; PG8_MMA(0, 0, At, B0); PG8_MMA(0, 1, At, B1); PG8_BAR; PG8_SCHED;
	v_mfma_f32_16x16x32_bf16 v[60:63], v[164:167], v[196:199], v[60:63]
	v_mfma_f32_16x16x32_bf16 v[56:59], v[172:175], v[196:199], v[56:59]
	v_mfma_f32_16x16x32_bf16 v[44:47], v[164:167], v[204:207], v[44:47]
	v_mfma_f32_16x16x32_bf16 v[40:43], v[172:175], v[204:207], v[40:43]
	v_mfma_f32_16x16x32_bf16 v[28:31], v[164:167], v[216:219], v[28:31]
	v_mfma_f32_16x16x32_bf16 v[24:27], v[172:175], v[216:219], v[24:27]
	v_mfma_f32_16x16x32_bf16 v[12:15], v[164:167], v[224:227], v[12:15]
	v_mfma_f32_16x16x32_bf16 v[8:11], v[172:175], v[224:227], v[8:11]
	v_mfma_f32_16x16x32_bf16 v[60:63], v[168:171], v[200:203], v[60:63]
	v_mfma_f32_16x16x32_bf16 v[56:59], v[176:179], v[200:203], v[56:59]
	v_mfma_f32_16x16x32_bf16 v[44:47], v[168:171], v[208:211], v[44:47]
	v_mfma_f32_16x16x32_bf16 v[40:43], v[176:179], v[208:211], v[40:43]
	v_mfma_f32_16x16x32_bf16 v[28:31], v[168:171], v[220:223], v[28:31]
	v_mfma_f32_16x16x32_bf16 v[24:27], v[176:179], v[220:223], v[24:27]
	v_mfma_f32_16x16x32_bf16 v[12:15], v[168:171], v[228:231], v[12:15]
	v_mfma_f32_16x16x32_bf16 v[8:11], v[176:179], v[228:231], v[8:11]
	v_mfma_f32_16x16x32_bf16 v[52:55], v[180:183], v[196:199], v[52:55]
	v_mfma_f32_16x16x32_bf16 v[48:51], v[188:191], v[196:199], v[48:51]
	v_mfma_f32_16x16x32_bf16 v[36:39], v[180:183], v[204:207], v[36:39]
	v_mfma_f32_16x16x32_bf16 v[32:35], v[188:191], v[204:207], v[32:35]
	v_mfma_f32_16x16x32_bf16 v[20:23], v[180:183], v[216:219], v[20:23]
	v_mfma_f32_16x16x32_bf16 v[16:19], v[188:191], v[216:219], v[16:19]
	v_mfma_f32_16x16x32_bf16 v[4:7], v[180:183], v[224:227], v[4:7]
	v_mfma_f32_16x16x32_bf16 v[0:3], v[188:191], v[224:227], v[0:3]
	v_mfma_f32_16x16x32_bf16 v[52:55], v[184:187], v[200:203], v[52:55]
	v_mfma_f32_16x16x32_bf16 v[48:51], v[192:195], v[200:203], v[48:51]
	v_mfma_f32_16x16x32_bf16 v[36:39], v[184:187], v[208:211], v[36:39]
	v_mfma_f32_16x16x32_bf16 v[32:35], v[192:195], v[208:211], v[32:35]
	v_mfma_f32_16x16x32_bf16 v[20:23], v[184:187], v[220:223], v[20:23]
	v_mfma_f32_16x16x32_bf16 v[16:19], v[192:195], v[220:223], v[16:19]
	v_mfma_f32_16x16x32_bf16 v[4:7], v[184:187], v[228:231], v[4:7]
	v_mfma_f32_16x16x32_bf16 v[0:3], v[192:195], v[228:231], v[0:3]
	s_setprio 0
	s_barrier
	v_add_u32_e32 v176, s60, v161
	v_add_u32_e32 v192, s61, v161
	ds_read_b128 v[164:167], v176
	ds_read_b128 v[168:171], v176 offset:1024
	ds_read_b128 v[172:175], v176 offset:2048
	ds_read_b128 v[176:179], v176 offset:3072
	ds_read_b128 v[180:183], v192
	ds_read_b128 v[184:187], v192 offset:1024
	ds_read_b128 v[188:191], v192 offset:2048
	ds_read_b128 v[192:195], v192 offset:3072
	v_lshl_add_u64 v[212:213], v[212:213], 0, s[14:15]
	s_mov_b32 m0, s46
	v_lshl_add_u64 v[242:243], v[212:213], 0, v[140:141]
	ds_read_b128 v[196:199], v163 offset:32768
	ds_read_b128 v[200:203], v163 offset:33792
	ds_read_b128 v[204:207], v163 offset:34816
	ds_read_b128 v[208:211], v163 offset:35840
	ds_read_b128 v[216:219], v163 offset:36864
	ds_read_b128 v[220:223], v163 offset:37888
	ds_read_b128 v[224:227], v163 offset:38912
	ds_read_b128 v[228:231], v163 offset:39936
	global_load_lds_dwordx4 v[242:243], off
	s_mov_b32 m0, s47
	v_lshl_add_u64 v[212:213], v[212:213], 0, v[136:137]
	global_load_lds_dwordx4 v[212:213], off
	s_waitcnt vmcnt(8) lgkmcnt(0)
	s_setprio 1
	s_barrier
; #define PG8_STAGE(bufoff, gbase, voff) do { _Pragma("unroll") for (int _i = 0; _i < 2; ++_i) \
;         __builtin_amdgcn_global_load_lds((const unsigned*)((const char*)(gbase) + (voff)[_i]), (PG8_LAS unsigned*)(lds + (bufoff) + ldsw + _i * 8192), 16, 0, 0); } while (0)
; #define PG8_LDA(dst, b, h) do { _Pragma("unroll") for (int m = 0; m < 4; ++m) _Pragma("unroll") for (int k = 0; k < 2; ++k) dst[m][k] = *(const PG8_LAS bf16x8*)(lds + PG8_SA(b, h) + aoff + m * 2048 + k * 1024); } while (0)
; #define PG8_MMA(ai, bj, At, Bt) do { __builtin_amdgcn_s_setprio(1); _Pragma("unroll") for (int m = 0; m < 4; ++m) _Pragma("unroll") for (int n = 0; n < 2; ++n) _Pragma("unroll") for (int k = 0; k < 2; ++k) \
;         acc[ai][bj][m][n] = __builtin_amdgcn_mfma_f32_16x16x32_bf16(Bt[n][k], At[m][k], acc[ai][bj][m][n], 0, 0, 0); __builtin_amdgcn_s_setprio(0); } while (0)
; #define PG8_WAIT_V(n) asm volatile("s_waitcnt vmcnt(" #n ")" ::: "memory")
; #define PG8_WAIT_L(n) asm volatile("s_waitcnt lgkmcnt(" #n ")" ::: "memory")
; #define PG8_BAR __builtin_amdgcn_s_barrier()
; #define PG8_SCHED __builtin_amdgcn_sched_barrier(0)
; template <class Epi, class Sched, bool ALIGN_EPI = false, bool SP2 = false>
; __device__ __forceinline__ void gemm_phase(PG8_LAS unsigned char* lds, const Gemm g, const Sched& S, const Epi& E) {
;     ...
;         for (int t = 0; t < nt; t += 2) {
;     ...
;             PG8_WAIT_V(8); PG8_WAIT_L(0); PG8_BAR; PG8_MMA(0, 0, At, B0); PG8_MMA(0, 1, At, B1); PG8_BAR; PG8_SCHED;
;             PG8_LDA(At, 1, 1); PG8_STAGE(PG8_SB(1, 0), b3, voffB); PG8_STAGE(PG8_SB(1, 1), b3 + hstep, voffB); PG8_STAGE(PG8_SA(1, 0), a3, voffA);
;             PG8_WAIT_V(8); PG8_WAIT_L(0); PG8_BAR; PG8_MMA(1, 0, At, B0); PG8_MMA(1, 1, At, B1); PG8_BAR; PG8_SCHED;
	v_mfma_f32_16x16x32_bf16 v[124:127], v[164:167], v[196:199], v[124:127]
	v_mfma_f32_16x16x32_bf16 v[120:123], v[172:175], v[196:199], v[120:123]
	v_mfma_f32_16x16x32_bf16 v[108:111], v[164:167], v[204:207], v[108:111]
	v_mfma_f32_16x16x32_bf16 v[104:107], v[172:175], v[204:207], v[104:107]
	v_mfma_f32_16x16x32_bf16 v[92:95], v[164:167], v[216:219], v[92:95]
	v_mfma_f32_16x16x32_bf16 v[88:91], v[172:175], v[216:219], v[88:91]
	v_mfma_f32_16x16x32_bf16 v[76:79], v[164:167], v[224:227], v[76:79]
	v_mfma_f32_16x16x32_bf16 v[72:75], v[172:175], v[224:227], v[72:75]
	v_mfma_f32_16x16x32_bf16 v[124:127], v[168:171], v[200:203], v[124:127]
	v_mfma_f32_16x16x32_bf16 v[120:123], v[176:179], v[200:203], v[120:123]
	v_mfma_f32_16x16x32_bf16 v[108:111], v[168:171], v[208:211], v[108:111]
	v_mfma_f32_16x16x32_bf16 v[104:107], v[176:179], v[208:211], v[104:107]
	v_mfma_f32_16x16x32_bf16 v[92:95], v[168:171], v[220:223], v[92:95]
	v_mfma_f32_16x16x32_bf16 v[88:91], v[176:179], v[220:223], v[88:91]
	v_mfma_f32_16x16x32_bf16 v[76:79], v[168:171], v[228:231], v[76:79]
	v_mfma_f32_16x16x32_bf16 v[72:75], v[176:179], v[228:231], v[72:75]
	v_mfma_f32_16x16x32_bf16 v[116:119], v[180:183], v[196:199], v[116:119]
	v_mfma_f32_16x16x32_bf16 v[112:115], v[188:191], v[196:199], v[112:115]
	v_mfma_f32_16x16x32_bf16 v[100:103], v[180:183], v[204:207], v[100:103]
	v_mfma_f32_16x16x32_bf16 v[96:99], v[188:191], v[204:207], v[96:99]
	v_mfma_f32_16x16x32_bf16 v[84:87], v[180:183], v[216:219], v[84:87]
	v_mfma_f32_16x16x32_bf16 v[80:83], v[188:191], v[216:219], v[80:83]
	v_mfma_f32_16x16x32_bf16 v[68:71], v[180:183], v[224:227], v[68:71]
	v_mfma_f32_16x16x32_bf16 v[64:67], v[188:191], v[224:227], v[64:67]
	v_mfma_f32_16x16x32_bf16 v[116:119], v[184:187], v[200:203], v[116:119]
	v_mfma_f32_16x16x32_bf16 v[112:115], v[192:195], v[200:203], v[112:115]
	v_mfma_f32_16x16x32_bf16 v[100:103], v[184:187], v[208:211], v[100:103]
	v_mfma_f32_16x16x32_bf16 v[96:99], v[192:195], v[208:211], v[96:99]
	v_mfma_f32_16x16x32_bf16 v[84:87], v[184:187], v[220:223], v[84:87]
	v_mfma_f32_16x16x32_bf16 v[80:83], v[192:195], v[220:223], v[80:83]
	v_mfma_f32_16x16x32_bf16 v[68:71], v[184:187], v[228:231], v[68:71]
	v_mfma_f32_16x16x32_bf16 v[64:67], v[192:195], v[228:231], v[64:67]
	s_setprio 0
	s_barrier
	s_add_i32 m0, s62, 0xffffff80
	ds_read_b128 v[196:199], v163 offset:49152
	ds_read_b128 v[200:203], v163 offset:50176
	ds_read_b128 v[204:207], v163 offset:51200
	global_load_lds_dwordx4 v[232:233], off offset:128
	s_add_i32 m0, s63, 0xffffff80
	ds_read_b128 v[228:231], v163 offset:56320
	global_load_lds_dwordx4 v[234:235], off offset:128
	s_add_i32 m0, s64, 0xffffff80
	ds_read_b128 v[224:227], v163 offset:55296
	global_load_lds_dwordx4 v[236:237], off offset:128
	s_add_i32 m0, s65, 0xffffff80
	ds_read_b128 v[220:223], v163 offset:54272
	global_load_lds_dwordx4 v[214:215], off offset:128
	s_add_i32 m0, s48, 0xffffff80
	ds_read_b128 v[216:219], v163 offset:53248
	global_load_lds_dwordx4 v[238:239], off offset:128
	s_add_i32 m0, s49, 0xffffff80
	ds_read_b128 v[208:211], v163 offset:52224
	global_load_lds_dwordx4 v[240:241], off offset:128
	s_waitcnt vmcnt(8) lgkmcnt(0)
	s_setprio 1
	s_barrier
	v_mfma_f32_16x16x32_bf16 v[60:63], v[164:167], v[196:199], v[60:63]
	v_mfma_f32_16x16x32_bf16 v[56:59], v[172:175], v[196:199], v[56:59]
	v_mfma_f32_16x16x32_bf16 v[44:47], v[164:167], v[204:207], v[44:47]
	v_mfma_f32_16x16x32_bf16 v[40:43], v[172:175], v[204:207], v[40:43]
	v_mfma_f32_16x16x32_bf16 v[28:31], v[164:167], v[216:219], v[28:31]
	v_mfma_f32_16x16x32_bf16 v[24:27], v[172:175], v[216:219], v[24:27]
	v_mfma_f32_16x16x32_bf16 v[12:15], v[164:167], v[224:227], v[12:15]
	v_mfma_f32_16x16x32_bf16 v[8:11], v[172:175], v[224:227], v[8:11]
	v_mfma_f32_16x16x32_bf16 v[60:63], v[168:171], v[200:203], v[60:63]
	v_mfma_f32_16x16x32_bf16 v[56:59], v[176:179], v[200:203], v[56:59]
	v_mfma_f32_16x16x32_bf16 v[44:47], v[168:171], v[208:211], v[44:47]
	v_mfma_f32_16x16x32_bf16 v[40:43], v[176:179], v[208:211], v[40:43]
	v_mfma_f32_16x16x32_bf16 v[28:31], v[168:171], v[220:223], v[28:31]
	v_mfma_f32_16x16x32_bf16 v[24:27], v[176:179], v[220:223], v[24:27]
	v_mfma_f32_16x16x32_bf16 v[12:15], v[168:171], v[228:231], v[12:15]
	v_mfma_f32_16x16x32_bf16 v[8:11], v[176:179], v[228:231], v[8:11]
	v_mfma_f32_16x16x32_bf16 v[52:55], v[180:183], v[196:199], v[52:55]
	v_mfma_f32_16x16x32_bf16 v[48:51], v[188:191], v[196:199], v[48:51]
	v_mfma_f32_16x16x32_bf16 v[36:39], v[180:183], v[204:207], v[36:39]
	v_mfma_f32_16x16x32_bf16 v[32:35], v[188:191], v[204:207], v[32:35]
	v_mfma_f32_16x16x32_bf16 v[20:23], v[180:183], v[216:219], v[20:23]
	v_mfma_f32_16x16x32_bf16 v[16:19], v[188:191], v[216:219], v[16:19]
	v_mfma_f32_16x16x32_bf16 v[4:7], v[180:183], v[224:227], v[4:7]
	v_mfma_f32_16x16x32_bf16 v[0:3], v[188:191], v[224:227], v[0:3]
	v_mfma_f32_16x16x32_bf16 v[52:55], v[184:187], v[200:203], v[52:55]
	v_mfma_f32_16x16x32_bf16 v[48:51], v[192:195], v[200:203], v[48:51]
	v_mfma_f32_16x16x32_bf16 v[36:39], v[184:187], v[208:211], v[36:39]
	v_mfma_f32_16x16x32_bf16 v[32:35], v[192:195], v[208:211], v[32:35]
	v_mfma_f32_16x16x32_bf16 v[20:23], v[184:187], v[220:223], v[20:23]
	v_mfma_f32_16x16x32_bf16 v[16:19], v[192:195], v[220:223], v[16:19]
	v_mfma_f32_16x16x32_bf16 v[4:7], v[184:187], v[228:231], v[4:7]
	v_mfma_f32_16x16x32_bf16 v[0:3], v[192:195], v[228:231], v[0:3]
	s_setprio 0
	s_barrier
	v_lshl_add_u64 v[154:155], v[154:155], 0, s[28:29]
	s_cmp_ge_i32 s10, s50
	v_lshl_add_u64 v[158:159], v[158:159], 0, s[28:29]
	s_cbranch_scc0 .LBB0_1169

; #define PG8_STAGE(bufoff, gbase, voff) do { _Pragma("unroll") for (int _i = 0; _i < 2; ++_i) \
;         __builtin_amdgcn_global_load_lds((const unsigned*)((const char*)(gbase) + (voff)[_i]), (PG8_LAS unsigned*)(lds + (bufoff) + ldsw + _i * 8192), 16, 0, 0); } while (0)
; #define PG8_LDA(dst, b, h) do { _Pragma("unroll") for (int m = 0; m < 4; ++m) _Pragma("unroll") for (int k = 0; k < 2; ++k) dst[m][k] = *(const PG8_LAS bf16x8*)(lds + PG8_SA(b, h) + aoff + m * 2048 + k * 1024); } while (0)
; #define PG8_LDB(dst, b, h) do { _Pragma("unroll") for (int n = 0; n < 2; ++n) _Pragma("unroll") for (int k = 0; k < 2; ++k) dst[n][k] = *(const PG8_LAS bf16x8*)(lds + PG8_SB(b, h) + boff + n * 2048 + k * 1024); } while (0)
; #define PG8_MMA(ai, bj, At, Bt) do { __builtin_amdgcn_s_setprio(1); _Pragma("unroll") for (int m = 0; m < 4; ++m) _Pragma("unroll") for (int n = 0; n < 2; ++n) _Pragma("unroll") for (int k = 0; k < 2; ++k) \
;         acc[ai][bj][m][n] = __builtin_amdgcn_mfma_f32_16x16x32_bf16(Bt[n][k], At[m][k], acc[ai][bj][m][n], 0, 0, 0); __builtin_amdgcn_s_setprio(0); } while (0)
; #define PG8_BAR __builtin_amdgcn_s_barrier()
; template <class Epi, class Sched, bool ALIGN_EPI = false, bool SP2 = false>
; __device__ __forceinline__ void gemm_phase(PG8_LAS unsigned char* lds, const Gemm g, const Sched& S, const Epi& E) {
;     ...
;         const bool has_next = S.next(ui + 1, nxt);
;         const char* nA = has_next ? (const char*)g.A + (size_t)nxt.pm * tstep : cA; const char* nB = has_next ? (const char*)g.Bt + (size_t)nxt.pn * tstep : cB;
;         for (int t = 0; t < nt; t += 2) {
;             const bool last = (t == nt - 2);
;             const char* a1 = cA + (size_t)(t + 1) * kstep;
;             const char* a2 = last ? nA : cA + (size_t)(t + 2) * kstep; const char* b2 = last ? nB : cB + (size_t)(t + 2) * kstep;
;             const char* a3 = a2 + kstep; const char* b3 = b2 + kstep;
;             if (last && has_next) S.a_ready(nxt);
;             if constexpr (SP2) {
;             PG8_LDB(B0, 0, 0); PG8_LDB(B1, 0, 1); PG8_SCHED; PG8_LDA(At, 0, 0); PG8_STAGE(PG8_SA(1, 1), a1 + hstep, voffA);
;             PG8_WAIT_V(8); PG8_WAIT_L(0); PG8_BAR; PG8_MMA(0, 0, At, B0); PG8_MMA(0, 1, At, B1); PG8_BAR; PG8_SCHED;
;             PG8_LDA(At, 0, 1); PG8_STAGE(PG8_SB(0, 0), b2, voffB); PG8_STAGE(PG8_SB(0, 1), b2 + hstep, voffB); PG8_STAGE(PG8_SA(0, 0), a2, voffA);
.LBB0_1192:
	v_add_u32_e32 v178, s56, v216
	v_add_u32_e32 v194, s57, v216
	ds_read_b128 v[138:141], v178
	ds_read_b128 v[142:145], v178 offset:1024
	ds_read_b128 v[146:149], v178 offset:2048
	ds_read_b128 v[178:181], v178 offset:3072
	ds_read_b128 v[182:185], v194
	ds_read_b128 v[186:189], v194 offset:1024
	ds_read_b128 v[190:193], v194 offset:2048
	ds_read_b128 v[194:197], v194 offset:3072
	s_cmp_eq_u32 s49, s10
	v_lshl_add_u64 v[198:199], v[136:137], 0, s[20:21]
	s_cselect_b64 vcc, -1, 0
	s_add_i32 s10, s10, 2
	v_cndmask_b32_e32 v215, v199, v175, vcc
	v_cndmask_b32_e32 v214, v198, v174, vcc
	v_cndmask_b32_e32 v237, v135, v177, vcc
	v_cndmask_b32_e32 v236, v134, v176, vcc
	v_lshl_add_u64 v[238:239], v[136:137], 0, v[168:169]
	s_add_i32 m0, s34, 0xc000
	ds_read_b128 v[198:201], v218
	ds_read_b128 v[202:205], v218 offset:1024
	ds_read_b128 v[206:209], v218 offset:2048
	ds_read_b128 v[210:213], v218 offset:3072
	ds_read_b128 v[220:223], v218 offset:4096
	ds_read_b128 v[224:227], v218 offset:5120
	ds_read_b128 v[228:231], v218 offset:6144
	ds_read_b128 v[232:235], v218 offset:7168
	global_load_lds_dwordx4 v[238:239], off
	s_add_i32 m0, s34, 0xe000
	v_lshl_add_u64 v[238:239], v[136:137], 0, v[166:167]
	global_load_lds_dwordx4 v[238:239], off
	s_waitcnt vmcnt(8) lgkmcnt(0)
	s_setprio 1
	s_barrier
	v_mfma_f32_16x16x32_bf16 v[130:133], v[138:141], v[198:201], v[130:133]
	v_mfma_f32_16x16x32_bf16 v[126:129], v[146:149], v[198:201], v[126:129]
	v_mfma_f32_16x16x32_bf16 v[114:117], v[138:141], v[206:209], v[114:117]
	v_mfma_f32_16x16x32_bf16 v[110:113], v[146:149], v[206:209], v[110:113]
	v_mfma_f32_16x16x32_bf16 v[98:101], v[138:141], v[220:223], v[98:101]
	v_mfma_f32_16x16x32_bf16 v[94:97], v[146:149], v[220:223], v[94:97]
	v_mfma_f32_16x16x32_bf16 v[82:85], v[138:141], v[228:231], v[82:85]
	v_mfma_f32_16x16x32_bf16 v[78:81], v[146:149], v[228:231], v[78:81]
	v_mfma_f32_16x16x32_bf16 v[130:133], v[142:145], v[202:205], v[130:133]
	v_mfma_f32_16x16x32_bf16 v[126:129], v[178:181], v[202:205], v[126:129]
	v_mfma_f32_16x16x32_bf16 v[114:117], v[142:145], v[210:213], v[114:117]
	v_mfma_f32_16x16x32_bf16 v[110:113], v[178:181], v[210:213], v[110:113]
	v_mfma_f32_16x16x32_bf16 v[98:101], v[142:145], v[224:227], v[98:101]
	v_mfma_f32_16x16x32_bf16 v[94:97], v[178:181], v[224:227], v[94:97]
	v_mfma_f32_16x16x32_bf16 v[82:85], v[142:145], v[232:235], v[82:85]
	v_mfma_f32_16x16x32_bf16 v[78:81], v[178:181], v[232:235], v[78:81]
	v_mfma_f32_16x16x32_bf16 v[122:125], v[182:185], v[198:201], v[122:125]
	v_mfma_f32_16x16x32_bf16 v[118:121], v[190:193], v[198:201], v[118:121]
	v_mfma_f32_16x16x32_bf16 v[106:109], v[182:185], v[206:209], v[106:109]
	v_mfma_f32_16x16x32_bf16 v[102:105], v[190:193], v[206:209], v[102:105]
	v_mfma_f32_16x16x32_bf16 v[90:93], v[182:185], v[220:223], v[90:93]
	v_mfma_f32_16x16x32_bf16 v[86:89], v[190:193], v[220:223], v[86:89]
	v_mfma_f32_16x16x32_bf16 v[74:77], v[182:185], v[228:231], v[74:77]
	v_mfma_f32_16x16x32_bf16 v[70:73], v[190:193], v[228:231], v[70:73]
	v_mfma_f32_16x16x32_bf16 v[122:125], v[186:189], v[202:205], v[122:125]
	v_mfma_f32_16x16x32_bf16 v[118:121], v[194:197], v[202:205], v[118:121]
	v_mfma_f32_16x16x32_bf16 v[106:109], v[186:189], v[210:213], v[106:109]
	v_mfma_f32_16x16x32_bf16 v[102:105], v[194:197], v[210:213], v[102:105]
	v_mfma_f32_16x16x32_bf16 v[90:93], v[186:189], v[224:227], v[90:93]
	v_mfma_f32_16x16x32_bf16 v[86:89], v[194:197], v[224:227], v[86:89]
	v_mfma_f32_16x16x32_bf16 v[74:77], v[186:189], v[232:235], v[74:77]
	v_mfma_f32_16x16x32_bf16 v[70:73], v[194:197], v[232:235], v[70:73]
	s_setprio 0
	s_barrier
	s_add_i32 s11, s56, s29
	v_lshl_add_u64 v[238:239], v[236:237], 0, v[158:159]
	s_mov_b32 m0, s11
	ds_read_b128 v[198:201], v218 offset:16384
	ds_read_b128 v[202:205], v218 offset:17408
	ds_read_b128 v[206:209], v218 offset:18432
	ds_read_b128 v[210:213], v218 offset:19456
	ds_read_b128 v[220:223], v218 offset:20480
	ds_read_b128 v[224:227], v218 offset:21504
	ds_read_b128 v[228:231], v218 offset:22528
	ds_read_b128 v[232:235], v218 offset:23552
	global_load_lds_dwordx4 v[238:239], off
	v_lshl_add_u64 v[240:241], v[236:237], 0, v[162:163]
	s_add_i32 m0, s11, 0x2000
	v_lshl_add_u64 v[236:237], v[236:237], 0, s[12:13]
	s_add_i32 s11, s57, s29
	global_load_lds_dwordx4 v[240:241], off
	v_lshl_add_u64 v[242:243], v[236:237], 0, v[158:159]
	s_mov_b32 m0, s11
	v_lshl_add_u64 v[236:237], v[236:237], 0, v[162:163]
	global_load_lds_dwordx4 v[242:243], off
	s_add_i32 m0, s11, 0x2000
	v_lshl_add_u64 v[244:245], v[214:215], 0, v[154:155]
	global_load_lds_dwordx4 v[236:237], off
	s_mov_b32 m0, s34
	v_lshl_add_u64 v[246:247], v[214:215], 0, v[160:161]
	global_load_lds_dwordx4 v[244:245], off
	s_mov_b32 m0, s35
	s_nop 0
	global_load_lds_dwordx4 v[246:247], off
	s_waitcnt vmcnt(8) lgkmcnt(0)
	s_setprio 1
	s_barrier
; #define PG8_STAGE(bufoff, gbase, voff) do { _Pragma("unroll") for (int _i = 0; _i < 2; ++_i) \
;         __builtin_amdgcn_global_load_lds((const unsigned*)((const char*)(gbase) + (voff)[_i]), (PG8_LAS unsigned*)(lds + (bufoff) + ldsw + _i * 8192), 16, 0, 0); } while (0)
; #define PG8_LDA(dst, b, h) do { _Pragma("unroll") for (int m = 0; m < 4; ++m) _Pragma("unroll") for (int k = 0; k < 2; ++k) dst[m][k] = *(const PG8_LAS bf16x8*)(lds + PG8_SA(b, h) + aoff + m * 2048 + k * 1024); } while (0)
; #define PG8_LDB(dst, b, h) do { _Pragma("unroll") for (int n = 0; n < 2; ++n) _Pragma("unroll") for (int k = 0; k < 2; ++k) dst[n][k] = *(const PG8_LAS bf16x8*)(lds + PG8_SB(b, h) + boff + n * 2048 + k * 1024); } while (0)
; #define PG8_MMA(ai, bj, At, Bt) do { __builtin_amdgcn_s_setprio(1); _Pragma("unroll") for (int m = 0; m < 4; ++m) _Pragma("unroll") for (int n = 0; n < 2; ++n) _Pragma("unroll") for (int k = 0; k < 2; ++k) \
;         acc[ai][bj][m][n] = __builtin_amdgcn_mfma_f32_16x16x32_bf16(Bt[n][k], At[m][k], acc[ai][bj][m][n], 0, 0, 0); __builtin_amdgcn_s_setprio(0); } while (0)
; #define PG8_WAIT_V(n) asm volatile("s_waitcnt vmcnt(" #n ")" ::: "memory")
; #define PG8_WAIT_L(n) asm volatile("s_waitcnt lgkmcnt(" #n ")" ::: "memory")
; #define PG8_BAR __builtin_amdgcn_s_barrier()
; #define PG8_SCHED __builtin_amdgcn_sched_barrier(0)
; template <class Epi, class Sched, bool ALIGN_EPI = false, bool SP2 = false>
; __device__ __forceinline__ void gemm_phase(PG8_LAS unsigned char* lds, const Gemm g, const Sched& S, const Epi& E) {
;     ...
;             PG8_WAIT_V(8); PG8_WAIT_L(0); PG8_BAR; PG8_MMA(1, 0, At, B0); PG8_MMA(1, 1, At, B1); PG8_BAR; PG8_SCHED;
;             PG8_LDB(B0, 1, 0); PG8_LDB(B1, 1, 1); PG8_SCHED; PG8_LDA(At, 1, 0); PG8_STAGE(PG8_SA(0, 1), a2 + hstep, voffA);
;             PG8_WAIT_V(8); PG8_WAIT_L(0); PG8_BAR; PG8_MMA(0, 0, At, B0); PG8_MMA(0, 1, At, B1); PG8_BAR; PG8_SCHED;
	v_mfma_f32_16x16x32_bf16 v[66:69], v[138:141], v[198:201], v[66:69]
	v_mfma_f32_16x16x32_bf16 v[62:65], v[146:149], v[198:201], v[62:65]
	v_mfma_f32_16x16x32_bf16 v[50:53], v[138:141], v[206:209], v[50:53]
	v_mfma_f32_16x16x32_bf16 v[46:49], v[146:149], v[206:209], v[46:49]
	v_mfma_f32_16x16x32_bf16 v[34:37], v[138:141], v[220:223], v[34:37]
	v_mfma_f32_16x16x32_bf16 v[30:33], v[146:149], v[220:223], v[30:33]
	v_mfma_f32_16x16x32_bf16 v[18:21], v[138:141], v[228:231], v[18:21]
	v_mfma_f32_16x16x32_bf16 v[14:17], v[146:149], v[228:231], v[14:17]
	v_mfma_f32_16x16x32_bf16 v[66:69], v[142:145], v[202:205], v[66:69]
	v_mfma_f32_16x16x32_bf16 v[62:65], v[178:181], v[202:205], v[62:65]
	v_mfma_f32_16x16x32_bf16 v[50:53], v[142:145], v[210:213], v[50:53]
	v_mfma_f32_16x16x32_bf16 v[46:49], v[178:181], v[210:213], v[46:49]
	v_mfma_f32_16x16x32_bf16 v[34:37], v[142:145], v[224:227], v[34:37]
	v_mfma_f32_16x16x32_bf16 v[30:33], v[178:181], v[224:227], v[30:33]
	v_mfma_f32_16x16x32_bf16 v[18:21], v[142:145], v[232:235], v[18:21]
	v_mfma_f32_16x16x32_bf16 v[14:17], v[178:181], v[232:235], v[14:17]
	v_mfma_f32_16x16x32_bf16 v[58:61], v[182:185], v[198:201], v[58:61]
	v_mfma_f32_16x16x32_bf16 v[54:57], v[190:193], v[198:201], v[54:57]
	v_mfma_f32_16x16x32_bf16 v[42:45], v[182:185], v[206:209], v[42:45]
	v_mfma_f32_16x16x32_bf16 v[38:41], v[190:193], v[206:209], v[38:41]
	v_mfma_f32_16x16x32_bf16 v[26:29], v[182:185], v[220:223], v[26:29]
	v_mfma_f32_16x16x32_bf16 v[22:25], v[190:193], v[220:223], v[22:25]
	v_mfma_f32_16x16x32_bf16 v[10:13], v[182:185], v[228:231], v[10:13]
	v_mfma_f32_16x16x32_bf16 v[6:9], v[190:193], v[228:231], v[6:9]
	v_mfma_f32_16x16x32_bf16 v[58:61], v[186:189], v[202:205], v[58:61]
	v_mfma_f32_16x16x32_bf16 v[54:57], v[194:197], v[202:205], v[54:57]
	v_mfma_f32_16x16x32_bf16 v[42:45], v[186:189], v[210:213], v[42:45]
	v_mfma_f32_16x16x32_bf16 v[38:41], v[194:197], v[210:213], v[38:41]
	v_mfma_f32_16x16x32_bf16 v[26:29], v[186:189], v[224:227], v[26:29]
	v_mfma_f32_16x16x32_bf16 v[22:25], v[194:197], v[224:227], v[22:25]
	v_mfma_f32_16x16x32_bf16 v[10:13], v[186:189], v[232:235], v[10:13]
	v_mfma_f32_16x16x32_bf16 v[6:9], v[194:197], v[232:235], v[6:9]
	s_setprio 0
	s_barrier
	s_add_i32 s11, 0, 0x18000
	s_add_i32 s31, 0, 0x1c000
	v_add_u32_e32 v178, s11, v216
	v_add_u32_e32 v194, s31, v216
	ds_read_b128 v[138:141], v178
	ds_read_b128 v[142:145], v178 offset:1024
	ds_read_b128 v[146:149], v178 offset:2048
	ds_read_b128 v[178:181], v178 offset:3072
	ds_read_b128 v[182:185], v194
	ds_read_b128 v[186:189], v194 offset:1024
	ds_read_b128 v[190:193], v194 offset:2048
	ds_read_b128 v[194:197], v194 offset:3072
	v_lshl_add_u64 v[214:215], v[214:215], 0, s[12:13]
	s_mov_b32 m0, s36
	v_lshl_add_u64 v[248:249], v[214:215], 0, v[154:155]
	ds_read_b128 v[198:201], v218 offset:32768
	ds_read_b128 v[202:205], v218 offset:33792
	ds_read_b128 v[206:209], v218 offset:34816
	ds_read_b128 v[210:213], v218 offset:35840
	ds_read_b128 v[220:223], v218 offset:36864
	ds_read_b128 v[224:227], v218 offset:37888
	ds_read_b128 v[228:231], v218 offset:38912
	ds_read_b128 v[232:235], v218 offset:39936
	global_load_lds_dwordx4 v[248:249], off
	s_mov_b32 m0, s37
	v_lshl_add_u64 v[214:215], v[214:215], 0, v[160:161]
	global_load_lds_dwordx4 v[214:215], off
	s_waitcnt vmcnt(8) lgkmcnt(0)
	s_setprio 1
	s_barrier
; #define PG8_STAGE(bufoff, gbase, voff) do { _Pragma("unroll") for (int _i = 0; _i < 2; ++_i) \
;         __builtin_amdgcn_global_load_lds((const unsigned*)((const char*)(gbase) + (voff)[_i]), (PG8_LAS unsigned*)(lds + (bufoff) + ldsw + _i * 8192), 16, 0, 0); } while (0)
; #define PG8_LDA(dst, b, h) do { _Pragma("unroll") for (int m = 0; m < 4; ++m) _Pragma("unroll") for (int k = 0; k < 2; ++k) dst[m][k] = *(const PG8_LAS bf16x8*)(lds + PG8_SA(b, h) + aoff + m * 2048 + k * 1024); } while (0)
; #define PG8_MMA(ai, bj, At, Bt) do { __builtin_amdgcn_s_setprio(1); _Pragma("unroll") for (int m = 0; m < 4; ++m) _Pragma("unroll") for (int n = 0; n < 2; ++n) _Pragma("unroll") for (int k = 0; k < 2; ++k) \
;         acc[ai][bj][m][n] = __builtin_amdgcn_mfma_f32_16x16x32_bf16(Bt[n][k], At[m][k], acc[ai][bj][m][n], 0, 0, 0); __builtin_amdgcn_s_setprio(0); } while (0)
; #define PG8_WAIT_V(n) asm volatile("s_waitcnt vmcnt(" #n ")" ::: "memory")
; #define PG8_WAIT_L(n) asm volatile("s_waitcnt lgkmcnt(" #n ")" ::: "memory")
; #define PG8_BAR __builtin_amdgcn_s_barrier()
; #define PG8_SCHED __builtin_amdgcn_sched_barrier(0)
; template <class Epi, class Sched, bool ALIGN_EPI = false, bool SP2 = false>
; __device__ __forceinline__ void gemm_phase(PG8_LAS unsigned char* lds, const Gemm g, const Sched& S, const Epi& E) {
;     ...
;         for (int t = 0; t < nt; t += 2) {
;     ...
;             PG8_WAIT_V(8); PG8_WAIT_L(0); PG8_BAR; PG8_MMA(0, 0, At, B0); PG8_MMA(0, 1, At, B1); PG8_BAR; PG8_SCHED;
;             PG8_LDA(At, 1, 1); PG8_STAGE(PG8_SB(1, 0), b3, voffB); PG8_STAGE(PG8_SB(1, 1), b3 + hstep, voffB); PG8_STAGE(PG8_SA(1, 0), a3, voffA);
;             PG8_WAIT_V(8); PG8_WAIT_L(0); PG8_BAR; PG8_MMA(1, 0, At, B0); PG8_MMA(1, 1, At, B1); PG8_BAR; PG8_SCHED;
	v_mfma_f32_16x16x32_bf16 v[130:133], v[138:141], v[198:201], v[130:133]
	v_mfma_f32_16x16x32_bf16 v[126:129], v[146:149], v[198:201], v[126:129]
	v_mfma_f32_16x16x32_bf16 v[114:117], v[138:141], v[206:209], v[114:117]
	v_mfma_f32_16x16x32_bf16 v[110:113], v[146:149], v[206:209], v[110:113]
	v_mfma_f32_16x16x32_bf16 v[98:101], v[138:141], v[220:223], v[98:101]
	v_mfma_f32_16x16x32_bf16 v[94:97], v[146:149], v[220:223], v[94:97]
	v_mfma_f32_16x16x32_bf16 v[82:85], v[138:141], v[228:231], v[82:85]
	v_mfma_f32_16x16x32_bf16 v[78:81], v[146:149], v[228:231], v[78:81]
	v_mfma_f32_16x16x32_bf16 v[130:133], v[142:145], v[202:205], v[130:133]
	v_mfma_f32_16x16x32_bf16 v[126:129], v[178:181], v[202:205], v[126:129]
	v_mfma_f32_16x16x32_bf16 v[114:117], v[142:145], v[210:213], v[114:117]
	v_mfma_f32_16x16x32_bf16 v[110:113], v[178:181], v[210:213], v[110:113]
	v_mfma_f32_16x16x32_bf16 v[98:101], v[142:145], v[224:227], v[98:101]
	v_mfma_f32_16x16x32_bf16 v[94:97], v[178:181], v[224:227], v[94:97]
	v_mfma_f32_16x16x32_bf16 v[82:85], v[142:145], v[232:235], v[82:85]
	v_mfma_f32_16x16x32_bf16 v[78:81], v[178:181], v[232:235], v[78:81]
	v_mfma_f32_16x16x32_bf16 v[122:125], v[182:185], v[198:201], v[122:125]
	v_mfma_f32_16x16x32_bf16 v[118:121], v[190:193], v[198:201], v[118:121]
	v_mfma_f32_16x16x32_bf16 v[106:109], v[182:185], v[206:209], v[106:109]
	v_mfma_f32_16x16x32_bf16 v[102:105], v[190:193], v[206:209], v[102:105]
	v_mfma_f32_16x16x32_bf16 v[90:93], v[182:185], v[220:223], v[90:93]
	v_mfma_f32_16x16x32_bf16 v[86:89], v[190:193], v[220:223], v[86:89]
	v_mfma_f32_16x16x32_bf16 v[74:77], v[182:185], v[228:231], v[74:77]
	v_mfma_f32_16x16x32_bf16 v[70:73], v[190:193], v[228:231], v[70:73]
	v_mfma_f32_16x16x32_bf16 v[122:125], v[186:189], v[202:205], v[122:125]
	v_mfma_f32_16x16x32_bf16 v[118:121], v[194:197], v[202:205], v[118:121]
	v_mfma_f32_16x16x32_bf16 v[106:109], v[186:189], v[210:213], v[106:109]
	v_mfma_f32_16x16x32_bf16 v[102:105], v[194:197], v[210:213], v[102:105]
	v_mfma_f32_16x16x32_bf16 v[90:93], v[186:189], v[224:227], v[90:93]
	v_mfma_f32_16x16x32_bf16 v[86:89], v[194:197], v[224:227], v[86:89]
	v_mfma_f32_16x16x32_bf16 v[74:77], v[186:189], v[232:235], v[74:77]
	v_mfma_f32_16x16x32_bf16 v[70:73], v[194:197], v[232:235], v[70:73]
	s_setprio 0
	s_barrier
	s_add_i32 s11, s11, s29
	s_add_i32 m0, s11, 0xffffff80
	ds_read_b128 v[198:201], v218 offset:49152
	ds_read_b128 v[202:205], v218 offset:50176
	ds_read_b128 v[206:209], v218 offset:51200
	ds_read_b128 v[210:213], v218 offset:52224
	global_load_lds_dwordx4 v[238:239], off offset:128
	s_add_i32 m0, s11, 0x1f80
	s_add_i32 s11, s31, s29
	global_load_lds_dwordx4 v[240:241], off offset:128
	s_add_i32 m0, s11, 0xffffff80
	ds_read_b128 v[232:235], v218 offset:56320
	global_load_lds_dwordx4 v[242:243], off offset:128
	s_add_i32 m0, s11, 0x1f80
	ds_read_b128 v[228:231], v218 offset:55296
	global_load_lds_dwordx4 v[236:237], off offset:128
	s_add_i32 m0, s41, 0xffffff80
	ds_read_b128 v[224:227], v218 offset:54272
	global_load_lds_dwordx4 v[244:245], off offset:128
	s_add_i32 m0, s46, 0xffffff80
	ds_read_b128 v[220:223], v218 offset:53248
	global_load_lds_dwordx4 v[246:247], off offset:128
	s_waitcnt vmcnt(8) lgkmcnt(0)
	s_setprio 1
	s_barrier
	v_mfma_f32_16x16x32_bf16 v[66:69], v[138:141], v[198:201], v[66:69]
	v_mfma_f32_16x16x32_bf16 v[62:65], v[146:149], v[198:201], v[62:65]
	v_mfma_f32_16x16x32_bf16 v[50:53], v[138:141], v[206:209], v[50:53]
	v_mfma_f32_16x16x32_bf16 v[46:49], v[146:149], v[206:209], v[46:49]
	v_mfma_f32_16x16x32_bf16 v[34:37], v[138:141], v[220:223], v[34:37]
	v_mfma_f32_16x16x32_bf16 v[30:33], v[146:149], v[220:223], v[30:33]
	v_mfma_f32_16x16x32_bf16 v[18:21], v[138:141], v[228:231], v[18:21]
	v_mfma_f32_16x16x32_bf16 v[14:17], v[146:149], v[228:231], v[14:17]
	v_mfma_f32_16x16x32_bf16 v[66:69], v[142:145], v[202:205], v[66:69]
	v_mfma_f32_16x16x32_bf16 v[62:65], v[178:181], v[202:205], v[62:65]
	v_mfma_f32_16x16x32_bf16 v[50:53], v[142:145], v[210:213], v[50:53]
	v_mfma_f32_16x16x32_bf16 v[46:49], v[178:181], v[210:213], v[46:49]
	v_mfma_f32_16x16x32_bf16 v[34:37], v[142:145], v[224:227], v[34:37]
	v_mfma_f32_16x16x32_bf16 v[30:33], v[178:181], v[224:227], v[30:33]
	v_mfma_f32_16x16x32_bf16 v[18:21], v[142:145], v[232:235], v[18:21]
	v_mfma_f32_16x16x32_bf16 v[14:17], v[178:181], v[232:235], v[14:17]
	v_mfma_f32_16x16x32_bf16 v[58:61], v[182:185], v[198:201], v[58:61]
	v_mfma_f32_16x16x32_bf16 v[54:57], v[190:193], v[198:201], v[54:57]
	v_mfma_f32_16x16x32_bf16 v[42:45], v[182:185], v[206:209], v[42:45]
	v_mfma_f32_16x16x32_bf16 v[38:41], v[190:193], v[206:209], v[38:41]
	v_mfma_f32_16x16x32_bf16 v[26:29], v[182:185], v[220:223], v[26:29]
	v_mfma_f32_16x16x32_bf16 v[22:25], v[190:193], v[220:223], v[22:25]
	v_mfma_f32_16x16x32_bf16 v[10:13], v[182:185], v[228:231], v[10:13]
	v_mfma_f32_16x16x32_bf16 v[6:9], v[190:193], v[228:231], v[6:9]
	v_mfma_f32_16x16x32_bf16 v[58:61], v[186:189], v[202:205], v[58:61]
	v_mfma_f32_16x16x32_bf16 v[54:57], v[194:197], v[202:205], v[54:57]
	v_mfma_f32_16x16x32_bf16 v[42:45], v[186:189], v[210:213], v[42:45]
	v_mfma_f32_16x16x32_bf16 v[38:41], v[194:197], v[210:213], v[38:41]
	v_mfma_f32_16x16x32_bf16 v[26:29], v[186:189], v[224:227], v[26:29]
	v_mfma_f32_16x16x32_bf16 v[22:25], v[194:197], v[224:227], v[22:25]
	v_mfma_f32_16x16x32_bf16 v[10:13], v[186:189], v[232:235], v[10:13]
	v_mfma_f32_16x16x32_bf16 v[6:9], v[194:197], v[232:235], v[6:9]
	s_setprio 0
	s_barrier
	v_lshl_add_u64 v[134:135], v[134:135], 0, s[26:27]
	s_cmp_ge_i32 s10, s48
	v_lshl_add_u64 v[136:137], v[136:137], 0, s[26:27]
	s_cbranch_scc0 .LBB0_1192

; #define PG8_STAGE(bufoff, gbase, voff) do { _Pragma("unroll") for (int _i = 0; _i < 2; ++_i) \
;         __builtin_amdgcn_global_load_lds((const unsigned*)((const char*)(gbase) + (voff)[_i]), (PG8_LAS unsigned*)(lds + (bufoff) + ldsw + _i * 8192), 16, 0, 0); } while (0)
; #define PG8_LDA(dst, b, h) do { _Pragma("unroll") for (int m = 0; m < 4; ++m) _Pragma("unroll") for (int k = 0; k < 2; ++k) dst[m][k] = *(const PG8_LAS bf16x8*)(lds + PG8_SA(b, h) + aoff + m * 2048 + k * 1024); } while (0)
; #define PG8_LDB(dst, b, h) do { _Pragma("unroll") for (int n = 0; n < 2; ++n) _Pragma("unroll") for (int k = 0; k < 2; ++k) dst[n][k] = *(const PG8_LAS bf16x8*)(lds + PG8_SB(b, h) + boff + n * 2048 + k * 1024); } while (0)
; #define PG8_MMA(ai, bj, At, Bt) do { __builtin_amdgcn_s_setprio(1); _Pragma("unroll") for (int m = 0; m < 4; ++m) _Pragma("unroll") for (int n = 0; n < 2; ++n) _Pragma("unroll") for (int k = 0; k < 2; ++k) \
;         acc[ai][bj][m][n] = __builtin_amdgcn_mfma_f32_16x16x32_bf16(Bt[n][k], At[m][k], acc[ai][bj][m][n], 0, 0, 0); __builtin_amdgcn_s_setprio(0); } while (0)
; #define PG8_BAR __builtin_amdgcn_s_barrier()
; template <class Epi, class Sched, bool ALIGN_EPI = false, bool SP2 = false>
; __device__ __forceinline__ void gemm_phase(PG8_LAS unsigned char* lds, const Gemm g, const Sched& S, const Epi& E) {
;     ...
;         const bool has_next = S.next(ui + 1, nxt);
;         const char* nA = has_next ? (const char*)g.A + (size_t)nxt.pm * tstep : cA; const char* nB = has_next ? (const char*)g.Bt + (size_t)nxt.pn * tstep : cB;
;         for (int t = 0; t < nt; t += 2) {
;             const bool last = (t == nt - 2);
;             const char* a1 = cA + (size_t)(t + 1) * kstep;
;             const char* a2 = last ? nA : cA + (size_t)(t + 2) * kstep; const char* b2 = last ? nB : cB + (size_t)(t + 2) * kstep;
;             const char* a3 = a2 + kstep; const char* b3 = b2 + kstep;
;             if (last && has_next) S.a_ready(nxt);
;             if constexpr (SP2) {
;             PG8_LDB(B0, 0, 0); PG8_LDB(B1, 0, 1); PG8_SCHED; PG8_LDA(At, 0, 0); PG8_STAGE(PG8_SA(1, 1), a1 + hstep, voffA);
;             PG8_WAIT_V(8); PG8_WAIT_L(0); PG8_BAR; PG8_MMA(0, 0, At, B0); PG8_MMA(0, 1, At, B1); PG8_BAR; PG8_SCHED;
;             PG8_LDA(At, 0, 1); PG8_STAGE(PG8_SB(0, 0), b2, voffB); PG8_STAGE(PG8_SB(0, 1), b2 + hstep, voffB); PG8_STAGE(PG8_SA(0, 0), a2, voffA);
.LBB0_1340:
	v_add_u32_e32 v148, s55, v201
	v_add_u32_e32 v190, s56, v201
	ds_read_b128 v[136:139], v148
	ds_read_b128 v[140:143], v148 offset:1024
	ds_read_b128 v[144:147], v148 offset:2048
	ds_read_b128 v[148:151], v148 offset:3072
	ds_read_b128 v[152:155], v190
	ds_read_b128 v[182:185], v190 offset:1024
	ds_read_b128 v[186:189], v190 offset:2048
	ds_read_b128 v[190:193], v190 offset:3072
	s_cmp_eq_u32 s48, s12
	v_lshl_add_u64 v[194:195], v[134:135], 0, s[22:23]
	s_cselect_b64 vcc, -1, 0
	s_add_i32 s12, s12, 2
	v_cndmask_b32_e32 v199, v195, v179, vcc
	v_cndmask_b32_e32 v198, v194, v178, vcc
	v_cndmask_b32_e32 v215, v133, v181, vcc
	v_cndmask_b32_e32 v214, v132, v180, vcc
	s_mov_b32 m0, s57
	v_lshl_add_u64 v[236:237], v[134:135], 0, v[174:175]
	ds_read_b128 v[194:197], v203
	ds_read_b128 v[206:209], v203 offset:1024
	ds_read_b128 v[210:213], v203 offset:2048
	ds_read_b128 v[216:219], v203 offset:3072
	ds_read_b128 v[220:223], v203 offset:4096
	ds_read_b128 v[224:227], v203 offset:5120
	ds_read_b128 v[228:231], v203 offset:6144
	ds_read_b128 v[232:235], v203 offset:7168
	global_load_lds_dwordx4 v[236:237], off
	s_mov_b32 m0, s58
	v_lshl_add_u64 v[236:237], v[134:135], 0, v[172:173]
	global_load_lds_dwordx4 v[236:237], off
	s_waitcnt vmcnt(8) lgkmcnt(0)
	s_setprio 1
	s_barrier
	v_mfma_f32_16x16x32_bf16 v[124:127], v[136:139], v[194:197], v[124:127]
	v_mfma_f32_16x16x32_bf16 v[128:131], v[144:147], v[194:197], v[128:131]
	v_mfma_f32_16x16x32_bf16 v[112:115], v[136:139], v[210:213], v[112:115]
	v_mfma_f32_16x16x32_bf16 v[108:111], v[144:147], v[210:213], v[108:111]
	v_mfma_f32_16x16x32_bf16 v[96:99], v[136:139], v[220:223], v[96:99]
	v_mfma_f32_16x16x32_bf16 v[92:95], v[144:147], v[220:223], v[92:95]
	v_mfma_f32_16x16x32_bf16 v[80:83], v[136:139], v[228:231], v[80:83]
	v_mfma_f32_16x16x32_bf16 v[76:79], v[144:147], v[228:231], v[76:79]
	v_mfma_f32_16x16x32_bf16 v[124:127], v[140:143], v[206:209], v[124:127]
	v_mfma_f32_16x16x32_bf16 v[128:131], v[148:151], v[206:209], v[128:131]
	v_mfma_f32_16x16x32_bf16 v[112:115], v[140:143], v[216:219], v[112:115]
	v_mfma_f32_16x16x32_bf16 v[108:111], v[148:151], v[216:219], v[108:111]
	v_mfma_f32_16x16x32_bf16 v[96:99], v[140:143], v[224:227], v[96:99]
	v_mfma_f32_16x16x32_bf16 v[92:95], v[148:151], v[224:227], v[92:95]
	v_mfma_f32_16x16x32_bf16 v[80:83], v[140:143], v[232:235], v[80:83]
	v_mfma_f32_16x16x32_bf16 v[76:79], v[148:151], v[232:235], v[76:79]
	v_mfma_f32_16x16x32_bf16 v[120:123], v[152:155], v[194:197], v[120:123]
	v_mfma_f32_16x16x32_bf16 v[116:119], v[186:189], v[194:197], v[116:119]
	v_mfma_f32_16x16x32_bf16 v[104:107], v[152:155], v[210:213], v[104:107]
	v_mfma_f32_16x16x32_bf16 v[100:103], v[186:189], v[210:213], v[100:103]
	v_mfma_f32_16x16x32_bf16 v[88:91], v[152:155], v[220:223], v[88:91]
	v_mfma_f32_16x16x32_bf16 v[84:87], v[186:189], v[220:223], v[84:87]
	v_mfma_f32_16x16x32_bf16 v[72:75], v[152:155], v[228:231], v[72:75]
	v_mfma_f32_16x16x32_bf16 v[68:71], v[186:189], v[228:231], v[68:71]
	v_mfma_f32_16x16x32_bf16 v[120:123], v[182:185], v[206:209], v[120:123]
	v_mfma_f32_16x16x32_bf16 v[116:119], v[190:193], v[206:209], v[116:119]
	v_mfma_f32_16x16x32_bf16 v[104:107], v[182:185], v[216:219], v[104:107]
	v_mfma_f32_16x16x32_bf16 v[100:103], v[190:193], v[216:219], v[100:103]
	v_mfma_f32_16x16x32_bf16 v[88:91], v[182:185], v[224:227], v[88:91]
	v_mfma_f32_16x16x32_bf16 v[84:87], v[190:193], v[224:227], v[84:87]
	v_mfma_f32_16x16x32_bf16 v[72:75], v[182:185], v[232:235], v[72:75]
	v_mfma_f32_16x16x32_bf16 v[68:71], v[190:193], v[232:235], v[68:71]
	s_setprio 0
	s_barrier
	s_mov_b32 m0, s59
	v_lshl_add_u64 v[236:237], v[214:215], 0, v[166:167]
	ds_read_b128 v[194:197], v203 offset:16384
	ds_read_b128 v[206:209], v203 offset:17408
	ds_read_b128 v[210:213], v203 offset:18432
	ds_read_b128 v[216:219], v203 offset:19456
	ds_read_b128 v[220:223], v203 offset:20480
	ds_read_b128 v[224:227], v203 offset:21504
	ds_read_b128 v[228:231], v203 offset:22528
	ds_read_b128 v[232:235], v203 offset:23552
	global_load_lds_dwordx4 v[236:237], off
	v_lshl_add_u64 v[238:239], v[214:215], 0, v[170:171]
	s_mov_b32 m0, s60
	v_lshl_add_u64 v[214:215], v[214:215], 0, s[14:15]
	s_add_i32 s13, s56, s30
	global_load_lds_dwordx4 v[238:239], off
	v_lshl_add_u64 v[240:241], v[214:215], 0, v[166:167]
	s_mov_b32 m0, s13
	v_lshl_add_u64 v[214:215], v[214:215], 0, v[170:171]
	global_load_lds_dwordx4 v[240:241], off
	s_add_i32 m0, s13, 0x2000
	v_lshl_add_u64 v[242:243], v[198:199], 0, v[164:165]
	global_load_lds_dwordx4 v[214:215], off
	s_mov_b32 m0, s31
	v_lshl_add_u64 v[244:245], v[198:199], 0, v[168:169]
	global_load_lds_dwordx4 v[242:243], off
	s_mov_b32 m0, s34
	s_nop 0
	global_load_lds_dwordx4 v[244:245], off
	s_waitcnt vmcnt(8) lgkmcnt(0)
	s_setprio 1
	s_barrier
; #define PG8_STAGE(bufoff, gbase, voff) do { _Pragma("unroll") for (int _i = 0; _i < 2; ++_i) \
;         __builtin_amdgcn_global_load_lds((const unsigned*)((const char*)(gbase) + (voff)[_i]), (PG8_LAS unsigned*)(lds + (bufoff) + ldsw + _i * 8192), 16, 0, 0); } while (0)
; #define PG8_LDA(dst, b, h) do { _Pragma("unroll") for (int m = 0; m < 4; ++m) _Pragma("unroll") for (int k = 0; k < 2; ++k) dst[m][k] = *(const PG8_LAS bf16x8*)(lds + PG8_SA(b, h) + aoff + m * 2048 + k * 1024); } while (0)
; #define PG8_LDB(dst, b, h) do { _Pragma("unroll") for (int n = 0; n < 2; ++n) _Pragma("unroll") for (int k = 0; k < 2; ++k) dst[n][k] = *(const PG8_LAS bf16x8*)(lds + PG8_SB(b, h) + boff + n * 2048 + k * 1024); } while (0)
; #define PG8_MMA(ai, bj, At, Bt) do { __builtin_amdgcn_s_setprio(1); _Pragma("unroll") for (int m = 0; m < 4; ++m) _Pragma("unroll") for (int n = 0; n < 2; ++n) _Pragma("unroll") for (int k = 0; k < 2; ++k) \
;         acc[ai][bj][m][n] = __builtin_amdgcn_mfma_f32_16x16x32_bf16(Bt[n][k], At[m][k], acc[ai][bj][m][n], 0, 0, 0); __builtin_amdgcn_s_setprio(0); } while (0)
; #define PG8_WAIT_V(n) asm volatile("s_waitcnt vmcnt(" #n ")" ::: "memory")
; #define PG8_WAIT_L(n) asm volatile("s_waitcnt lgkmcnt(" #n ")" ::: "memory")
; #define PG8_BAR __builtin_amdgcn_s_barrier()
; #define PG8_SCHED __builtin_amdgcn_sched_barrier(0)
; template <class Epi, class Sched, bool ALIGN_EPI = false, bool SP2 = false>
; __device__ __forceinline__ void gemm_phase(PG8_LAS unsigned char* lds, const Gemm g, const Sched& S, const Epi& E) {
;     ...
;             PG8_WAIT_V(8); PG8_WAIT_L(0); PG8_BAR; PG8_MMA(1, 0, At, B0); PG8_MMA(1, 1, At, B1); PG8_BAR; PG8_SCHED;
;             PG8_LDB(B0, 1, 0); PG8_LDB(B1, 1, 1); PG8_SCHED; PG8_LDA(At, 1, 0); PG8_STAGE(PG8_SA(0, 1), a2 + hstep, voffA);
;             PG8_WAIT_V(8); PG8_WAIT_L(0); PG8_BAR; PG8_MMA(0, 0, At, B0); PG8_MMA(0, 1, At, B1); PG8_BAR; PG8_SCHED;
	v_mfma_f32_16x16x32_bf16 v[64:67], v[136:139], v[194:197], v[64:67]
	v_mfma_f32_16x16x32_bf16 v[60:63], v[144:147], v[194:197], v[60:63]
	v_mfma_f32_16x16x32_bf16 v[48:51], v[136:139], v[210:213], v[48:51]
	v_mfma_f32_16x16x32_bf16 v[44:47], v[144:147], v[210:213], v[44:47]
	v_mfma_f32_16x16x32_bf16 v[32:35], v[136:139], v[220:223], v[32:35]
	v_mfma_f32_16x16x32_bf16 v[28:31], v[144:147], v[220:223], v[28:31]
	v_mfma_f32_16x16x32_bf16 v[16:19], v[136:139], v[228:231], v[16:19]
	v_mfma_f32_16x16x32_bf16 v[12:15], v[144:147], v[228:231], v[12:15]
	v_mfma_f32_16x16x32_bf16 v[64:67], v[140:143], v[206:209], v[64:67]
	v_mfma_f32_16x16x32_bf16 v[60:63], v[148:151], v[206:209], v[60:63]
	v_mfma_f32_16x16x32_bf16 v[48:51], v[140:143], v[216:219], v[48:51]
	v_mfma_f32_16x16x32_bf16 v[44:47], v[148:151], v[216:219], v[44:47]
	v_mfma_f32_16x16x32_bf16 v[32:35], v[140:143], v[224:227], v[32:35]
	v_mfma_f32_16x16x32_bf16 v[28:31], v[148:151], v[224:227], v[28:31]
	v_mfma_f32_16x16x32_bf16 v[16:19], v[140:143], v[232:235], v[16:19]
	v_mfma_f32_16x16x32_bf16 v[12:15], v[148:151], v[232:235], v[12:15]
	v_mfma_f32_16x16x32_bf16 v[56:59], v[152:155], v[194:197], v[56:59]
	v_mfma_f32_16x16x32_bf16 v[52:55], v[186:189], v[194:197], v[52:55]
	v_mfma_f32_16x16x32_bf16 v[40:43], v[152:155], v[210:213], v[40:43]
	v_mfma_f32_16x16x32_bf16 v[36:39], v[186:189], v[210:213], v[36:39]
	v_mfma_f32_16x16x32_bf16 v[24:27], v[152:155], v[220:223], v[24:27]
	v_mfma_f32_16x16x32_bf16 v[20:23], v[186:189], v[220:223], v[20:23]
	v_mfma_f32_16x16x32_bf16 v[8:11], v[152:155], v[228:231], v[8:11]
	v_mfma_f32_16x16x32_bf16 v[4:7], v[186:189], v[228:231], v[4:7]
	v_mfma_f32_16x16x32_bf16 v[56:59], v[182:185], v[206:209], v[56:59]
	v_mfma_f32_16x16x32_bf16 v[52:55], v[190:193], v[206:209], v[52:55]
	v_mfma_f32_16x16x32_bf16 v[40:43], v[182:185], v[216:219], v[40:43]
	v_mfma_f32_16x16x32_bf16 v[36:39], v[190:193], v[216:219], v[36:39]
	v_mfma_f32_16x16x32_bf16 v[24:27], v[182:185], v[224:227], v[24:27]
	v_mfma_f32_16x16x32_bf16 v[20:23], v[190:193], v[224:227], v[20:23]
	v_mfma_f32_16x16x32_bf16 v[8:11], v[182:185], v[232:235], v[8:11]
	v_mfma_f32_16x16x32_bf16 v[4:7], v[190:193], v[232:235], v[4:7]
	s_setprio 0
	s_barrier
	s_add_i32 s13, 0, 0x18000
	s_add_i32 s29, 0, 0x1c000
	v_add_u32_e32 v148, s13, v201
	v_add_u32_e32 v190, s29, v201
	ds_read_b128 v[136:139], v148
	ds_read_b128 v[140:143], v148 offset:1024
	ds_read_b128 v[144:147], v148 offset:2048
	ds_read_b128 v[148:151], v148 offset:3072
	ds_read_b128 v[152:155], v190
	ds_read_b128 v[182:185], v190 offset:1024
	ds_read_b128 v[186:189], v190 offset:2048
	ds_read_b128 v[190:193], v190 offset:3072
	v_lshl_add_u64 v[198:199], v[198:199], 0, s[14:15]
	s_mov_b32 m0, s35
	v_lshl_add_u64 v[246:247], v[198:199], 0, v[164:165]
	ds_read_b128 v[194:197], v203 offset:32768
	ds_read_b128 v[206:209], v203 offset:33792
	ds_read_b128 v[210:213], v203 offset:34816
	ds_read_b128 v[216:219], v203 offset:35840
	ds_read_b128 v[220:223], v203 offset:36864
	ds_read_b128 v[224:227], v203 offset:37888
	ds_read_b128 v[228:231], v203 offset:38912
	ds_read_b128 v[232:235], v203 offset:39936
	global_load_lds_dwordx4 v[246:247], off
	s_mov_b32 m0, s36
	v_lshl_add_u64 v[198:199], v[198:199], 0, v[168:169]
	global_load_lds_dwordx4 v[198:199], off
	s_waitcnt vmcnt(8) lgkmcnt(0)
	s_setprio 1
	s_barrier
; #define PG8_STAGE(bufoff, gbase, voff) do { _Pragma("unroll") for (int _i = 0; _i < 2; ++_i) \
;         __builtin_amdgcn_global_load_lds((const unsigned*)((const char*)(gbase) + (voff)[_i]), (PG8_LAS unsigned*)(lds + (bufoff) + ldsw + _i * 8192), 16, 0, 0); } while (0)
; #define PG8_LDA(dst, b, h) do { _Pragma("unroll") for (int m = 0; m < 4; ++m) _Pragma("unroll") for (int k = 0; k < 2; ++k) dst[m][k] = *(const PG8_LAS bf16x8*)(lds + PG8_SA(b, h) + aoff + m * 2048 + k * 1024); } while (0)
; #define PG8_MMA(ai, bj, At, Bt) do { __builtin_amdgcn_s_setprio(1); _Pragma("unroll") for (int m = 0; m < 4; ++m) _Pragma("unroll") for (int n = 0; n < 2; ++n) _Pragma("unroll") for (int k = 0; k < 2; ++k) \
;         acc[ai][bj][m][n] = __builtin_amdgcn_mfma_f32_16x16x32_bf16(Bt[n][k], At[m][k], acc[ai][bj][m][n], 0, 0, 0); __builtin_amdgcn_s_setprio(0); } while (0)
; #define PG8_WAIT_V(n) asm volatile("s_waitcnt vmcnt(" #n ")" ::: "memory")
; #define PG8_WAIT_L(n) asm volatile("s_waitcnt lgkmcnt(" #n ")" ::: "memory")
; #define PG8_BAR __builtin_amdgcn_s_barrier()
; #define PG8_SCHED __builtin_amdgcn_sched_barrier(0)
; template <class Epi, class Sched, bool ALIGN_EPI = false, bool SP2 = false>
; __device__ __forceinline__ void gemm_phase(PG8_LAS unsigned char* lds, const Gemm g, const Sched& S, const Epi& E) {
;     ...
;         for (int t = 0; t < nt; t += 2) {
;     ...
;             PG8_WAIT_V(8); PG8_WAIT_L(0); PG8_BAR; PG8_MMA(0, 0, At, B0); PG8_MMA(0, 1, At, B1); PG8_BAR; PG8_SCHED;
;             PG8_LDA(At, 1, 1); PG8_STAGE(PG8_SB(1, 0), b3, voffB); PG8_STAGE(PG8_SB(1, 1), b3 + hstep, voffB); PG8_STAGE(PG8_SA(1, 0), a3, voffA);
;             PG8_WAIT_V(8); PG8_WAIT_L(0); PG8_BAR; PG8_MMA(1, 0, At, B0); PG8_MMA(1, 1, At, B1); PG8_BAR; PG8_SCHED;
	v_mfma_f32_16x16x32_bf16 v[124:127], v[136:139], v[194:197], v[124:127]
	v_mfma_f32_16x16x32_bf16 v[128:131], v[144:147], v[194:197], v[128:131]
	v_mfma_f32_16x16x32_bf16 v[112:115], v[136:139], v[210:213], v[112:115]
	v_mfma_f32_16x16x32_bf16 v[108:111], v[144:147], v[210:213], v[108:111]
	v_mfma_f32_16x16x32_bf16 v[96:99], v[136:139], v[220:223], v[96:99]
	v_mfma_f32_16x16x32_bf16 v[92:95], v[144:147], v[220:223], v[92:95]
	v_mfma_f32_16x16x32_bf16 v[80:83], v[136:139], v[228:231], v[80:83]
	v_mfma_f32_16x16x32_bf16 v[76:79], v[144:147], v[228:231], v[76:79]
	v_mfma_f32_16x16x32_bf16 v[124:127], v[140:143], v[206:209], v[124:127]
	v_mfma_f32_16x16x32_bf16 v[128:131], v[148:151], v[206:209], v[128:131]
	v_mfma_f32_16x16x32_bf16 v[112:115], v[140:143], v[216:219], v[112:115]
	v_mfma_f32_16x16x32_bf16 v[108:111], v[148:151], v[216:219], v[108:111]
	v_mfma_f32_16x16x32_bf16 v[96:99], v[140:143], v[224:227], v[96:99]
	v_mfma_f32_16x16x32_bf16 v[92:95], v[148:151], v[224:227], v[92:95]
	v_mfma_f32_16x16x32_bf16 v[80:83], v[140:143], v[232:235], v[80:83]
	v_mfma_f32_16x16x32_bf16 v[76:79], v[148:151], v[232:235], v[76:79]
	v_mfma_f32_16x16x32_bf16 v[120:123], v[152:155], v[194:197], v[120:123]
	v_mfma_f32_16x16x32_bf16 v[116:119], v[186:189], v[194:197], v[116:119]
	v_mfma_f32_16x16x32_bf16 v[104:107], v[152:155], v[210:213], v[104:107]
	v_mfma_f32_16x16x32_bf16 v[100:103], v[186:189], v[210:213], v[100:103]
	v_mfma_f32_16x16x32_bf16 v[88:91], v[152:155], v[220:223], v[88:91]
	v_mfma_f32_16x16x32_bf16 v[84:87], v[186:189], v[220:223], v[84:87]
	v_mfma_f32_16x16x32_bf16 v[72:75], v[152:155], v[228:231], v[72:75]
	v_mfma_f32_16x16x32_bf16 v[68:71], v[186:189], v[228:231], v[68:71]
	v_mfma_f32_16x16x32_bf16 v[120:123], v[182:185], v[206:209], v[120:123]
	v_mfma_f32_16x16x32_bf16 v[116:119], v[190:193], v[206:209], v[116:119]
	v_mfma_f32_16x16x32_bf16 v[104:107], v[182:185], v[216:219], v[104:107]
	v_mfma_f32_16x16x32_bf16 v[100:103], v[190:193], v[216:219], v[100:103]
	v_mfma_f32_16x16x32_bf16 v[88:91], v[182:185], v[224:227], v[88:91]
	v_mfma_f32_16x16x32_bf16 v[84:87], v[190:193], v[224:227], v[84:87]
	v_mfma_f32_16x16x32_bf16 v[72:75], v[182:185], v[232:235], v[72:75]
	v_mfma_f32_16x16x32_bf16 v[68:71], v[190:193], v[232:235], v[68:71]
	s_setprio 0
	s_barrier
	s_add_i32 s13, s13, s30
	s_add_i32 m0, s13, 0xffffff80
	ds_read_b128 v[194:197], v203 offset:49152
	ds_read_b128 v[206:209], v203 offset:50176
	ds_read_b128 v[210:213], v203 offset:51200
	ds_read_b128 v[216:219], v203 offset:52224
	global_load_lds_dwordx4 v[236:237], off offset:128
	s_add_i32 m0, s13, 0x1f80
	s_add_i32 s13, s29, s30
	global_load_lds_dwordx4 v[238:239], off offset:128
	s_add_i32 m0, s13, 0xffffff80
	ds_read_b128 v[232:235], v203 offset:56320
	global_load_lds_dwordx4 v[240:241], off offset:128
	s_add_i32 m0, s13, 0x1f80
	ds_read_b128 v[228:231], v203 offset:55296
	global_load_lds_dwordx4 v[214:215], off offset:128
	s_add_i32 m0, s37, 0xffffff80
	ds_read_b128 v[224:227], v203 offset:54272
	global_load_lds_dwordx4 v[242:243], off offset:128
	s_add_i32 m0, s41, 0xffffff80
	ds_read_b128 v[220:223], v203 offset:53248
	global_load_lds_dwordx4 v[244:245], off offset:128
	s_waitcnt vmcnt(8) lgkmcnt(0)
	s_setprio 1
	s_barrier
	v_mfma_f32_16x16x32_bf16 v[64:67], v[136:139], v[194:197], v[64:67]
	v_mfma_f32_16x16x32_bf16 v[60:63], v[144:147], v[194:197], v[60:63]
	v_mfma_f32_16x16x32_bf16 v[48:51], v[136:139], v[210:213], v[48:51]
	v_mfma_f32_16x16x32_bf16 v[44:47], v[144:147], v[210:213], v[44:47]
	v_mfma_f32_16x16x32_bf16 v[32:35], v[136:139], v[220:223], v[32:35]
	v_mfma_f32_16x16x32_bf16 v[28:31], v[144:147], v[220:223], v[28:31]
	v_mfma_f32_16x16x32_bf16 v[16:19], v[136:139], v[228:231], v[16:19]
	v_mfma_f32_16x16x32_bf16 v[12:15], v[144:147], v[228:231], v[12:15]
	v_mfma_f32_16x16x32_bf16 v[64:67], v[140:143], v[206:209], v[64:67]
	v_mfma_f32_16x16x32_bf16 v[60:63], v[148:151], v[206:209], v[60:63]
	v_mfma_f32_16x16x32_bf16 v[48:51], v[140:143], v[216:219], v[48:51]
	v_mfma_f32_16x16x32_bf16 v[44:47], v[148:151], v[216:219], v[44:47]
	v_mfma_f32_16x16x32_bf16 v[32:35], v[140:143], v[224:227], v[32:35]
	v_mfma_f32_16x16x32_bf16 v[28:31], v[148:151], v[224:227], v[28:31]
	v_mfma_f32_16x16x32_bf16 v[16:19], v[140:143], v[232:235], v[16:19]
	v_mfma_f32_16x16x32_bf16 v[12:15], v[148:151], v[232:235], v[12:15]
	v_mfma_f32_16x16x32_bf16 v[56:59], v[152:155], v[194:197], v[56:59]
	v_mfma_f32_16x16x32_bf16 v[52:55], v[186:189], v[194:197], v[52:55]
	v_mfma_f32_16x16x32_bf16 v[40:43], v[152:155], v[210:213], v[40:43]
	v_mfma_f32_16x16x32_bf16 v[36:39], v[186:189], v[210:213], v[36:39]
	v_mfma_f32_16x16x32_bf16 v[24:27], v[152:155], v[220:223], v[24:27]
	v_mfma_f32_16x16x32_bf16 v[20:23], v[186:189], v[220:223], v[20:23]
	v_mfma_f32_16x16x32_bf16 v[8:11], v[152:155], v[228:231], v[8:11]
	v_mfma_f32_16x16x32_bf16 v[4:7], v[186:189], v[228:231], v[4:7]
	v_mfma_f32_16x16x32_bf16 v[56:59], v[182:185], v[206:209], v[56:59]
	v_mfma_f32_16x16x32_bf16 v[52:55], v[190:193], v[206:209], v[52:55]
	v_mfma_f32_16x16x32_bf16 v[40:43], v[182:185], v[216:219], v[40:43]
	v_mfma_f32_16x16x32_bf16 v[36:39], v[190:193], v[216:219], v[36:39]
	v_mfma_f32_16x16x32_bf16 v[24:27], v[182:185], v[224:227], v[24:27]
	v_mfma_f32_16x16x32_bf16 v[20:23], v[190:193], v[224:227], v[20:23]
	v_mfma_f32_16x16x32_bf16 v[8:11], v[182:185], v[232:235], v[8:11]
	v_mfma_f32_16x16x32_bf16 v[4:7], v[190:193], v[232:235], v[4:7]
	s_setprio 0
	s_barrier
	v_lshl_add_u64 v[132:133], v[132:133], 0, s[26:27]
	s_cmp_ge_i32 s12, s47
	v_lshl_add_u64 v[134:135], v[134:135], 0, s[26:27]
	s_cbranch_scc0 .LBB0_1340

; #define PG8_STAGE(bufoff, gbase, voff) do { _Pragma("unroll") for (int _i = 0; _i < 2; ++_i) \
;         __builtin_amdgcn_global_load_lds((const unsigned*)((const char*)(gbase) + (voff)[_i]), (PG8_LAS unsigned*)(lds + (bufoff) + ldsw + _i * 8192), 16, 0, 0); } while (0)
; #define PG8_LDA(dst, b, h) do { _Pragma("unroll") for (int m = 0; m < 4; ++m) _Pragma("unroll") for (int k = 0; k < 2; ++k) dst[m][k] = *(const PG8_LAS bf16x8*)(lds + PG8_SA(b, h) + aoff + m * 2048 + k * 1024); } while (0)
; #define PG8_MMA(ai, bj, At, Bt) do { __builtin_amdgcn_s_setprio(1); _Pragma("unroll") for (int m = 0; m < 4; ++m) _Pragma("unroll") for (int n = 0; n < 2; ++n) _Pragma("unroll") for (int k = 0; k < 2; ++k) \
;         acc[ai][bj][m][n] = __builtin_amdgcn_mfma_f32_16x16x32_bf16(Bt[n][k], At[m][k], acc[ai][bj][m][n], 0, 0, 0); __builtin_amdgcn_s_setprio(0); } while (0)
; #define PG8_WAIT_V(n) asm volatile("s_waitcnt vmcnt(" #n ")" ::: "memory")
; #define PG8_WAIT_L(n) asm volatile("s_waitcnt lgkmcnt(" #n ")" ::: "memory")
; #define PG8_BAR __builtin_amdgcn_s_barrier()
; #define PG8_SCHED __builtin_amdgcn_sched_barrier(0)
; template <class Epi, class Sched, bool ALIGN_EPI = false, bool SP2 = false>
; __device__ __forceinline__ void gemm_phase(PG8_LAS unsigned char* lds, const Gemm g, const Sched& S, const Epi& E) {
;     ...
;             PG8_WAIT_V(8); PG8_WAIT_L(0); PG8_BAR; PG8_MMA(0, 0, At, B0); PG8_MMA(0, 1, At, B1); PG8_BAR; PG8_SCHED;
;             PG8_LDA(At, 1, 1); PG8_STAGE(PG8_SB(1, 0), b3, voffB); PG8_STAGE(PG8_SB(1, 1), b3 + hstep, voffB); PG8_STAGE(PG8_SA(1, 0), a3, voffA);
;             PG8_WAIT_V(8); PG8_WAIT_L(0); PG8_BAR; PG8_MMA(1, 0, At, B0); PG8_MMA(1, 1, At, B1); PG8_BAR; PG8_SCHED;
.Lio_skipk2:
	s_setprio 0
	s_barrier
	s_add_i32 s11, s11, s41
	s_add_i32 m0, s11, 0xffffff80
	ds_read_b128 v[198:201], v213 offset:49152
	ds_read_b128 v[202:205], v213 offset:50176
	ds_read_b128 v[206:209], v213 offset:51200
	ds_read_b128 v[220:223], v213 offset:52224
	global_load_lds_dwordx4 v[240:241], off offset:128
	s_add_i32 m0, s11, 0x1f80
	s_add_i32 s11, s13, s41
	global_load_lds_dwordx4 v[242:243], off offset:128
	s_add_i32 m0, s11, 0xffffff80
	ds_read_b128 v[236:239], v213 offset:56320
	global_load_lds_dwordx4 v[244:245], off offset:128
	s_add_i32 m0, s11, 0x1f80
	ds_read_b128 v[232:235], v213 offset:55296
	global_load_lds_dwordx4 v[214:215], off offset:128
	s_add_i32 m0, s69, 0xffffff80
	ds_read_b128 v[228:231], v213 offset:54272
	global_load_lds_dwordx4 v[246:247], off offset:128
	s_add_i32 m0, s70, 0xffffff80
	ds_read_b128 v[224:227], v213 offset:53248
	global_load_lds_dwordx4 v[248:249], off offset:128
	s_waitcnt vmcnt(8) lgkmcnt(0)
	s_setprio 1
	s_barrier
	v_mfma_f32_16x16x32_bf16 v[60:63], v[132:135], v[198:201], v[60:63]
	v_mfma_f32_16x16x32_bf16 v[56:59], v[174:177], v[198:201], v[56:59]
	v_mfma_f32_16x16x32_bf16 v[44:47], v[132:135], v[206:209], v[44:47]
	v_mfma_f32_16x16x32_bf16 v[40:43], v[174:177], v[206:209], v[40:43]
	v_mfma_f32_16x16x32_bf16 v[28:31], v[132:135], v[224:227], v[28:31]
	v_mfma_f32_16x16x32_bf16 v[24:27], v[174:177], v[224:227], v[24:27]
	v_mfma_f32_16x16x32_bf16 v[12:15], v[132:135], v[232:235], v[12:15]
	v_mfma_f32_16x16x32_bf16 v[8:11], v[174:177], v[232:235], v[8:11]
	v_mfma_f32_16x16x32_bf16 v[60:63], v[136:139], v[202:205], v[60:63]
	v_mfma_f32_16x16x32_bf16 v[56:59], v[178:181], v[202:205], v[56:59]
	v_mfma_f32_16x16x32_bf16 v[44:47], v[136:139], v[220:223], v[44:47]
	v_mfma_f32_16x16x32_bf16 v[40:43], v[178:181], v[220:223], v[40:43]
	v_mfma_f32_16x16x32_bf16 v[28:31], v[136:139], v[228:231], v[28:31]
	v_mfma_f32_16x16x32_bf16 v[24:27], v[178:181], v[228:231], v[24:27]
	v_mfma_f32_16x16x32_bf16 v[12:15], v[136:139], v[236:239], v[12:15]
	v_mfma_f32_16x16x32_bf16 v[8:11], v[178:181], v[236:239], v[8:11]
	s_cmp_eq_u32 s22, 12
	s_cbranch_scc1 .Lio_skipk3
	v_mfma_f32_16x16x32_bf16 v[52:55], v[182:185], v[198:201], v[52:55]
	v_mfma_f32_16x16x32_bf16 v[48:51], v[190:193], v[198:201], v[48:51]
	v_mfma_f32_16x16x32_bf16 v[36:39], v[182:185], v[206:209], v[36:39]
	v_mfma_f32_16x16x32_bf16 v[32:35], v[190:193], v[206:209], v[32:35]
	v_mfma_f32_16x16x32_bf16 v[20:23], v[182:185], v[224:227], v[20:23]
	v_mfma_f32_16x16x32_bf16 v[16:19], v[190:193], v[224:227], v[16:19]
	v_mfma_f32_16x16x32_bf16 v[4:7], v[182:185], v[232:235], v[4:7]
	v_mfma_f32_16x16x32_bf16 v[0:3], v[190:193], v[232:235], v[0:3]
	v_mfma_f32_16x16x32_bf16 v[52:55], v[186:189], v[202:205], v[52:55]
	v_mfma_f32_16x16x32_bf16 v[48:51], v[194:197], v[202:205], v[48:51]
	v_mfma_f32_16x16x32_bf16 v[36:39], v[186:189], v[220:223], v[36:39]
	v_mfma_f32_16x16x32_bf16 v[32:35], v[194:197], v[220:223], v[32:35]
	v_mfma_f32_16x16x32_bf16 v[20:23], v[186:189], v[228:231], v[20:23]
	v_mfma_f32_16x16x32_bf16 v[16:19], v[194:197], v[228:231], v[16:19]
	v_mfma_f32_16x16x32_bf16 v[4:7], v[186:189], v[236:239], v[4:7]
	v_mfma_f32_16x16x32_bf16 v[0:3], v[194:197], v[236:239], v[0:3]

; #define PG8_STAGE(bufoff, gbase, voff) do { _Pragma("unroll") for (int _i = 0; _i < 2; ++_i) \
;         __builtin_amdgcn_global_load_lds((const unsigned*)((const char*)(gbase) + (voff)[_i]), (PG8_LAS unsigned*)(lds + (bufoff) + ldsw + _i * 8192), 16, 0, 0); } while (0)
; #define PG8_LDA(dst, b, h) do { _Pragma("unroll") for (int m = 0; m < 4; ++m) _Pragma("unroll") for (int k = 0; k < 2; ++k) dst[m][k] = *(const PG8_LAS bf16x8*)(lds + PG8_SA(b, h) + aoff + m * 2048 + k * 1024); } while (0)
; #define PG8_LDB(dst, b, h) do { _Pragma("unroll") for (int n = 0; n < 2; ++n) _Pragma("unroll") for (int k = 0; k < 2; ++k) dst[n][k] = *(const PG8_LAS bf16x8*)(lds + PG8_SB(b, h) + boff + n * 2048 + k * 1024); } while (0)
; #define PG8_MMA(ai, bj, At, Bt) do { __builtin_amdgcn_s_setprio(1); _Pragma("unroll") for (int m = 0; m < 4; ++m) _Pragma("unroll") for (int n = 0; n < 2; ++n) _Pragma("unroll") for (int k = 0; k < 2; ++k) \
;         acc[ai][bj][m][n] = __builtin_amdgcn_mfma_f32_16x16x32_bf16(Bt[n][k], At[m][k], acc[ai][bj][m][n], 0, 0, 0); __builtin_amdgcn_s_setprio(0); } while (0)
; #define PG8_BAR __builtin_amdgcn_s_barrier()
; template <class Epi, class Sched, bool ALIGN_EPI = false, bool SP2 = false>
; __device__ __forceinline__ void gemm_phase(PG8_LAS unsigned char* lds, const Gemm g, const Sched& S, const Epi& E) {
;     ...
;         const bool has_next = S.next(ui + 1, nxt);
;         const char* nA = has_next ? (const char*)g.A + (size_t)nxt.pm * tstep : cA; const char* nB = has_next ? (const char*)g.Bt + (size_t)nxt.pn * tstep : cB;
;         for (int t = 0; t < nt; t += 2) {
;             const bool last = (t == nt - 2);
;             const char* a1 = cA + (size_t)(t + 1) * kstep;
;             const char* a2 = last ? nA : cA + (size_t)(t + 2) * kstep; const char* b2 = last ? nB : cB + (size_t)(t + 2) * kstep;
;             const char* a3 = a2 + kstep; const char* b3 = b2 + kstep;
;             if (last && has_next) S.a_ready(nxt);
;             if constexpr (SP2) {
;             PG8_LDB(B0, 0, 0); PG8_LDB(B1, 0, 1); PG8_SCHED; PG8_LDA(At, 0, 0); PG8_STAGE(PG8_SA(1, 1), a1 + hstep, voffA);
;             PG8_WAIT_V(8); PG8_WAIT_L(0); PG8_BAR; PG8_MMA(0, 0, At, B0); PG8_MMA(0, 1, At, B1); PG8_BAR; PG8_SCHED;
;             PG8_LDA(At, 0, 1); PG8_STAGE(PG8_SB(0, 0), b2, voffB); PG8_STAGE(PG8_SB(0, 1), b2 + hstep, voffB); PG8_STAGE(PG8_SA(0, 0), a2, voffA);
.LBB0_1695:
	v_add_u32_e32 v188, s54, v199
	ds_read_b128 v[132:135], v201
	ds_read_b128 v[136:139], v201 offset:1024
	ds_read_b128 v[140:143], v201 offset:2048
	ds_read_b128 v[144:147], v201 offset:3072
	ds_read_b128 v[148:151], v188
	ds_read_b128 v[180:183], v188 offset:1024
	ds_read_b128 v[184:187], v188 offset:2048
	ds_read_b128 v[188:191], v188 offset:3072
	s_cmp_eq_u32 s48, s12
	v_lshl_add_u64 v[192:193], v[130:131], 0, s[22:23]
	s_cselect_b64 vcc, -1, 0
	s_add_i32 s12, s12, 2
	v_cndmask_b32_e32 v197, v193, v177, vcc
	v_cndmask_b32_e32 v196, v192, v176, vcc
	v_cndmask_b32_e32 v213, v129, v179, vcc
	v_cndmask_b32_e32 v212, v128, v178, vcc
	s_mov_b32 m0, s55
	v_lshl_add_u64 v[214:215], v[130:131], 0, v[172:173]
	ds_read_b128 v[192:195], v202
	ds_read_b128 v[204:207], v202 offset:1024
	ds_read_b128 v[208:211], v202 offset:2048
	ds_read_b128 v[216:219], v202 offset:3072
	ds_read_b128 v[220:223], v202 offset:4096
	ds_read_b128 v[224:227], v202 offset:5120
	ds_read_b128 v[228:231], v202 offset:6144
	ds_read_b128 v[232:235], v202 offset:7168
	global_load_lds_dwordx4 v[214:215], off
	s_mov_b32 m0, s56
	v_lshl_add_u64 v[214:215], v[130:131], 0, v[170:171]
	global_load_lds_dwordx4 v[214:215], off
	s_waitcnt vmcnt(8) lgkmcnt(0)
	s_setprio 1
	s_barrier
	v_mfma_f32_16x16x32_bf16 v[120:123], v[132:135], v[192:195], v[120:123]
	v_mfma_f32_16x16x32_bf16 v[124:127], v[140:143], v[192:195], v[124:127]
	v_mfma_f32_16x16x32_bf16 v[108:111], v[132:135], v[208:211], v[108:111]
	v_mfma_f32_16x16x32_bf16 v[104:107], v[140:143], v[208:211], v[104:107]
	v_mfma_f32_16x16x32_bf16 v[92:95], v[132:135], v[220:223], v[92:95]
	v_mfma_f32_16x16x32_bf16 v[88:91], v[140:143], v[220:223], v[88:91]
	v_mfma_f32_16x16x32_bf16 v[76:79], v[132:135], v[228:231], v[76:79]
	v_mfma_f32_16x16x32_bf16 v[72:75], v[140:143], v[228:231], v[72:75]
	v_mfma_f32_16x16x32_bf16 v[120:123], v[136:139], v[204:207], v[120:123]
	v_mfma_f32_16x16x32_bf16 v[124:127], v[144:147], v[204:207], v[124:127]
	v_mfma_f32_16x16x32_bf16 v[108:111], v[136:139], v[216:219], v[108:111]
	v_mfma_f32_16x16x32_bf16 v[104:107], v[144:147], v[216:219], v[104:107]
	v_mfma_f32_16x16x32_bf16 v[92:95], v[136:139], v[224:227], v[92:95]
	v_mfma_f32_16x16x32_bf16 v[88:91], v[144:147], v[224:227], v[88:91]
	v_mfma_f32_16x16x32_bf16 v[76:79], v[136:139], v[232:235], v[76:79]
	v_mfma_f32_16x16x32_bf16 v[72:75], v[144:147], v[232:235], v[72:75]
	v_mfma_f32_16x16x32_bf16 v[116:119], v[148:151], v[192:195], v[116:119]
	v_mfma_f32_16x16x32_bf16 v[112:115], v[184:187], v[192:195], v[112:115]
	v_mfma_f32_16x16x32_bf16 v[100:103], v[148:151], v[208:211], v[100:103]
	v_mfma_f32_16x16x32_bf16 v[96:99], v[184:187], v[208:211], v[96:99]
	v_mfma_f32_16x16x32_bf16 v[84:87], v[148:151], v[220:223], v[84:87]
	v_mfma_f32_16x16x32_bf16 v[80:83], v[184:187], v[220:223], v[80:83]
	v_mfma_f32_16x16x32_bf16 v[68:71], v[148:151], v[228:231], v[68:71]
	v_mfma_f32_16x16x32_bf16 v[64:67], v[184:187], v[228:231], v[64:67]
	v_mfma_f32_16x16x32_bf16 v[116:119], v[180:183], v[204:207], v[116:119]
	v_mfma_f32_16x16x32_bf16 v[112:115], v[188:191], v[204:207], v[112:115]
	v_mfma_f32_16x16x32_bf16 v[100:103], v[180:183], v[216:219], v[100:103]
	v_mfma_f32_16x16x32_bf16 v[96:99], v[188:191], v[216:219], v[96:99]
	v_mfma_f32_16x16x32_bf16 v[84:87], v[180:183], v[224:227], v[84:87]
	v_mfma_f32_16x16x32_bf16 v[80:83], v[188:191], v[224:227], v[80:83]
	v_mfma_f32_16x16x32_bf16 v[68:71], v[180:183], v[232:235], v[68:71]
	v_mfma_f32_16x16x32_bf16 v[64:67], v[188:191], v[232:235], v[64:67]
	s_setprio 0
	s_barrier
	s_mov_b32 m0, s57
	v_lshl_add_u64 v[214:215], v[212:213], 0, v[164:165]
	ds_read_b128 v[192:195], v202 offset:16384
	ds_read_b128 v[204:207], v202 offset:17408
	ds_read_b128 v[208:211], v202 offset:18432
	ds_read_b128 v[216:219], v202 offset:19456
	ds_read_b128 v[220:223], v202 offset:20480
	ds_read_b128 v[224:227], v202 offset:21504
	ds_read_b128 v[228:231], v202 offset:22528
	ds_read_b128 v[232:235], v202 offset:23552
	global_load_lds_dwordx4 v[214:215], off
	v_lshl_add_u64 v[236:237], v[212:213], 0, v[168:169]
	s_mov_b32 m0, s58
	v_lshl_add_u64 v[212:213], v[212:213], 0, s[14:15]
	s_add_i32 s13, s54, s30
	global_load_lds_dwordx4 v[236:237], off
	v_lshl_add_u64 v[238:239], v[212:213], 0, v[164:165]
	s_mov_b32 m0, s13
	v_lshl_add_u64 v[212:213], v[212:213], 0, v[168:169]
	global_load_lds_dwordx4 v[238:239], off
	s_add_i32 m0, s13, 0x2000
	v_lshl_add_u64 v[240:241], v[196:197], 0, v[162:163]
	global_load_lds_dwordx4 v[212:213], off
	s_mov_b32 m0, s31
	v_lshl_add_u64 v[242:243], v[196:197], 0, v[166:167]
	global_load_lds_dwordx4 v[240:241], off
	s_mov_b32 m0, s34
	s_nop 0
	global_load_lds_dwordx4 v[242:243], off
	s_waitcnt vmcnt(8) lgkmcnt(0)
	s_setprio 1
	s_barrier
; #define PG8_STAGE(bufoff, gbase, voff) do { _Pragma("unroll") for (int _i = 0; _i < 2; ++_i) \
;         __builtin_amdgcn_global_load_lds((const unsigned*)((const char*)(gbase) + (voff)[_i]), (PG8_LAS unsigned*)(lds + (bufoff) + ldsw + _i * 8192), 16, 0, 0); } while (0)
; #define PG8_LDA(dst, b, h) do { _Pragma("unroll") for (int m = 0; m < 4; ++m) _Pragma("unroll") for (int k = 0; k < 2; ++k) dst[m][k] = *(const PG8_LAS bf16x8*)(lds + PG8_SA(b, h) + aoff + m * 2048 + k * 1024); } while (0)
; #define PG8_LDB(dst, b, h) do { _Pragma("unroll") for (int n = 0; n < 2; ++n) _Pragma("unroll") for (int k = 0; k < 2; ++k) dst[n][k] = *(const PG8_LAS bf16x8*)(lds + PG8_SB(b, h) + boff + n * 2048 + k * 1024); } while (0)
; #define PG8_MMA(ai, bj, At, Bt) do { __builtin_amdgcn_s_setprio(1); _Pragma("unroll") for (int m = 0; m < 4; ++m) _Pragma("unroll") for (int n = 0; n < 2; ++n) _Pragma("unroll") for (int k = 0; k < 2; ++k) \
;         acc[ai][bj][m][n] = __builtin_amdgcn_mfma_f32_16x16x32_bf16(Bt[n][k], At[m][k], acc[ai][bj][m][n], 0, 0, 0); __builtin_amdgcn_s_setprio(0); } while (0)
; #define PG8_WAIT_V(n) asm volatile("s_waitcnt vmcnt(" #n ")" ::: "memory")
; #define PG8_WAIT_L(n) asm volatile("s_waitcnt lgkmcnt(" #n ")" ::: "memory")
; #define PG8_BAR __builtin_amdgcn_s_barrier()
; #define PG8_SCHED __builtin_amdgcn_sched_barrier(0)
; template <class Epi, class Sched, bool ALIGN_EPI = false, bool SP2 = false>
; __device__ __forceinline__ void gemm_phase(PG8_LAS unsigned char* lds, const Gemm g, const Sched& S, const Epi& E) {
;     ...
;             PG8_WAIT_V(8); PG8_WAIT_L(0); PG8_BAR; PG8_MMA(1, 0, At, B0); PG8_MMA(1, 1, At, B1); PG8_BAR; PG8_SCHED;
;             PG8_LDB(B0, 1, 0); PG8_LDB(B1, 1, 1); PG8_SCHED; PG8_LDA(At, 1, 0); PG8_STAGE(PG8_SA(0, 1), a2 + hstep, voffA);
;             PG8_WAIT_V(8); PG8_WAIT_L(0); PG8_BAR; PG8_MMA(0, 0, At, B0); PG8_MMA(0, 1, At, B1); PG8_BAR; PG8_SCHED;
	v_mfma_f32_16x16x32_bf16 v[60:63], v[132:135], v[192:195], v[60:63]
	v_mfma_f32_16x16x32_bf16 v[56:59], v[140:143], v[192:195], v[56:59]
	v_mfma_f32_16x16x32_bf16 v[44:47], v[132:135], v[208:211], v[44:47]
	v_mfma_f32_16x16x32_bf16 v[40:43], v[140:143], v[208:211], v[40:43]
	v_mfma_f32_16x16x32_bf16 v[28:31], v[132:135], v[220:223], v[28:31]
	v_mfma_f32_16x16x32_bf16 v[24:27], v[140:143], v[220:223], v[24:27]
	v_mfma_f32_16x16x32_bf16 v[12:15], v[132:135], v[228:231], v[12:15]
	v_mfma_f32_16x16x32_bf16 v[8:11], v[140:143], v[228:231], v[8:11]
	v_mfma_f32_16x16x32_bf16 v[60:63], v[136:139], v[204:207], v[60:63]
	v_mfma_f32_16x16x32_bf16 v[56:59], v[144:147], v[204:207], v[56:59]
	v_mfma_f32_16x16x32_bf16 v[44:47], v[136:139], v[216:219], v[44:47]
	v_mfma_f32_16x16x32_bf16 v[40:43], v[144:147], v[216:219], v[40:43]
	v_mfma_f32_16x16x32_bf16 v[28:31], v[136:139], v[224:227], v[28:31]
	v_mfma_f32_16x16x32_bf16 v[24:27], v[144:147], v[224:227], v[24:27]
	v_mfma_f32_16x16x32_bf16 v[12:15], v[136:139], v[232:235], v[12:15]
	v_mfma_f32_16x16x32_bf16 v[8:11], v[144:147], v[232:235], v[8:11]
	v_mfma_f32_16x16x32_bf16 v[52:55], v[148:151], v[192:195], v[52:55]
	v_mfma_f32_16x16x32_bf16 v[48:51], v[184:187], v[192:195], v[48:51]
	v_mfma_f32_16x16x32_bf16 v[36:39], v[148:151], v[208:211], v[36:39]
	v_mfma_f32_16x16x32_bf16 v[32:35], v[184:187], v[208:211], v[32:35]
	v_mfma_f32_16x16x32_bf16 v[20:23], v[148:151], v[220:223], v[20:23]
	v_mfma_f32_16x16x32_bf16 v[16:19], v[184:187], v[220:223], v[16:19]
	v_mfma_f32_16x16x32_bf16 v[4:7], v[148:151], v[228:231], v[4:7]
	v_mfma_f32_16x16x32_bf16 v[0:3], v[184:187], v[228:231], v[0:3]
	v_mfma_f32_16x16x32_bf16 v[52:55], v[180:183], v[204:207], v[52:55]
	v_mfma_f32_16x16x32_bf16 v[48:51], v[188:191], v[204:207], v[48:51]
	v_mfma_f32_16x16x32_bf16 v[36:39], v[180:183], v[216:219], v[36:39]
	v_mfma_f32_16x16x32_bf16 v[32:35], v[188:191], v[216:219], v[32:35]
	v_mfma_f32_16x16x32_bf16 v[20:23], v[180:183], v[224:227], v[20:23]
	v_mfma_f32_16x16x32_bf16 v[16:19], v[188:191], v[224:227], v[16:19]
	v_mfma_f32_16x16x32_bf16 v[4:7], v[180:183], v[232:235], v[4:7]
	v_mfma_f32_16x16x32_bf16 v[0:3], v[188:191], v[232:235], v[0:3]
	s_setprio 0
	s_barrier
	s_add_i32 s13, 0, 0x18000
	s_add_i32 s29, 0, 0x1c000
	v_add_u32_e32 v144, s13, v199
	v_add_u32_e32 v188, s29, v199
	ds_read_b128 v[132:135], v144
	ds_read_b128 v[136:139], v144 offset:1024
	ds_read_b128 v[140:143], v144 offset:2048
	ds_read_b128 v[144:147], v144 offset:3072
	ds_read_b128 v[148:151], v188
	ds_read_b128 v[180:183], v188 offset:1024
	ds_read_b128 v[184:187], v188 offset:2048
	ds_read_b128 v[188:191], v188 offset:3072
	v_lshl_add_u64 v[196:197], v[196:197], 0, s[14:15]
	s_mov_b32 m0, s35
	v_lshl_add_u64 v[244:245], v[196:197], 0, v[162:163]
	ds_read_b128 v[192:195], v202 offset:32768
	ds_read_b128 v[204:207], v202 offset:33792
	ds_read_b128 v[208:211], v202 offset:34816
	ds_read_b128 v[216:219], v202 offset:35840
	ds_read_b128 v[220:223], v202 offset:36864
	ds_read_b128 v[224:227], v202 offset:37888
	ds_read_b128 v[228:231], v202 offset:38912
	ds_read_b128 v[232:235], v202 offset:39936
	global_load_lds_dwordx4 v[244:245], off
	s_mov_b32 m0, s36
	v_lshl_add_u64 v[196:197], v[196:197], 0, v[166:167]
	global_load_lds_dwordx4 v[196:197], off
	s_waitcnt vmcnt(8) lgkmcnt(0)
	s_setprio 1
	s_barrier
; #define PG8_STAGE(bufoff, gbase, voff) do { _Pragma("unroll") for (int _i = 0; _i < 2; ++_i) \
;         __builtin_amdgcn_global_load_lds((const unsigned*)((const char*)(gbase) + (voff)[_i]), (PG8_LAS unsigned*)(lds + (bufoff) + ldsw + _i * 8192), 16, 0, 0); } while (0)
; #define PG8_LDA(dst, b, h) do { _Pragma("unroll") for (int m = 0; m < 4; ++m) _Pragma("unroll") for (int k = 0; k < 2; ++k) dst[m][k] = *(const PG8_LAS bf16x8*)(lds + PG8_SA(b, h) + aoff + m * 2048 + k * 1024); } while (0)
; #define PG8_MMA(ai, bj, At, Bt) do { __builtin_amdgcn_s_setprio(1); _Pragma("unroll") for (int m = 0; m < 4; ++m) _Pragma("unroll") for (int n = 0; n < 2; ++n) _Pragma("unroll") for (int k = 0; k < 2; ++k) \
;         acc[ai][bj][m][n] = __builtin_amdgcn_mfma_f32_16x16x32_bf16(Bt[n][k], At[m][k], acc[ai][bj][m][n], 0, 0, 0); __builtin_amdgcn_s_setprio(0); } while (0)
; #define PG8_WAIT_V(n) asm volatile("s_waitcnt vmcnt(" #n ")" ::: "memory")
; #define PG8_WAIT_L(n) asm volatile("s_waitcnt lgkmcnt(" #n ")" ::: "memory")
; #define PG8_BAR __builtin_amdgcn_s_barrier()
; #define PG8_SCHED __builtin_amdgcn_sched_barrier(0)
; template <class Epi, class Sched, bool ALIGN_EPI = false, bool SP2 = false>
; __device__ __forceinline__ void gemm_phase(PG8_LAS unsigned char* lds, const Gemm g, const Sched& S, const Epi& E) {
;     ...
;         for (int t = 0; t < nt; t += 2) {
;     ...
;             PG8_WAIT_V(8); PG8_WAIT_L(0); PG8_BAR; PG8_MMA(0, 0, At, B0); PG8_MMA(0, 1, At, B1); PG8_BAR; PG8_SCHED;
;             PG8_LDA(At, 1, 1); PG8_STAGE(PG8_SB(1, 0), b3, voffB); PG8_STAGE(PG8_SB(1, 1), b3 + hstep, voffB); PG8_STAGE(PG8_SA(1, 0), a3, voffA);
;             PG8_WAIT_V(8); PG8_WAIT_L(0); PG8_BAR; PG8_MMA(1, 0, At, B0); PG8_MMA(1, 1, At, B1); PG8_BAR; PG8_SCHED;
	v_mfma_f32_16x16x32_bf16 v[120:123], v[132:135], v[192:195], v[120:123]
	v_mfma_f32_16x16x32_bf16 v[124:127], v[140:143], v[192:195], v[124:127]
	v_mfma_f32_16x16x32_bf16 v[108:111], v[132:135], v[208:211], v[108:111]
	v_mfma_f32_16x16x32_bf16 v[104:107], v[140:143], v[208:211], v[104:107]
	v_mfma_f32_16x16x32_bf16 v[92:95], v[132:135], v[220:223], v[92:95]
	v_mfma_f32_16x16x32_bf16 v[88:91], v[140:143], v[220:223], v[88:91]
	v_mfma_f32_16x16x32_bf16 v[76:79], v[132:135], v[228:231], v[76:79]
	v_mfma_f32_16x16x32_bf16 v[72:75], v[140:143], v[228:231], v[72:75]
	v_mfma_f32_16x16x32_bf16 v[120:123], v[136:139], v[204:207], v[120:123]
	v_mfma_f32_16x16x32_bf16 v[124:127], v[144:147], v[204:207], v[124:127]
	v_mfma_f32_16x16x32_bf16 v[108:111], v[136:139], v[216:219], v[108:111]
	v_mfma_f32_16x16x32_bf16 v[104:107], v[144:147], v[216:219], v[104:107]
	v_mfma_f32_16x16x32_bf16 v[92:95], v[136:139], v[224:227], v[92:95]
	v_mfma_f32_16x16x32_bf16 v[88:91], v[144:147], v[224:227], v[88:91]
	v_mfma_f32_16x16x32_bf16 v[76:79], v[136:139], v[232:235], v[76:79]
	v_mfma_f32_16x16x32_bf16 v[72:75], v[144:147], v[232:235], v[72:75]
	v_mfma_f32_16x16x32_bf16 v[116:119], v[148:151], v[192:195], v[116:119]
	v_mfma_f32_16x16x32_bf16 v[112:115], v[184:187], v[192:195], v[112:115]
	v_mfma_f32_16x16x32_bf16 v[100:103], v[148:151], v[208:211], v[100:103]
	v_mfma_f32_16x16x32_bf16 v[96:99], v[184:187], v[208:211], v[96:99]
	v_mfma_f32_16x16x32_bf16 v[84:87], v[148:151], v[220:223], v[84:87]
	v_mfma_f32_16x16x32_bf16 v[80:83], v[184:187], v[220:223], v[80:83]
	v_mfma_f32_16x16x32_bf16 v[68:71], v[148:151], v[228:231], v[68:71]
	v_mfma_f32_16x16x32_bf16 v[64:67], v[184:187], v[228:231], v[64:67]
	v_mfma_f32_16x16x32_bf16 v[116:119], v[180:183], v[204:207], v[116:119]
	v_mfma_f32_16x16x32_bf16 v[112:115], v[188:191], v[204:207], v[112:115]
	v_mfma_f32_16x16x32_bf16 v[100:103], v[180:183], v[216:219], v[100:103]
	v_mfma_f32_16x16x32_bf16 v[96:99], v[188:191], v[216:219], v[96:99]
	v_mfma_f32_16x16x32_bf16 v[84:87], v[180:183], v[224:227], v[84:87]
	v_mfma_f32_16x16x32_bf16 v[80:83], v[188:191], v[224:227], v[80:83]
	v_mfma_f32_16x16x32_bf16 v[68:71], v[180:183], v[232:235], v[68:71]
	v_mfma_f32_16x16x32_bf16 v[64:67], v[188:191], v[232:235], v[64:67]
	s_setprio 0
	s_barrier
	s_add_i32 s13, s13, s30
	s_add_i32 m0, s13, 0xffffff80
	ds_read_b128 v[192:195], v202 offset:49152
	ds_read_b128 v[204:207], v202 offset:50176
	ds_read_b128 v[208:211], v202 offset:51200
	ds_read_b128 v[216:219], v202 offset:52224
	global_load_lds_dwordx4 v[214:215], off offset:128
	s_add_i32 m0, s13, 0x1f80
	s_add_i32 s13, s29, s30
	global_load_lds_dwordx4 v[236:237], off offset:128
	s_add_i32 m0, s13, 0xffffff80
	ds_read_b128 v[232:235], v202 offset:56320
	global_load_lds_dwordx4 v[238:239], off offset:128
	s_add_i32 m0, s13, 0x1f80
	ds_read_b128 v[228:231], v202 offset:55296
	global_load_lds_dwordx4 v[212:213], off offset:128
	s_add_i32 m0, s37, 0xffffff80
	ds_read_b128 v[224:227], v202 offset:54272
	global_load_lds_dwordx4 v[240:241], off offset:128
	s_add_i32 m0, s41, 0xffffff80
	ds_read_b128 v[220:223], v202 offset:53248
	global_load_lds_dwordx4 v[242:243], off offset:128
	s_waitcnt vmcnt(8) lgkmcnt(0)
	s_setprio 1
	s_barrier
	v_mfma_f32_16x16x32_bf16 v[60:63], v[132:135], v[192:195], v[60:63]
	v_mfma_f32_16x16x32_bf16 v[56:59], v[140:143], v[192:195], v[56:59]
	v_mfma_f32_16x16x32_bf16 v[44:47], v[132:135], v[208:211], v[44:47]
	v_mfma_f32_16x16x32_bf16 v[40:43], v[140:143], v[208:211], v[40:43]
	v_mfma_f32_16x16x32_bf16 v[28:31], v[132:135], v[220:223], v[28:31]
	v_mfma_f32_16x16x32_bf16 v[24:27], v[140:143], v[220:223], v[24:27]
	v_mfma_f32_16x16x32_bf16 v[12:15], v[132:135], v[228:231], v[12:15]
	v_mfma_f32_16x16x32_bf16 v[8:11], v[140:143], v[228:231], v[8:11]
	v_mfma_f32_16x16x32_bf16 v[60:63], v[136:139], v[204:207], v[60:63]
	v_mfma_f32_16x16x32_bf16 v[56:59], v[144:147], v[204:207], v[56:59]
	v_mfma_f32_16x16x32_bf16 v[44:47], v[136:139], v[216:219], v[44:47]
	v_mfma_f32_16x16x32_bf16 v[40:43], v[144:147], v[216:219], v[40:43]
	v_mfma_f32_16x16x32_bf16 v[28:31], v[136:139], v[224:227], v[28:31]
	v_mfma_f32_16x16x32_bf16 v[24:27], v[144:147], v[224:227], v[24:27]
	v_mfma_f32_16x16x32_bf16 v[12:15], v[136:139], v[232:235], v[12:15]
	v_mfma_f32_16x16x32_bf16 v[8:11], v[144:147], v[232:235], v[8:11]
	v_mfma_f32_16x16x32_bf16 v[52:55], v[148:151], v[192:195], v[52:55]
	v_mfma_f32_16x16x32_bf16 v[48:51], v[184:187], v[192:195], v[48:51]
	v_mfma_f32_16x16x32_bf16 v[36:39], v[148:151], v[208:211], v[36:39]
	v_mfma_f32_16x16x32_bf16 v[32:35], v[184:187], v[208:211], v[32:35]
	v_mfma_f32_16x16x32_bf16 v[20:23], v[148:151], v[220:223], v[20:23]
	v_mfma_f32_16x16x32_bf16 v[16:19], v[184:187], v[220:223], v[16:19]
	v_mfma_f32_16x16x32_bf16 v[4:7], v[148:151], v[228:231], v[4:7]
	v_mfma_f32_16x16x32_bf16 v[0:3], v[184:187], v[228:231], v[0:3]
	v_mfma_f32_16x16x32_bf16 v[52:55], v[180:183], v[204:207], v[52:55]
	v_mfma_f32_16x16x32_bf16 v[48:51], v[188:191], v[204:207], v[48:51]
	v_mfma_f32_16x16x32_bf16 v[36:39], v[180:183], v[216:219], v[36:39]
	v_mfma_f32_16x16x32_bf16 v[32:35], v[188:191], v[216:219], v[32:35]
	v_mfma_f32_16x16x32_bf16 v[20:23], v[180:183], v[224:227], v[20:23]
	v_mfma_f32_16x16x32_bf16 v[16:19], v[188:191], v[224:227], v[16:19]
	v_mfma_f32_16x16x32_bf16 v[4:7], v[180:183], v[232:235], v[4:7]
	v_mfma_f32_16x16x32_bf16 v[0:3], v[188:191], v[232:235], v[0:3]
	s_setprio 0
	s_barrier
	v_lshl_add_u64 v[128:129], v[128:129], 0, s[26:27]
	s_cmp_ge_i32 s12, s47
	v_lshl_add_u64 v[130:131], v[130:131], 0, s[26:27]
	s_cbranch_scc0 .LBB0_1695

; #define PG8_STAGE(bufoff, gbase, voff) do { _Pragma("unroll") for (int _i = 0; _i < 2; ++_i) \
;         __builtin_amdgcn_global_load_lds((const unsigned*)((const char*)(gbase) + (voff)[_i]), (PG8_LAS unsigned*)(lds + (bufoff) + ldsw + _i * 8192), 16, 0, 0); } while (0)
; #define PG8_LDA(dst, b, h) do { _Pragma("unroll") for (int m = 0; m < 4; ++m) _Pragma("unroll") for (int k = 0; k < 2; ++k) dst[m][k] = *(const PG8_LAS bf16x8*)(lds + PG8_SA(b, h) + aoff + m * 2048 + k * 1024); } while (0)
; #define PG8_LDB(dst, b, h) do { _Pragma("unroll") for (int n = 0; n < 2; ++n) _Pragma("unroll") for (int k = 0; k < 2; ++k) dst[n][k] = *(const PG8_LAS bf16x8*)(lds + PG8_SB(b, h) + boff + n * 2048 + k * 1024); } while (0)
; #define PG8_MMA(ai, bj, At, Bt) do { __builtin_amdgcn_s_setprio(1); _Pragma("unroll") for (int m = 0; m < 4; ++m) _Pragma("unroll") for (int n = 0; n < 2; ++n) _Pragma("unroll") for (int k = 0; k < 2; ++k) \
;         acc[ai][bj][m][n] = __builtin_amdgcn_mfma_f32_16x16x32_bf16(Bt[n][k], At[m][k], acc[ai][bj][m][n], 0, 0, 0); __builtin_amdgcn_s_setprio(0); } while (0)
; #define PG8_BAR __builtin_amdgcn_s_barrier()
; template <class Epi, class Sched, bool ALIGN_EPI = false, bool SP2 = false>
; __device__ __forceinline__ void gemm_phase(PG8_LAS unsigned char* lds, const Gemm g, const Sched& S, const Epi& E) {
;     ...
;         const bool has_next = S.next(ui + 1, nxt);
;         const char* nA = has_next ? (const char*)g.A + (size_t)nxt.pm * tstep : cA; const char* nB = has_next ? (const char*)g.Bt + (size_t)nxt.pn * tstep : cB;
;         for (int t = 0; t < nt; t += 2) {
;             const bool last = (t == nt - 2);
;             const char* a1 = cA + (size_t)(t + 1) * kstep;
;             const char* a2 = last ? nA : cA + (size_t)(t + 2) * kstep; const char* b2 = last ? nB : cB + (size_t)(t + 2) * kstep;
;             const char* a3 = a2 + kstep; const char* b3 = b2 + kstep;
;             if (last && has_next) S.a_ready(nxt);
;             if constexpr (SP2) {
;             PG8_LDB(B0, 0, 0); PG8_LDB(B1, 0, 1); PG8_SCHED; PG8_LDA(At, 0, 0); PG8_STAGE(PG8_SA(1, 1), a1 + hstep, voffA);
;             PG8_WAIT_V(8); PG8_WAIT_L(0); PG8_BAR; PG8_MMA(0, 0, At, B0); PG8_MMA(0, 1, At, B1); PG8_BAR; PG8_SCHED;
;             PG8_LDA(At, 0, 1); PG8_STAGE(PG8_SB(0, 0), b2, voffB); PG8_STAGE(PG8_SB(0, 1), b2 + hstep, voffB); PG8_STAGE(PG8_SA(0, 0), a2, voffA);
.LBB0_1776:
	v_add_u32_e32 v166, s54, v169
	v_add_u32_e32 v168, s55, v169
	ds_read_b128 v[162:165], v166
	ds_read_b128 v[182:185], v166 offset:1024
	ds_read_b128 v[186:189], v166 offset:2048
	ds_read_b128 v[190:193], v166 offset:3072
	ds_read_b128 v[194:197], v168
	ds_read_b128 v[198:201], v168 offset:1024
	ds_read_b128 v[202:205], v168 offset:2048
	ds_read_b128 v[206:209], v168 offset:3072
	s_cmp_eq_u32 s53, s10
	v_lshl_add_u64 v[172:173], v[160:161], 0, s[22:23]
	s_cselect_b64 vcc, -1, 0
	s_add_i32 s10, s10, 2
	v_cndmask_b32_e32 v173, v173, v153, vcc
	v_cndmask_b32_e32 v172, v172, v152, vcc
	v_cndmask_b32_e32 v215, v159, v155, vcc
	v_cndmask_b32_e32 v214, v158, v154, vcc
	s_mov_b32 m0, s56
	v_lshl_add_u64 v[244:245], v[160:161], 0, v[148:149]
	ds_read_b128 v[210:213], v179
	ds_read_b128 v[216:219], v179 offset:1024
	ds_read_b128 v[220:223], v179 offset:2048
	ds_read_b128 v[224:227], v179 offset:3072
	ds_read_b128 v[228:231], v179 offset:4096
	ds_read_b128 v[232:235], v179 offset:5120
	ds_read_b128 v[236:239], v179 offset:6144
	ds_read_b128 v[240:243], v179 offset:7168
	global_load_lds_dwordx4 v[244:245], off
	s_mov_b32 m0, s57
	v_lshl_add_u64 v[244:245], v[160:161], 0, v[146:147]
	global_load_lds_dwordx4 v[244:245], off
	s_waitcnt vmcnt(8) lgkmcnt(0)
	s_setprio 1
	s_barrier
	v_mfma_f32_16x16x32_bf16 v[124:127], v[162:165], v[210:213], v[124:127]
	v_mfma_f32_16x16x32_bf16 v[116:119], v[186:189], v[210:213], v[116:119]
	v_mfma_f32_16x16x32_bf16 v[108:111], v[162:165], v[220:223], v[108:111]
	v_mfma_f32_16x16x32_bf16 v[100:103], v[186:189], v[220:223], v[100:103]
	v_mfma_f32_16x16x32_bf16 v[92:95], v[162:165], v[228:231], v[92:95]
	v_mfma_f32_16x16x32_bf16 v[84:87], v[186:189], v[228:231], v[84:87]
	v_mfma_f32_16x16x32_bf16 v[76:79], v[162:165], v[236:239], v[76:79]
	v_mfma_f32_16x16x32_bf16 v[68:71], v[186:189], v[236:239], v[68:71]
	v_mfma_f32_16x16x32_bf16 v[124:127], v[182:185], v[216:219], v[124:127]
	v_mfma_f32_16x16x32_bf16 v[116:119], v[190:193], v[216:219], v[116:119]
	v_mfma_f32_16x16x32_bf16 v[108:111], v[182:185], v[224:227], v[108:111]
	v_mfma_f32_16x16x32_bf16 v[100:103], v[190:193], v[224:227], v[100:103]
	v_mfma_f32_16x16x32_bf16 v[92:95], v[182:185], v[232:235], v[92:95]
	v_mfma_f32_16x16x32_bf16 v[84:87], v[190:193], v[232:235], v[84:87]
	v_mfma_f32_16x16x32_bf16 v[76:79], v[182:185], v[240:243], v[76:79]
	v_mfma_f32_16x16x32_bf16 v[68:71], v[190:193], v[240:243], v[68:71]
	v_mfma_f32_16x16x32_bf16 v[120:123], v[194:197], v[210:213], v[120:123]
	v_mfma_f32_16x16x32_bf16 v[112:115], v[202:205], v[210:213], v[112:115]
	v_mfma_f32_16x16x32_bf16 v[104:107], v[194:197], v[220:223], v[104:107]
	v_mfma_f32_16x16x32_bf16 v[96:99], v[202:205], v[220:223], v[96:99]
	v_mfma_f32_16x16x32_bf16 v[88:91], v[194:197], v[228:231], v[88:91]
	v_mfma_f32_16x16x32_bf16 v[80:83], v[202:205], v[228:231], v[80:83]
	v_mfma_f32_16x16x32_bf16 v[72:75], v[194:197], v[236:239], v[72:75]
	v_mfma_f32_16x16x32_bf16 v[64:67], v[202:205], v[236:239], v[64:67]
	v_mfma_f32_16x16x32_bf16 v[120:123], v[198:201], v[216:219], v[120:123]
	v_mfma_f32_16x16x32_bf16 v[112:115], v[206:209], v[216:219], v[112:115]
	v_mfma_f32_16x16x32_bf16 v[104:107], v[198:201], v[224:227], v[104:107]
	v_mfma_f32_16x16x32_bf16 v[96:99], v[206:209], v[224:227], v[96:99]
	v_mfma_f32_16x16x32_bf16 v[88:91], v[198:201], v[232:235], v[88:91]
	v_mfma_f32_16x16x32_bf16 v[80:83], v[206:209], v[232:235], v[80:83]
	v_mfma_f32_16x16x32_bf16 v[72:75], v[198:201], v[240:243], v[72:75]
	v_mfma_f32_16x16x32_bf16 v[64:67], v[206:209], v[240:243], v[64:67]
	s_setprio 0
	s_barrier
	s_mov_b32 m0, s60
	v_lshl_add_u64 v[244:245], v[214:215], 0, v[138:139]
	ds_read_b128 v[210:213], v179 offset:16384
	ds_read_b128 v[216:219], v179 offset:17408
	ds_read_b128 v[220:223], v179 offset:18432
	ds_read_b128 v[224:227], v179 offset:19456
	ds_read_b128 v[228:231], v179 offset:20480
	ds_read_b128 v[232:235], v179 offset:21504
	ds_read_b128 v[236:239], v179 offset:22528
	ds_read_b128 v[240:243], v179 offset:23552
	global_load_lds_dwordx4 v[244:245], off
	v_lshl_add_u64 v[246:247], v[214:215], 0, v[134:135]
	s_mov_b32 m0, s61
	v_lshl_add_u64 v[214:215], v[214:215], 0, s[14:15]
	global_load_lds_dwordx4 v[246:247], off
	v_lshl_add_u64 v[248:249], v[214:215], 0, v[138:139]
	s_mov_b32 m0, s62
	v_lshl_add_u64 v[214:215], v[214:215], 0, v[134:135]
	global_load_lds_dwordx4 v[248:249], off
	s_add_i32 m0, s62, 0x2000
	v_lshl_add_u64 v[250:251], v[172:173], 0, v[140:141]
	global_load_lds_dwordx4 v[214:215], off
	s_mov_b32 m0, s46
	v_lshl_add_u64 v[252:253], v[172:173], 0, v[136:137]
	global_load_lds_dwordx4 v[250:251], off
	s_mov_b32 m0, s47
	s_nop 0
	global_load_lds_dwordx4 v[252:253], off
	s_waitcnt vmcnt(8) lgkmcnt(0)
	s_setprio 1
	s_barrier
; #define PG8_STAGE(bufoff, gbase, voff) do { _Pragma("unroll") for (int _i = 0; _i < 2; ++_i) \
;         __builtin_amdgcn_global_load_lds((const unsigned*)((const char*)(gbase) + (voff)[_i]), (PG8_LAS unsigned*)(lds + (bufoff) + ldsw + _i * 8192), 16, 0, 0); } while (0)
; #define PG8_LDA(dst, b, h) do { _Pragma("unroll") for (int m = 0; m < 4; ++m) _Pragma("unroll") for (int k = 0; k < 2; ++k) dst[m][k] = *(const PG8_LAS bf16x8*)(lds + PG8_SA(b, h) + aoff + m * 2048 + k * 1024); } while (0)
; #define PG8_LDB(dst, b, h) do { _Pragma("unroll") for (int n = 0; n < 2; ++n) _Pragma("unroll") for (int k = 0; k < 2; ++k) dst[n][k] = *(const PG8_LAS bf16x8*)(lds + PG8_SB(b, h) + boff + n * 2048 + k * 1024); } while (0)
; #define PG8_MMA(ai, bj, At, Bt) do { __builtin_amdgcn_s_setprio(1); _Pragma("unroll") for (int m = 0; m < 4; ++m) _Pragma("unroll") for (int n = 0; n < 2; ++n) _Pragma("unroll") for (int k = 0; k < 2; ++k) \
;         acc[ai][bj][m][n] = __builtin_amdgcn_mfma_f32_16x16x32_bf16(Bt[n][k], At[m][k], acc[ai][bj][m][n], 0, 0, 0); __builtin_amdgcn_s_setprio(0); } while (0)
; #define PG8_WAIT_V(n) asm volatile("s_waitcnt vmcnt(" #n ")" ::: "memory")
; #define PG8_WAIT_L(n) asm volatile("s_waitcnt lgkmcnt(" #n ")" ::: "memory")
; #define PG8_BAR __builtin_amdgcn_s_barrier()
; #define PG8_SCHED __builtin_amdgcn_sched_barrier(0)
; template <class Epi, class Sched, bool ALIGN_EPI = false, bool SP2 = false>
; __device__ __forceinline__ void gemm_phase(PG8_LAS unsigned char* lds, const Gemm g, const Sched& S, const Epi& E) {
;     ...
;             PG8_WAIT_V(8); PG8_WAIT_L(0); PG8_BAR; PG8_MMA(1, 0, At, B0); PG8_MMA(1, 1, At, B1); PG8_BAR; PG8_SCHED;
;             PG8_LDB(B0, 1, 0); PG8_LDB(B1, 1, 1); PG8_SCHED; PG8_LDA(At, 1, 0); PG8_STAGE(PG8_SA(0, 1), a2 + hstep, voffA);
;             PG8_WAIT_V(8); PG8_WAIT_L(0); PG8_BAR; PG8_MMA(0, 0, At, B0); PG8_MMA(0, 1, At, B1); PG8_BAR; PG8_SCHED;
	v_mfma_f32_16x16x32_bf16 v[60:63], v[162:165], v[210:213], v[60:63]
	v_mfma_f32_16x16x32_bf16 v[52:55], v[186:189], v[210:213], v[52:55]
	v_mfma_f32_16x16x32_bf16 v[44:47], v[162:165], v[220:223], v[44:47]
	v_mfma_f32_16x16x32_bf16 v[36:39], v[186:189], v[220:223], v[36:39]
	v_mfma_f32_16x16x32_bf16 v[28:31], v[162:165], v[228:231], v[28:31]
	v_mfma_f32_16x16x32_bf16 v[20:23], v[186:189], v[228:231], v[20:23]
	v_mfma_f32_16x16x32_bf16 v[12:15], v[162:165], v[236:239], v[12:15]
	v_mfma_f32_16x16x32_bf16 v[4:7], v[186:189], v[236:239], v[4:7]
	v_mfma_f32_16x16x32_bf16 v[60:63], v[182:185], v[216:219], v[60:63]
	v_mfma_f32_16x16x32_bf16 v[52:55], v[190:193], v[216:219], v[52:55]
	v_mfma_f32_16x16x32_bf16 v[44:47], v[182:185], v[224:227], v[44:47]
	v_mfma_f32_16x16x32_bf16 v[36:39], v[190:193], v[224:227], v[36:39]
	v_mfma_f32_16x16x32_bf16 v[28:31], v[182:185], v[232:235], v[28:31]
	v_mfma_f32_16x16x32_bf16 v[20:23], v[190:193], v[232:235], v[20:23]
	v_mfma_f32_16x16x32_bf16 v[12:15], v[182:185], v[240:243], v[12:15]
	v_mfma_f32_16x16x32_bf16 v[4:7], v[190:193], v[240:243], v[4:7]
	v_mfma_f32_16x16x32_bf16 v[56:59], v[194:197], v[210:213], v[56:59]
	v_mfma_f32_16x16x32_bf16 v[48:51], v[202:205], v[210:213], v[48:51]
	v_mfma_f32_16x16x32_bf16 v[40:43], v[194:197], v[220:223], v[40:43]
	v_mfma_f32_16x16x32_bf16 v[32:35], v[202:205], v[220:223], v[32:35]
	v_mfma_f32_16x16x32_bf16 v[24:27], v[194:197], v[228:231], v[24:27]
	v_mfma_f32_16x16x32_bf16 v[16:19], v[202:205], v[228:231], v[16:19]
	v_mfma_f32_16x16x32_bf16 v[8:11], v[194:197], v[236:239], v[8:11]
	v_mfma_f32_16x16x32_bf16 v[0:3], v[202:205], v[236:239], v[0:3]
	v_mfma_f32_16x16x32_bf16 v[56:59], v[198:201], v[216:219], v[56:59]
	v_mfma_f32_16x16x32_bf16 v[48:51], v[206:209], v[216:219], v[48:51]
	v_mfma_f32_16x16x32_bf16 v[40:43], v[198:201], v[224:227], v[40:43]
	v_mfma_f32_16x16x32_bf16 v[32:35], v[206:209], v[224:227], v[32:35]
	v_mfma_f32_16x16x32_bf16 v[24:27], v[198:201], v[232:235], v[24:27]
	v_mfma_f32_16x16x32_bf16 v[16:19], v[206:209], v[232:235], v[16:19]
	v_mfma_f32_16x16x32_bf16 v[8:11], v[198:201], v[240:243], v[8:11]
	v_mfma_f32_16x16x32_bf16 v[0:3], v[206:209], v[240:243], v[0:3]
	s_setprio 0
	s_barrier
	s_add_i32 s11, 0, 0x18000
	v_add_u32_e32 v166, s11, v169
	s_add_i32 s13, 0, 0x1c000
	ds_read_b128 v[162:165], v166
	ds_read_b128 v[182:185], v166 offset:1024
	ds_read_b128 v[186:189], v166 offset:2048
	ds_read_b128 v[190:193], v166 offset:3072
	v_add_u32_e32 v166, s13, v169
	ds_read_b128 v[194:197], v166
	ds_read_b128 v[198:201], v166 offset:1024
	ds_read_b128 v[202:205], v166 offset:2048
	ds_read_b128 v[206:209], v166 offset:3072
	v_lshl_add_u64 v[172:173], v[172:173], 0, s[14:15]
	s_mov_b32 m0, s48
	v_lshl_add_u64 v[170:171], v[172:173], 0, v[140:141]
	ds_read_b128 v[210:213], v179 offset:32768
	ds_read_b128 v[216:219], v179 offset:33792
	ds_read_b128 v[220:223], v179 offset:34816
	ds_read_b128 v[224:227], v179 offset:35840
	ds_read_b128 v[228:231], v179 offset:36864
	ds_read_b128 v[232:235], v179 offset:37888
	ds_read_b128 v[236:239], v179 offset:38912
	ds_read_b128 v[240:243], v179 offset:39936
	global_load_lds_dwordx4 v[170:171], off
	s_mov_b32 m0, s49
	v_lshl_add_u64 v[170:171], v[172:173], 0, v[136:137]
	global_load_lds_dwordx4 v[170:171], off
	s_waitcnt vmcnt(8) lgkmcnt(0)
	s_setprio 1
	s_barrier
; #define PG8_STAGE(bufoff, gbase, voff) do { _Pragma("unroll") for (int _i = 0; _i < 2; ++_i) \
;         __builtin_amdgcn_global_load_lds((const unsigned*)((const char*)(gbase) + (voff)[_i]), (PG8_LAS unsigned*)(lds + (bufoff) + ldsw + _i * 8192), 16, 0, 0); } while (0)
; #define PG8_LDA(dst, b, h) do { _Pragma("unroll") for (int m = 0; m < 4; ++m) _Pragma("unroll") for (int k = 0; k < 2; ++k) dst[m][k] = *(const PG8_LAS bf16x8*)(lds + PG8_SA(b, h) + aoff + m * 2048 + k * 1024); } while (0)
; #define PG8_MMA(ai, bj, At, Bt) do { __builtin_amdgcn_s_setprio(1); _Pragma("unroll") for (int m = 0; m < 4; ++m) _Pragma("unroll") for (int n = 0; n < 2; ++n) _Pragma("unroll") for (int k = 0; k < 2; ++k) \
;         acc[ai][bj][m][n] = __builtin_amdgcn_mfma_f32_16x16x32_bf16(Bt[n][k], At[m][k], acc[ai][bj][m][n], 0, 0, 0); __builtin_amdgcn_s_setprio(0); } while (0)
; #define PG8_WAIT_V(n) asm volatile("s_waitcnt vmcnt(" #n ")" ::: "memory")
; #define PG8_WAIT_L(n) asm volatile("s_waitcnt lgkmcnt(" #n ")" ::: "memory")
; #define PG8_BAR __builtin_amdgcn_s_barrier()
; #define PG8_SCHED __builtin_amdgcn_sched_barrier(0)
; template <class Epi, class Sched, bool ALIGN_EPI = false, bool SP2 = false>
; __device__ __forceinline__ void gemm_phase(PG8_LAS unsigned char* lds, const Gemm g, const Sched& S, const Epi& E) {
;     ...
;             PG8_WAIT_V(8); PG8_WAIT_L(0); PG8_BAR; PG8_MMA(0, 0, At, B0); PG8_MMA(0, 1, At, B1); PG8_BAR; PG8_SCHED;
;             PG8_LDA(At, 1, 1); PG8_STAGE(PG8_SB(1, 0), b3, voffB); PG8_STAGE(PG8_SB(1, 1), b3 + hstep, voffB); PG8_STAGE(PG8_SA(1, 0), a3, voffA);
;             PG8_WAIT_V(8); PG8_WAIT_L(0); PG8_BAR; PG8_MMA(1, 0, At, B0); PG8_MMA(1, 1, At, B1); PG8_BAR; PG8_SCHED;
	v_mfma_f32_16x16x32_bf16 v[124:127], v[162:165], v[210:213], v[124:127]
	v_mfma_f32_16x16x32_bf16 v[116:119], v[186:189], v[210:213], v[116:119]
	v_mfma_f32_16x16x32_bf16 v[108:111], v[162:165], v[220:223], v[108:111]
	v_mfma_f32_16x16x32_bf16 v[100:103], v[186:189], v[220:223], v[100:103]
	v_mfma_f32_16x16x32_bf16 v[92:95], v[162:165], v[228:231], v[92:95]
	v_mfma_f32_16x16x32_bf16 v[84:87], v[186:189], v[228:231], v[84:87]
	v_mfma_f32_16x16x32_bf16 v[76:79], v[162:165], v[236:239], v[76:79]
	v_mfma_f32_16x16x32_bf16 v[68:71], v[186:189], v[236:239], v[68:71]
	v_mfma_f32_16x16x32_bf16 v[124:127], v[182:185], v[216:219], v[124:127]
	v_mfma_f32_16x16x32_bf16 v[116:119], v[190:193], v[216:219], v[116:119]
	v_mfma_f32_16x16x32_bf16 v[108:111], v[182:185], v[224:227], v[108:111]
	v_mfma_f32_16x16x32_bf16 v[100:103], v[190:193], v[224:227], v[100:103]
	v_mfma_f32_16x16x32_bf16 v[92:95], v[182:185], v[232:235], v[92:95]
	v_mfma_f32_16x16x32_bf16 v[84:87], v[190:193], v[232:235], v[84:87]
	v_mfma_f32_16x16x32_bf16 v[76:79], v[182:185], v[240:243], v[76:79]
	v_mfma_f32_16x16x32_bf16 v[68:71], v[190:193], v[240:243], v[68:71]
	v_mfma_f32_16x16x32_bf16 v[120:123], v[194:197], v[210:213], v[120:123]
	v_mfma_f32_16x16x32_bf16 v[112:115], v[202:205], v[210:213], v[112:115]
	v_mfma_f32_16x16x32_bf16 v[104:107], v[194:197], v[220:223], v[104:107]
	v_mfma_f32_16x16x32_bf16 v[96:99], v[202:205], v[220:223], v[96:99]
	v_mfma_f32_16x16x32_bf16 v[88:91], v[194:197], v[228:231], v[88:91]
	v_mfma_f32_16x16x32_bf16 v[80:83], v[202:205], v[228:231], v[80:83]
	v_mfma_f32_16x16x32_bf16 v[72:75], v[194:197], v[236:239], v[72:75]
	v_mfma_f32_16x16x32_bf16 v[64:67], v[202:205], v[236:239], v[64:67]
	v_mfma_f32_16x16x32_bf16 v[120:123], v[198:201], v[216:219], v[120:123]
	v_mfma_f32_16x16x32_bf16 v[112:115], v[206:209], v[216:219], v[112:115]
	v_mfma_f32_16x16x32_bf16 v[104:107], v[198:201], v[224:227], v[104:107]
	v_mfma_f32_16x16x32_bf16 v[96:99], v[206:209], v[224:227], v[96:99]
	v_mfma_f32_16x16x32_bf16 v[88:91], v[198:201], v[232:235], v[88:91]
	v_mfma_f32_16x16x32_bf16 v[80:83], v[206:209], v[232:235], v[80:83]
	v_mfma_f32_16x16x32_bf16 v[72:75], v[198:201], v[240:243], v[72:75]
	v_mfma_f32_16x16x32_bf16 v[64:67], v[206:209], v[240:243], v[64:67]
	s_setprio 0
	s_barrier
	s_add_i32 s11, s11, s29
	s_add_i32 m0, s11, 0xffffff80
	ds_read_b128 v[210:213], v179 offset:49152
	ds_read_b128 v[216:219], v179 offset:50176
	ds_read_b128 v[220:223], v179 offset:51200
	ds_read_b128 v[224:227], v179 offset:52224
	global_load_lds_dwordx4 v[244:245], off offset:128
	s_add_i32 m0, s11, 0x1f80
	s_add_i32 s11, s13, s29
	global_load_lds_dwordx4 v[246:247], off offset:128
	s_add_i32 m0, s11, 0xffffff80
	ds_read_b128 v[240:243], v179 offset:56320
	global_load_lds_dwordx4 v[248:249], off offset:128
	s_add_i32 m0, s11, 0x1f80
	ds_read_b128 v[236:239], v179 offset:55296
	global_load_lds_dwordx4 v[214:215], off offset:128
	s_add_i32 m0, s50, 0xffffff80
	ds_read_b128 v[232:235], v179 offset:54272
	global_load_lds_dwordx4 v[250:251], off offset:128
	s_add_i32 m0, s51, 0xffffff80
	ds_read_b128 v[228:231], v179 offset:53248
	global_load_lds_dwordx4 v[252:253], off offset:128
	s_waitcnt vmcnt(8) lgkmcnt(0)
	s_setprio 1
	s_barrier
	v_mfma_f32_16x16x32_bf16 v[60:63], v[162:165], v[210:213], v[60:63]
	v_mfma_f32_16x16x32_bf16 v[52:55], v[186:189], v[210:213], v[52:55]
	v_mfma_f32_16x16x32_bf16 v[44:47], v[162:165], v[220:223], v[44:47]
	v_mfma_f32_16x16x32_bf16 v[36:39], v[186:189], v[220:223], v[36:39]
	v_mfma_f32_16x16x32_bf16 v[28:31], v[162:165], v[228:231], v[28:31]
	v_mfma_f32_16x16x32_bf16 v[20:23], v[186:189], v[228:231], v[20:23]
	v_mfma_f32_16x16x32_bf16 v[12:15], v[162:165], v[236:239], v[12:15]
	v_mfma_f32_16x16x32_bf16 v[4:7], v[186:189], v[236:239], v[4:7]
	v_mfma_f32_16x16x32_bf16 v[60:63], v[182:185], v[216:219], v[60:63]
	v_mfma_f32_16x16x32_bf16 v[52:55], v[190:193], v[216:219], v[52:55]
	v_mfma_f32_16x16x32_bf16 v[44:47], v[182:185], v[224:227], v[44:47]
	v_mfma_f32_16x16x32_bf16 v[36:39], v[190:193], v[224:227], v[36:39]
	v_mfma_f32_16x16x32_bf16 v[28:31], v[182:185], v[232:235], v[28:31]
	v_mfma_f32_16x16x32_bf16 v[20:23], v[190:193], v[232:235], v[20:23]
	v_mfma_f32_16x16x32_bf16 v[12:15], v[182:185], v[240:243], v[12:15]
	v_mfma_f32_16x16x32_bf16 v[4:7], v[190:193], v[240:243], v[4:7]
	v_mfma_f32_16x16x32_bf16 v[56:59], v[194:197], v[210:213], v[56:59]
	v_mfma_f32_16x16x32_bf16 v[48:51], v[202:205], v[210:213], v[48:51]
	v_mfma_f32_16x16x32_bf16 v[40:43], v[194:197], v[220:223], v[40:43]
	v_mfma_f32_16x16x32_bf16 v[32:35], v[202:205], v[220:223], v[32:35]
	v_mfma_f32_16x16x32_bf16 v[24:27], v[194:197], v[228:231], v[24:27]
	v_mfma_f32_16x16x32_bf16 v[16:19], v[202:205], v[228:231], v[16:19]
	v_mfma_f32_16x16x32_bf16 v[8:11], v[194:197], v[236:239], v[8:11]
	v_mfma_f32_16x16x32_bf16 v[0:3], v[202:205], v[236:239], v[0:3]
	v_mfma_f32_16x16x32_bf16 v[56:59], v[198:201], v[216:219], v[56:59]
	v_mfma_f32_16x16x32_bf16 v[48:51], v[206:209], v[216:219], v[48:51]
	v_mfma_f32_16x16x32_bf16 v[40:43], v[198:201], v[224:227], v[40:43]
	v_mfma_f32_16x16x32_bf16 v[32:35], v[206:209], v[224:227], v[32:35]
	v_mfma_f32_16x16x32_bf16 v[24:27], v[198:201], v[232:235], v[24:27]
	v_mfma_f32_16x16x32_bf16 v[16:19], v[206:209], v[232:235], v[16:19]
	v_mfma_f32_16x16x32_bf16 v[8:11], v[198:201], v[240:243], v[8:11]
	v_mfma_f32_16x16x32_bf16 v[0:3], v[206:209], v[240:243], v[0:3]
	s_setprio 0
	s_barrier
	v_lshl_add_u64 v[158:159], v[158:159], 0, s[26:27]
	s_cmp_ge_i32 s10, s52
	v_lshl_add_u64 v[160:161], v[160:161], 0, s[26:27]
	s_cbranch_scc0 .LBB0_1776

; #define PG8_STAGE(bufoff, gbase, voff) do { _Pragma("unroll") for (int _i = 0; _i < 2; ++_i) \
;         __builtin_amdgcn_global_load_lds((const unsigned*)((const char*)(gbase) + (voff)[_i]), (PG8_LAS unsigned*)(lds + (bufoff) + ldsw + _i * 8192), 16, 0, 0); } while (0)
; #define PG8_LDA(dst, b, h) do { _Pragma("unroll") for (int m = 0; m < 4; ++m) _Pragma("unroll") for (int k = 0; k < 2; ++k) dst[m][k] = *(const PG8_LAS bf16x8*)(lds + PG8_SA(b, h) + aoff + m * 2048 + k * 1024); } while (0)
; #define PG8_LDB(dst, b, h) do { _Pragma("unroll") for (int n = 0; n < 2; ++n) _Pragma("unroll") for (int k = 0; k < 2; ++k) dst[n][k] = *(const PG8_LAS bf16x8*)(lds + PG8_SB(b, h) + boff + n * 2048 + k * 1024); } while (0)
; #define PG8_MMA(ai, bj, At, Bt) do { __builtin_amdgcn_s_setprio(1); _Pragma("unroll") for (int m = 0; m < 4; ++m) _Pragma("unroll") for (int n = 0; n < 2; ++n) _Pragma("unroll") for (int k = 0; k < 2; ++k) \
;         acc[ai][bj][m][n] = __builtin_amdgcn_mfma_f32_16x16x32_bf16(Bt[n][k], At[m][k], acc[ai][bj][m][n], 0, 0, 0); __builtin_amdgcn_s_setprio(0); } while (0)
; #define PG8_WAIT_V(n) asm volatile("s_waitcnt vmcnt(" #n ")" ::: "memory")
; #define PG8_WAIT_L(n) asm volatile("s_waitcnt lgkmcnt(" #n ")" ::: "memory")
; template <class Epi, class Sched, bool ALIGN_EPI = false, bool SP2 = false>
; __device__ __forceinline__ void gemm_phase(PG8_LAS unsigned char* lds, const Gemm g, const Sched& S, const Epi& E) {
;     ...
;             const bool last = (t == nt - 2);
;             const char* a1 = cA + (size_t)(t + 1) * kstep;
;             const char* a2 = last ? nA : cA + (size_t)(t + 2) * kstep; const char* b2 = last ? nB : cB + (size_t)(t + 2) * kstep;
;             const char* a3 = a2 + kstep; const char* b3 = b2 + kstep;
;             if (last && has_next) S.a_ready(nxt);
;             if constexpr (SP2) {
;             PG8_LDB(B0, 0, 0); PG8_LDB(B1, 0, 1); PG8_SCHED; PG8_LDA(At, 0, 0); PG8_STAGE(PG8_SA(1, 1), a1 + hstep, voffA);
;             PG8_WAIT_V(8); PG8_WAIT_L(0); PG8_BAR; PG8_MMA(0, 0, At, B0); PG8_MMA(0, 1, At, B1); PG8_BAR; PG8_SCHED;
;             PG8_LDA(At, 0, 1); PG8_STAGE(PG8_SB(0, 0), b2, voffB); PG8_STAGE(PG8_SB(0, 1), b2 + hstep, voffB); PG8_STAGE(PG8_SA(0, 0), a2, voffA);
;             PG8_WAIT_V(8); PG8_WAIT_L(0); PG8_BAR; PG8_MMA(1, 0, At, B0); PG8_MMA(1, 1, At, B1); PG8_BAR; PG8_SCHED;
.LBB0_1924:
	v_add_u32_e32 v192, s50, v161
	ds_read_b128 v[164:167], v162
	ds_read_b128 v[168:171], v162 offset:1024
	ds_read_b128 v[172:175], v162 offset:2048
	ds_read_b128 v[176:179], v162 offset:3072
	ds_read_b128 v[180:183], v192
	ds_read_b128 v[184:187], v192 offset:1024
	ds_read_b128 v[188:191], v192 offset:2048
	ds_read_b128 v[192:195], v192 offset:3072
	s_cmp_eq_u32 s49, s10
	v_lshl_add_u64 v[196:197], v[158:159], 0, s[24:25]
	s_cselect_b64 vcc, -1, 0
	s_add_i32 s10, s10, 2
	v_cndmask_b32_e32 v213, v197, v151, vcc
	v_cndmask_b32_e32 v212, v196, v150, vcc
	v_cndmask_b32_e32 v215, v155, v153, vcc
	v_cndmask_b32_e32 v214, v154, v152, vcc
	s_mov_b32 m0, s51
	v_lshl_add_u64 v[232:233], v[158:159], 0, v[146:147]
	ds_read_b128 v[196:199], v163
	ds_read_b128 v[200:203], v163 offset:1024
	ds_read_b128 v[204:207], v163 offset:2048
	ds_read_b128 v[208:211], v163 offset:3072
	ds_read_b128 v[216:219], v163 offset:4096
	ds_read_b128 v[220:223], v163 offset:5120
	ds_read_b128 v[224:227], v163 offset:6144
	ds_read_b128 v[228:231], v163 offset:7168
	global_load_lds_dwordx4 v[232:233], off
	s_mov_b32 m0, s52
	v_lshl_add_u64 v[232:233], v[158:159], 0, v[144:145]
	global_load_lds_dwordx4 v[232:233], off
	s_waitcnt vmcnt(8) lgkmcnt(0)
	s_setprio 1
	s_barrier
	v_mfma_f32_16x16x32_bf16 v[124:127], v[164:167], v[196:199], v[124:127]
	v_mfma_f32_16x16x32_bf16 v[120:123], v[172:175], v[196:199], v[120:123]
	v_mfma_f32_16x16x32_bf16 v[108:111], v[164:167], v[204:207], v[108:111]
	v_mfma_f32_16x16x32_bf16 v[104:107], v[172:175], v[204:207], v[104:107]
	v_mfma_f32_16x16x32_bf16 v[92:95], v[164:167], v[216:219], v[92:95]
	v_mfma_f32_16x16x32_bf16 v[88:91], v[172:175], v[216:219], v[88:91]
	v_mfma_f32_16x16x32_bf16 v[76:79], v[164:167], v[224:227], v[76:79]
	v_mfma_f32_16x16x32_bf16 v[72:75], v[172:175], v[224:227], v[72:75]
	v_mfma_f32_16x16x32_bf16 v[124:127], v[168:171], v[200:203], v[124:127]
	v_mfma_f32_16x16x32_bf16 v[120:123], v[176:179], v[200:203], v[120:123]
	v_mfma_f32_16x16x32_bf16 v[108:111], v[168:171], v[208:211], v[108:111]
	v_mfma_f32_16x16x32_bf16 v[104:107], v[176:179], v[208:211], v[104:107]
	v_mfma_f32_16x16x32_bf16 v[92:95], v[168:171], v[220:223], v[92:95]
	v_mfma_f32_16x16x32_bf16 v[88:91], v[176:179], v[220:223], v[88:91]
	v_mfma_f32_16x16x32_bf16 v[76:79], v[168:171], v[228:231], v[76:79]
	v_mfma_f32_16x16x32_bf16 v[72:75], v[176:179], v[228:231], v[72:75]
	v_mfma_f32_16x16x32_bf16 v[116:119], v[180:183], v[196:199], v[116:119]
	v_mfma_f32_16x16x32_bf16 v[112:115], v[188:191], v[196:199], v[112:115]
	v_mfma_f32_16x16x32_bf16 v[100:103], v[180:183], v[204:207], v[100:103]
	v_mfma_f32_16x16x32_bf16 v[96:99], v[188:191], v[204:207], v[96:99]
	v_mfma_f32_16x16x32_bf16 v[84:87], v[180:183], v[216:219], v[84:87]
	v_mfma_f32_16x16x32_bf16 v[80:83], v[188:191], v[216:219], v[80:83]
	v_mfma_f32_16x16x32_bf16 v[68:71], v[180:183], v[224:227], v[68:71]
	v_mfma_f32_16x16x32_bf16 v[64:67], v[188:191], v[224:227], v[64:67]
	v_mfma_f32_16x16x32_bf16 v[116:119], v[184:187], v[200:203], v[116:119]
	v_mfma_f32_16x16x32_bf16 v[112:115], v[192:195], v[200:203], v[112:115]
	v_mfma_f32_16x16x32_bf16 v[100:103], v[184:187], v[208:211], v[100:103]
	v_mfma_f32_16x16x32_bf16 v[96:99], v[192:195], v[208:211], v[96:99]
	v_mfma_f32_16x16x32_bf16 v[84:87], v[184:187], v[220:223], v[84:87]
	v_mfma_f32_16x16x32_bf16 v[80:83], v[192:195], v[220:223], v[80:83]
	v_mfma_f32_16x16x32_bf16 v[68:71], v[184:187], v[228:231], v[68:71]
	v_mfma_f32_16x16x32_bf16 v[64:67], v[192:195], v[228:231], v[64:67]
	s_setprio 0
	s_barrier
	s_mov_b32 m0, s53
	v_lshl_add_u64 v[232:233], v[214:215], 0, v[138:139]
	ds_read_b128 v[196:199], v163 offset:16384
	ds_read_b128 v[200:203], v163 offset:17408
	ds_read_b128 v[204:207], v163 offset:18432
	ds_read_b128 v[208:211], v163 offset:19456
	ds_read_b128 v[216:219], v163 offset:20480
	ds_read_b128 v[220:223], v163 offset:21504
	ds_read_b128 v[224:227], v163 offset:22528
	ds_read_b128 v[228:231], v163 offset:23552
	global_load_lds_dwordx4 v[232:233], off
	v_lshl_add_u64 v[234:235], v[214:215], 0, v[134:135]
	s_mov_b32 m0, s54
	v_lshl_add_u64 v[214:215], v[214:215], 0, s[14:15]
	global_load_lds_dwordx4 v[234:235], off
	v_lshl_add_u64 v[236:237], v[214:215], 0, v[138:139]
	s_mov_b32 m0, s55
	v_lshl_add_u64 v[214:215], v[214:215], 0, v[134:135]
	global_load_lds_dwordx4 v[236:237], off
	s_mov_b32 m0, s56
	v_lshl_add_u64 v[238:239], v[212:213], 0, v[140:141]
	global_load_lds_dwordx4 v[214:215], off
	s_mov_b32 m0, s37
	v_lshl_add_u64 v[240:241], v[212:213], 0, v[136:137]
	global_load_lds_dwordx4 v[238:239], off
	s_mov_b32 m0, s41
	s_nop 0
	global_load_lds_dwordx4 v[240:241], off
	s_waitcnt vmcnt(8) lgkmcnt(0)
	s_setprio 1
	s_barrier
; #define PG8_STAGE(bufoff, gbase, voff) do { _Pragma("unroll") for (int _i = 0; _i < 2; ++_i) \
;         __builtin_amdgcn_global_load_lds((const unsigned*)((const char*)(gbase) + (voff)[_i]), (PG8_LAS unsigned*)(lds + (bufoff) + ldsw + _i * 8192), 16, 0, 0); } while (0)
; #define PG8_LDA(dst, b, h) do { _Pragma("unroll") for (int m = 0; m < 4; ++m) _Pragma("unroll") for (int k = 0; k < 2; ++k) dst[m][k] = *(const PG8_LAS bf16x8*)(lds + PG8_SA(b, h) + aoff + m * 2048 + k * 1024); } while (0)
; #define PG8_LDB(dst, b, h) do { _Pragma("unroll") for (int n = 0; n < 2; ++n) _Pragma("unroll") for (int k = 0; k < 2; ++k) dst[n][k] = *(const PG8_LAS bf16x8*)(lds + PG8_SB(b, h) + boff + n * 2048 + k * 1024); } while (0)
; #define PG8_MMA(ai, bj, At, Bt) do { __builtin_amdgcn_s_setprio(1); _Pragma("unroll") for (int m = 0; m < 4; ++m) _Pragma("unroll") for (int n = 0; n < 2; ++n) _Pragma("unroll") for (int k = 0; k < 2; ++k) \
;         acc[ai][bj][m][n] = __builtin_amdgcn_mfma_f32_16x16x32_bf16(Bt[n][k], At[m][k], acc[ai][bj][m][n], 0, 0, 0); __builtin_amdgcn_s_setprio(0); } while (0)
; #define PG8_WAIT_V(n) asm volatile("s_waitcnt vmcnt(" #n ")" ::: "memory")
; #define PG8_WAIT_L(n) asm volatile("s_waitcnt lgkmcnt(" #n ")" ::: "memory")
; #define PG8_BAR __builtin_amdgcn_s_barrier()
; #define PG8_SCHED __builtin_amdgcn_sched_barrier(0)
; template <class Epi, class Sched, bool ALIGN_EPI = false, bool SP2 = false>
; __device__ __forceinline__ void gemm_phase(PG8_LAS unsigned char* lds, const Gemm g, const Sched& S, const Epi& E) {
;     ...
;             PG8_WAIT_V(8); PG8_WAIT_L(0); PG8_BAR; PG8_MMA(1, 0, At, B0); PG8_MMA(1, 1, At, B1); PG8_BAR; PG8_SCHED;
;             PG8_LDB(B0, 1, 0); PG8_LDB(B1, 1, 1); PG8_SCHED; PG8_LDA(At, 1, 0); PG8_STAGE(PG8_SA(0, 1), a2 + hstep, voffA);
;             PG8_WAIT_V(8); PG8_WAIT_L(0); PG8_BAR; PG8_MMA(0, 0, At, B0); PG8_MMA(0, 1, At, B1); PG8_BAR; PG8_SCHED;
	v_mfma_f32_16x16x32_bf16 v[60:63], v[164:167], v[196:199], v[60:63]
	v_mfma_f32_16x16x32_bf16 v[56:59], v[172:175], v[196:199], v[56:59]
	v_mfma_f32_16x16x32_bf16 v[44:47], v[164:167], v[204:207], v[44:47]
	v_mfma_f32_16x16x32_bf16 v[40:43], v[172:175], v[204:207], v[40:43]
	v_mfma_f32_16x16x32_bf16 v[28:31], v[164:167], v[216:219], v[28:31]
	v_mfma_f32_16x16x32_bf16 v[24:27], v[172:175], v[216:219], v[24:27]
	v_mfma_f32_16x16x32_bf16 v[12:15], v[164:167], v[224:227], v[12:15]
	v_mfma_f32_16x16x32_bf16 v[8:11], v[172:175], v[224:227], v[8:11]
	v_mfma_f32_16x16x32_bf16 v[60:63], v[168:171], v[200:203], v[60:63]
	v_mfma_f32_16x16x32_bf16 v[56:59], v[176:179], v[200:203], v[56:59]
	v_mfma_f32_16x16x32_bf16 v[44:47], v[168:171], v[208:211], v[44:47]
	v_mfma_f32_16x16x32_bf16 v[40:43], v[176:179], v[208:211], v[40:43]
	v_mfma_f32_16x16x32_bf16 v[28:31], v[168:171], v[220:223], v[28:31]
	v_mfma_f32_16x16x32_bf16 v[24:27], v[176:179], v[220:223], v[24:27]
	v_mfma_f32_16x16x32_bf16 v[12:15], v[168:171], v[228:231], v[12:15]
	v_mfma_f32_16x16x32_bf16 v[8:11], v[176:179], v[228:231], v[8:11]
	v_mfma_f32_16x16x32_bf16 v[52:55], v[180:183], v[196:199], v[52:55]
	v_mfma_f32_16x16x32_bf16 v[48:51], v[188:191], v[196:199], v[48:51]
	v_mfma_f32_16x16x32_bf16 v[36:39], v[180:183], v[204:207], v[36:39]
	v_mfma_f32_16x16x32_bf16 v[32:35], v[188:191], v[204:207], v[32:35]
	v_mfma_f32_16x16x32_bf16 v[20:23], v[180:183], v[216:219], v[20:23]
	v_mfma_f32_16x16x32_bf16 v[16:19], v[188:191], v[216:219], v[16:19]
	v_mfma_f32_16x16x32_bf16 v[4:7], v[180:183], v[224:227], v[4:7]
	v_mfma_f32_16x16x32_bf16 v[0:3], v[188:191], v[224:227], v[0:3]
	v_mfma_f32_16x16x32_bf16 v[52:55], v[184:187], v[200:203], v[52:55]
	v_mfma_f32_16x16x32_bf16 v[48:51], v[192:195], v[200:203], v[48:51]
	v_mfma_f32_16x16x32_bf16 v[36:39], v[184:187], v[208:211], v[36:39]
	v_mfma_f32_16x16x32_bf16 v[32:35], v[192:195], v[208:211], v[32:35]
	v_mfma_f32_16x16x32_bf16 v[20:23], v[184:187], v[220:223], v[20:23]
	v_mfma_f32_16x16x32_bf16 v[16:19], v[192:195], v[220:223], v[16:19]
	v_mfma_f32_16x16x32_bf16 v[4:7], v[184:187], v[228:231], v[4:7]
	v_mfma_f32_16x16x32_bf16 v[0:3], v[192:195], v[228:231], v[0:3]
	s_setprio 0
	s_barrier
	v_add_u32_e32 v176, s57, v161
	v_add_u32_e32 v192, s58, v161
	ds_read_b128 v[164:167], v176
	ds_read_b128 v[168:171], v176 offset:1024
	ds_read_b128 v[172:175], v176 offset:2048
	ds_read_b128 v[176:179], v176 offset:3072
	ds_read_b128 v[180:183], v192
	ds_read_b128 v[184:187], v192 offset:1024
	ds_read_b128 v[188:191], v192 offset:2048
	ds_read_b128 v[192:195], v192 offset:3072
	v_lshl_add_u64 v[212:213], v[212:213], 0, s[14:15]
	s_mov_b32 m0, s44
	v_lshl_add_u64 v[242:243], v[212:213], 0, v[140:141]
	ds_read_b128 v[196:199], v163 offset:32768
	ds_read_b128 v[200:203], v163 offset:33792
	ds_read_b128 v[204:207], v163 offset:34816
	ds_read_b128 v[208:211], v163 offset:35840
	ds_read_b128 v[216:219], v163 offset:36864
	ds_read_b128 v[220:223], v163 offset:37888
	ds_read_b128 v[224:227], v163 offset:38912
	ds_read_b128 v[228:231], v163 offset:39936
	global_load_lds_dwordx4 v[242:243], off
	s_mov_b32 m0, s45
	v_lshl_add_u64 v[212:213], v[212:213], 0, v[136:137]
	global_load_lds_dwordx4 v[212:213], off
	s_waitcnt vmcnt(8) lgkmcnt(0)
	s_setprio 1
	s_barrier
; #define PG8_STAGE(bufoff, gbase, voff) do { _Pragma("unroll") for (int _i = 0; _i < 2; ++_i) \
;         __builtin_amdgcn_global_load_lds((const unsigned*)((const char*)(gbase) + (voff)[_i]), (PG8_LAS unsigned*)(lds + (bufoff) + ldsw + _i * 8192), 16, 0, 0); } while (0)
; #define PG8_LDA(dst, b, h) do { _Pragma("unroll") for (int m = 0; m < 4; ++m) _Pragma("unroll") for (int k = 0; k < 2; ++k) dst[m][k] = *(const PG8_LAS bf16x8*)(lds + PG8_SA(b, h) + aoff + m * 2048 + k * 1024); } while (0)
; #define PG8_MMA(ai, bj, At, Bt) do { __builtin_amdgcn_s_setprio(1); _Pragma("unroll") for (int m = 0; m < 4; ++m) _Pragma("unroll") for (int n = 0; n < 2; ++n) _Pragma("unroll") for (int k = 0; k < 2; ++k) \
;         acc[ai][bj][m][n] = __builtin_amdgcn_mfma_f32_16x16x32_bf16(Bt[n][k], At[m][k], acc[ai][bj][m][n], 0, 0, 0); __builtin_amdgcn_s_setprio(0); } while (0)
; #define PG8_WAIT_V(n) asm volatile("s_waitcnt vmcnt(" #n ")" ::: "memory")
; #define PG8_WAIT_L(n) asm volatile("s_waitcnt lgkmcnt(" #n ")" ::: "memory")
; #define PG8_BAR __builtin_amdgcn_s_barrier()
; #define PG8_SCHED __builtin_amdgcn_sched_barrier(0)
; template <class Epi, class Sched, bool ALIGN_EPI = false, bool SP2 = false>
; __device__ __forceinline__ void gemm_phase(PG8_LAS unsigned char* lds, const Gemm g, const Sched& S, const Epi& E) {
;     ...
;             PG8_WAIT_V(8); PG8_WAIT_L(0); PG8_BAR; PG8_MMA(0, 0, At, B0); PG8_MMA(0, 1, At, B1); PG8_BAR; PG8_SCHED;
;             PG8_LDA(At, 1, 1); PG8_STAGE(PG8_SB(1, 0), b3, voffB); PG8_STAGE(PG8_SB(1, 1), b3 + hstep, voffB); PG8_STAGE(PG8_SA(1, 0), a3, voffA);
;             PG8_WAIT_V(8); PG8_WAIT_L(0); PG8_BAR; PG8_MMA(1, 0, At, B0); PG8_MMA(1, 1, At, B1); PG8_BAR; PG8_SCHED;
	v_mfma_f32_16x16x32_bf16 v[124:127], v[164:167], v[196:199], v[124:127]
	v_mfma_f32_16x16x32_bf16 v[120:123], v[172:175], v[196:199], v[120:123]
	v_mfma_f32_16x16x32_bf16 v[108:111], v[164:167], v[204:207], v[108:111]
	v_mfma_f32_16x16x32_bf16 v[104:107], v[172:175], v[204:207], v[104:107]
	v_mfma_f32_16x16x32_bf16 v[92:95], v[164:167], v[216:219], v[92:95]
	v_mfma_f32_16x16x32_bf16 v[88:91], v[172:175], v[216:219], v[88:91]
	v_mfma_f32_16x16x32_bf16 v[76:79], v[164:167], v[224:227], v[76:79]
	v_mfma_f32_16x16x32_bf16 v[72:75], v[172:175], v[224:227], v[72:75]
	v_mfma_f32_16x16x32_bf16 v[124:127], v[168:171], v[200:203], v[124:127]
	v_mfma_f32_16x16x32_bf16 v[120:123], v[176:179], v[200:203], v[120:123]
	v_mfma_f32_16x16x32_bf16 v[108:111], v[168:171], v[208:211], v[108:111]
	v_mfma_f32_16x16x32_bf16 v[104:107], v[176:179], v[208:211], v[104:107]
	v_mfma_f32_16x16x32_bf16 v[92:95], v[168:171], v[220:223], v[92:95]
	v_mfma_f32_16x16x32_bf16 v[88:91], v[176:179], v[220:223], v[88:91]
	v_mfma_f32_16x16x32_bf16 v[76:79], v[168:171], v[228:231], v[76:79]
	v_mfma_f32_16x16x32_bf16 v[72:75], v[176:179], v[228:231], v[72:75]
	v_mfma_f32_16x16x32_bf16 v[116:119], v[180:183], v[196:199], v[116:119]
	v_mfma_f32_16x16x32_bf16 v[112:115], v[188:191], v[196:199], v[112:115]
	v_mfma_f32_16x16x32_bf16 v[100:103], v[180:183], v[204:207], v[100:103]
	v_mfma_f32_16x16x32_bf16 v[96:99], v[188:191], v[204:207], v[96:99]
	v_mfma_f32_16x16x32_bf16 v[84:87], v[180:183], v[216:219], v[84:87]
	v_mfma_f32_16x16x32_bf16 v[80:83], v[188:191], v[216:219], v[80:83]
	v_mfma_f32_16x16x32_bf16 v[68:71], v[180:183], v[224:227], v[68:71]
	v_mfma_f32_16x16x32_bf16 v[64:67], v[188:191], v[224:227], v[64:67]
	v_mfma_f32_16x16x32_bf16 v[116:119], v[184:187], v[200:203], v[116:119]
	v_mfma_f32_16x16x32_bf16 v[112:115], v[192:195], v[200:203], v[112:115]
	v_mfma_f32_16x16x32_bf16 v[100:103], v[184:187], v[208:211], v[100:103]
	v_mfma_f32_16x16x32_bf16 v[96:99], v[192:195], v[208:211], v[96:99]
	v_mfma_f32_16x16x32_bf16 v[84:87], v[184:187], v[220:223], v[84:87]
	v_mfma_f32_16x16x32_bf16 v[80:83], v[192:195], v[220:223], v[80:83]
	v_mfma_f32_16x16x32_bf16 v[68:71], v[184:187], v[228:231], v[68:71]
	v_mfma_f32_16x16x32_bf16 v[64:67], v[192:195], v[228:231], v[64:67]
	s_setprio 0
	s_barrier
	s_add_i32 m0, s59, 0xffffff80
	ds_read_b128 v[196:199], v163 offset:49152
	ds_read_b128 v[200:203], v163 offset:50176
	ds_read_b128 v[204:207], v163 offset:51200
	global_load_lds_dwordx4 v[232:233], off offset:128
	s_add_i32 m0, s60, 0xffffff80
	ds_read_b128 v[228:231], v163 offset:56320
	global_load_lds_dwordx4 v[234:235], off offset:128
	s_add_i32 m0, s61, 0xffffff80
	ds_read_b128 v[224:227], v163 offset:55296
	global_load_lds_dwordx4 v[236:237], off offset:128
	s_add_i32 m0, s62, 0xffffff80
	ds_read_b128 v[220:223], v163 offset:54272
	global_load_lds_dwordx4 v[214:215], off offset:128
	s_add_i32 m0, s46, 0xffffff80
	ds_read_b128 v[216:219], v163 offset:53248
	global_load_lds_dwordx4 v[238:239], off offset:128
	s_add_i32 m0, s47, 0xffffff80
	ds_read_b128 v[208:211], v163 offset:52224
	global_load_lds_dwordx4 v[240:241], off offset:128
	s_waitcnt vmcnt(8) lgkmcnt(0)
	s_setprio 1
	s_barrier
	v_mfma_f32_16x16x32_bf16 v[60:63], v[164:167], v[196:199], v[60:63]
	v_mfma_f32_16x16x32_bf16 v[56:59], v[172:175], v[196:199], v[56:59]
	v_mfma_f32_16x16x32_bf16 v[44:47], v[164:167], v[204:207], v[44:47]
	v_mfma_f32_16x16x32_bf16 v[40:43], v[172:175], v[204:207], v[40:43]
	v_mfma_f32_16x16x32_bf16 v[28:31], v[164:167], v[216:219], v[28:31]
	v_mfma_f32_16x16x32_bf16 v[24:27], v[172:175], v[216:219], v[24:27]
	v_mfma_f32_16x16x32_bf16 v[12:15], v[164:167], v[224:227], v[12:15]
	v_mfma_f32_16x16x32_bf16 v[8:11], v[172:175], v[224:227], v[8:11]
	v_mfma_f32_16x16x32_bf16 v[60:63], v[168:171], v[200:203], v[60:63]
	v_mfma_f32_16x16x32_bf16 v[56:59], v[176:179], v[200:203], v[56:59]
	v_mfma_f32_16x16x32_bf16 v[44:47], v[168:171], v[208:211], v[44:47]
	v_mfma_f32_16x16x32_bf16 v[40:43], v[176:179], v[208:211], v[40:43]
	v_mfma_f32_16x16x32_bf16 v[28:31], v[168:171], v[220:223], v[28:31]
	v_mfma_f32_16x16x32_bf16 v[24:27], v[176:179], v[220:223], v[24:27]
	v_mfma_f32_16x16x32_bf16 v[12:15], v[168:171], v[228:231], v[12:15]
	v_mfma_f32_16x16x32_bf16 v[8:11], v[176:179], v[228:231], v[8:11]
	v_mfma_f32_16x16x32_bf16 v[52:55], v[180:183], v[196:199], v[52:55]
	v_mfma_f32_16x16x32_bf16 v[48:51], v[188:191], v[196:199], v[48:51]
	v_mfma_f32_16x16x32_bf16 v[36:39], v[180:183], v[204:207], v[36:39]
	v_mfma_f32_16x16x32_bf16 v[32:35], v[188:191], v[204:207], v[32:35]
	v_mfma_f32_16x16x32_bf16 v[20:23], v[180:183], v[216:219], v[20:23]
	v_mfma_f32_16x16x32_bf16 v[16:19], v[188:191], v[216:219], v[16:19]
	v_mfma_f32_16x16x32_bf16 v[4:7], v[180:183], v[224:227], v[4:7]
	v_mfma_f32_16x16x32_bf16 v[0:3], v[188:191], v[224:227], v[0:3]
	v_mfma_f32_16x16x32_bf16 v[52:55], v[184:187], v[200:203], v[52:55]
	v_mfma_f32_16x16x32_bf16 v[48:51], v[192:195], v[200:203], v[48:51]
	v_mfma_f32_16x16x32_bf16 v[36:39], v[184:187], v[208:211], v[36:39]
	v_mfma_f32_16x16x32_bf16 v[32:35], v[192:195], v[208:211], v[32:35]
	v_mfma_f32_16x16x32_bf16 v[20:23], v[184:187], v[220:223], v[20:23]
	v_mfma_f32_16x16x32_bf16 v[16:19], v[192:195], v[220:223], v[16:19]
	v_mfma_f32_16x16x32_bf16 v[4:7], v[184:187], v[228:231], v[4:7]
	v_mfma_f32_16x16x32_bf16 v[0:3], v[192:195], v[228:231], v[0:3]
	s_setprio 0
	s_barrier
	v_lshl_add_u64 v[154:155], v[154:155], 0, s[28:29]
	s_cmp_ge_i32 s10, s48
	v_lshl_add_u64 v[158:159], v[158:159], 0, s[28:29]
	s_cbranch_scc0 .LBB0_1924

; #define PG8_STAGE(bufoff, gbase, voff) do { _Pragma("unroll") for (int _i = 0; _i < 2; ++_i) \
;         __builtin_amdgcn_global_load_lds((const unsigned*)((const char*)(gbase) + (voff)[_i]), (PG8_LAS unsigned*)(lds + (bufoff) + ldsw + _i * 8192), 16, 0, 0); } while (0)
; #define PG8_LDA(dst, b, h) do { _Pragma("unroll") for (int m = 0; m < 4; ++m) _Pragma("unroll") for (int k = 0; k < 2; ++k) dst[m][k] = *(const PG8_LAS bf16x8*)(lds + PG8_SA(b, h) + aoff + m * 2048 + k * 1024); } while (0)
; #define PG8_LDB(dst, b, h) do { _Pragma("unroll") for (int n = 0; n < 2; ++n) _Pragma("unroll") for (int k = 0; k < 2; ++k) dst[n][k] = *(const PG8_LAS bf16x8*)(lds + PG8_SB(b, h) + boff + n * 2048 + k * 1024); } while (0)
; #define PG8_MMA(ai, bj, At, Bt) do { __builtin_amdgcn_s_setprio(1); _Pragma("unroll") for (int m = 0; m < 4; ++m) _Pragma("unroll") for (int n = 0; n < 2; ++n) _Pragma("unroll") for (int k = 0; k < 2; ++k) \
;         acc[ai][bj][m][n] = __builtin_amdgcn_mfma_f32_16x16x32_bf16(Bt[n][k], At[m][k], acc[ai][bj][m][n], 0, 0, 0); __builtin_amdgcn_s_setprio(0); } while (0)
; #define PG8_WAIT_V(n) asm volatile("s_waitcnt vmcnt(" #n ")" ::: "memory")
; #define PG8_WAIT_L(n) asm volatile("s_waitcnt lgkmcnt(" #n ")" ::: "memory")
; template <class Epi, class Sched, bool ALIGN_EPI = false, bool SP2 = false>
; __device__ __forceinline__ void gemm_phase(PG8_LAS unsigned char* lds, const Gemm g, const Sched& S, const Epi& E) {
;     ...
;             const bool last = (t == nt - 2);
;             const char* a1 = cA + (size_t)(t + 1) * kstep;
;             const char* a2 = last ? nA : cA + (size_t)(t + 2) * kstep; const char* b2 = last ? nB : cB + (size_t)(t + 2) * kstep;
;             const char* a3 = a2 + kstep; const char* b3 = b2 + kstep;
;             if (last && has_next) S.a_ready(nxt);
;             if constexpr (SP2) {
;             PG8_LDB(B0, 0, 0); PG8_LDB(B1, 0, 1); PG8_SCHED; PG8_LDA(At, 0, 0); PG8_STAGE(PG8_SA(1, 1), a1 + hstep, voffA);
;             PG8_WAIT_V(8); PG8_WAIT_L(0); PG8_BAR; PG8_MMA(0, 0, At, B0); PG8_MMA(0, 1, At, B1); PG8_BAR; PG8_SCHED;
;             PG8_LDA(At, 0, 1); PG8_STAGE(PG8_SB(0, 0), b2, voffB); PG8_STAGE(PG8_SB(0, 1), b2 + hstep, voffB); PG8_STAGE(PG8_SA(0, 0), a2, voffA);
;             PG8_WAIT_V(8); PG8_WAIT_L(0); PG8_BAR; PG8_MMA(1, 0, At, B0); PG8_MMA(1, 1, At, B1); PG8_BAR; PG8_SCHED;
.LBB0_1947:
	v_add_u32_e32 v178, s53, v216
	v_add_u32_e32 v194, s54, v216
	ds_read_b128 v[138:141], v178
	ds_read_b128 v[142:145], v178 offset:1024
	ds_read_b128 v[146:149], v178 offset:2048
	ds_read_b128 v[178:181], v178 offset:3072
	ds_read_b128 v[182:185], v194
	ds_read_b128 v[186:189], v194 offset:1024
	ds_read_b128 v[190:193], v194 offset:2048
	ds_read_b128 v[194:197], v194 offset:3072
	s_cmp_eq_u32 s47, s10
	v_lshl_add_u64 v[198:199], v[136:137], 0, s[20:21]
	s_cselect_b64 vcc, -1, 0
	s_add_i32 s10, s10, 2
	v_cndmask_b32_e32 v215, v199, v175, vcc
	v_cndmask_b32_e32 v214, v198, v174, vcc
	v_cndmask_b32_e32 v237, v135, v177, vcc
	v_cndmask_b32_e32 v236, v134, v176, vcc
	v_lshl_add_u64 v[238:239], v[136:137], 0, v[168:169]
	s_add_i32 m0, s34, 0xc000
	ds_read_b128 v[198:201], v218
	ds_read_b128 v[202:205], v218 offset:1024
	ds_read_b128 v[206:209], v218 offset:2048
	ds_read_b128 v[210:213], v218 offset:3072
	ds_read_b128 v[220:223], v218 offset:4096
	ds_read_b128 v[224:227], v218 offset:5120
	ds_read_b128 v[228:231], v218 offset:6144
	ds_read_b128 v[232:235], v218 offset:7168
	global_load_lds_dwordx4 v[238:239], off
	s_add_i32 m0, s34, 0xe000
	v_lshl_add_u64 v[238:239], v[136:137], 0, v[166:167]
	global_load_lds_dwordx4 v[238:239], off
	s_waitcnt vmcnt(8) lgkmcnt(0)
	s_setprio 1
	s_barrier
	v_mfma_f32_16x16x32_bf16 v[130:133], v[138:141], v[198:201], v[130:133]
	v_mfma_f32_16x16x32_bf16 v[126:129], v[146:149], v[198:201], v[126:129]
	v_mfma_f32_16x16x32_bf16 v[114:117], v[138:141], v[206:209], v[114:117]
	v_mfma_f32_16x16x32_bf16 v[110:113], v[146:149], v[206:209], v[110:113]
	v_mfma_f32_16x16x32_bf16 v[98:101], v[138:141], v[220:223], v[98:101]
	v_mfma_f32_16x16x32_bf16 v[94:97], v[146:149], v[220:223], v[94:97]
	v_mfma_f32_16x16x32_bf16 v[82:85], v[138:141], v[228:231], v[82:85]
	v_mfma_f32_16x16x32_bf16 v[78:81], v[146:149], v[228:231], v[78:81]
	v_mfma_f32_16x16x32_bf16 v[130:133], v[142:145], v[202:205], v[130:133]
	v_mfma_f32_16x16x32_bf16 v[126:129], v[178:181], v[202:205], v[126:129]
	v_mfma_f32_16x16x32_bf16 v[114:117], v[142:145], v[210:213], v[114:117]
	v_mfma_f32_16x16x32_bf16 v[110:113], v[178:181], v[210:213], v[110:113]
	v_mfma_f32_16x16x32_bf16 v[98:101], v[142:145], v[224:227], v[98:101]
	v_mfma_f32_16x16x32_bf16 v[94:97], v[178:181], v[224:227], v[94:97]
	v_mfma_f32_16x16x32_bf16 v[82:85], v[142:145], v[232:235], v[82:85]
	v_mfma_f32_16x16x32_bf16 v[78:81], v[178:181], v[232:235], v[78:81]
	v_mfma_f32_16x16x32_bf16 v[122:125], v[182:185], v[198:201], v[122:125]
	v_mfma_f32_16x16x32_bf16 v[118:121], v[190:193], v[198:201], v[118:121]
	v_mfma_f32_16x16x32_bf16 v[106:109], v[182:185], v[206:209], v[106:109]
	v_mfma_f32_16x16x32_bf16 v[102:105], v[190:193], v[206:209], v[102:105]
	v_mfma_f32_16x16x32_bf16 v[90:93], v[182:185], v[220:223], v[90:93]
	v_mfma_f32_16x16x32_bf16 v[86:89], v[190:193], v[220:223], v[86:89]
	v_mfma_f32_16x16x32_bf16 v[74:77], v[182:185], v[228:231], v[74:77]
	v_mfma_f32_16x16x32_bf16 v[70:73], v[190:193], v[228:231], v[70:73]
	v_mfma_f32_16x16x32_bf16 v[122:125], v[186:189], v[202:205], v[122:125]
	v_mfma_f32_16x16x32_bf16 v[118:121], v[194:197], v[202:205], v[118:121]
	v_mfma_f32_16x16x32_bf16 v[106:109], v[186:189], v[210:213], v[106:109]
	v_mfma_f32_16x16x32_bf16 v[102:105], v[194:197], v[210:213], v[102:105]
	v_mfma_f32_16x16x32_bf16 v[90:93], v[186:189], v[224:227], v[90:93]
	v_mfma_f32_16x16x32_bf16 v[86:89], v[194:197], v[224:227], v[86:89]
	v_mfma_f32_16x16x32_bf16 v[74:77], v[186:189], v[232:235], v[74:77]
	v_mfma_f32_16x16x32_bf16 v[70:73], v[194:197], v[232:235], v[70:73]
	s_setprio 0
	s_barrier
	s_add_i32 s11, s53, s29
	v_lshl_add_u64 v[238:239], v[236:237], 0, v[158:159]
	s_mov_b32 m0, s11
	ds_read_b128 v[198:201], v218 offset:16384
	ds_read_b128 v[202:205], v218 offset:17408
	ds_read_b128 v[206:209], v218 offset:18432
	ds_read_b128 v[210:213], v218 offset:19456
	ds_read_b128 v[220:223], v218 offset:20480
	ds_read_b128 v[224:227], v218 offset:21504
	ds_read_b128 v[228:231], v218 offset:22528
	ds_read_b128 v[232:235], v218 offset:23552
	global_load_lds_dwordx4 v[238:239], off
	v_lshl_add_u64 v[240:241], v[236:237], 0, v[162:163]
	s_add_i32 m0, s11, 0x2000
	v_lshl_add_u64 v[236:237], v[236:237], 0, s[12:13]
	s_add_i32 s11, s54, s29
	global_load_lds_dwordx4 v[240:241], off
	v_lshl_add_u64 v[242:243], v[236:237], 0, v[158:159]
	s_mov_b32 m0, s11
	v_lshl_add_u64 v[236:237], v[236:237], 0, v[162:163]
	global_load_lds_dwordx4 v[242:243], off
	s_add_i32 m0, s11, 0x2000
	v_lshl_add_u64 v[244:245], v[214:215], 0, v[154:155]
	global_load_lds_dwordx4 v[236:237], off
	s_mov_b32 m0, s34
	v_lshl_add_u64 v[246:247], v[214:215], 0, v[160:161]
	global_load_lds_dwordx4 v[244:245], off
	s_mov_b32 m0, s35
	s_nop 0
	global_load_lds_dwordx4 v[246:247], off
	s_waitcnt vmcnt(8) lgkmcnt(0)
	s_setprio 1
	s_barrier
; #define PG8_STAGE(bufoff, gbase, voff) do { _Pragma("unroll") for (int _i = 0; _i < 2; ++_i) \
;         __builtin_amdgcn_global_load_lds((const unsigned*)((const char*)(gbase) + (voff)[_i]), (PG8_LAS unsigned*)(lds + (bufoff) + ldsw + _i * 8192), 16, 0, 0); } while (0)
; #define PG8_LDA(dst, b, h) do { _Pragma("unroll") for (int m = 0; m < 4; ++m) _Pragma("unroll") for (int k = 0; k < 2; ++k) dst[m][k] = *(const PG8_LAS bf16x8*)(lds + PG8_SA(b, h) + aoff + m * 2048 + k * 1024); } while (0)
; #define PG8_LDB(dst, b, h) do { _Pragma("unroll") for (int n = 0; n < 2; ++n) _Pragma("unroll") for (int k = 0; k < 2; ++k) dst[n][k] = *(const PG8_LAS bf16x8*)(lds + PG8_SB(b, h) + boff + n * 2048 + k * 1024); } while (0)
; #define PG8_MMA(ai, bj, At, Bt) do { __builtin_amdgcn_s_setprio(1); _Pragma("unroll") for (int m = 0; m < 4; ++m) _Pragma("unroll") for (int n = 0; n < 2; ++n) _Pragma("unroll") for (int k = 0; k < 2; ++k) \
;         acc[ai][bj][m][n] = __builtin_amdgcn_mfma_f32_16x16x32_bf16(Bt[n][k], At[m][k], acc[ai][bj][m][n], 0, 0, 0); __builtin_amdgcn_s_setprio(0); } while (0)
; #define PG8_WAIT_V(n) asm volatile("s_waitcnt vmcnt(" #n ")" ::: "memory")
; #define PG8_WAIT_L(n) asm volatile("s_waitcnt lgkmcnt(" #n ")" ::: "memory")
; #define PG8_BAR __builtin_amdgcn_s_barrier()
; #define PG8_SCHED __builtin_amdgcn_sched_barrier(0)
; template <class Epi, class Sched, bool ALIGN_EPI = false, bool SP2 = false>
; __device__ __forceinline__ void gemm_phase(PG8_LAS unsigned char* lds, const Gemm g, const Sched& S, const Epi& E) {
;     ...
;             PG8_WAIT_V(8); PG8_WAIT_L(0); PG8_BAR; PG8_MMA(1, 0, At, B0); PG8_MMA(1, 1, At, B1); PG8_BAR; PG8_SCHED;
;             PG8_LDB(B0, 1, 0); PG8_LDB(B1, 1, 1); PG8_SCHED; PG8_LDA(At, 1, 0); PG8_STAGE(PG8_SA(0, 1), a2 + hstep, voffA);
;             PG8_WAIT_V(8); PG8_WAIT_L(0); PG8_BAR; PG8_MMA(0, 0, At, B0); PG8_MMA(0, 1, At, B1); PG8_BAR; PG8_SCHED;
	v_mfma_f32_16x16x32_bf16 v[66:69], v[138:141], v[198:201], v[66:69]
	v_mfma_f32_16x16x32_bf16 v[62:65], v[146:149], v[198:201], v[62:65]
	v_mfma_f32_16x16x32_bf16 v[50:53], v[138:141], v[206:209], v[50:53]
	v_mfma_f32_16x16x32_bf16 v[46:49], v[146:149], v[206:209], v[46:49]
	v_mfma_f32_16x16x32_bf16 v[34:37], v[138:141], v[220:223], v[34:37]
	v_mfma_f32_16x16x32_bf16 v[30:33], v[146:149], v[220:223], v[30:33]
	v_mfma_f32_16x16x32_bf16 v[18:21], v[138:141], v[228:231], v[18:21]
	v_mfma_f32_16x16x32_bf16 v[14:17], v[146:149], v[228:231], v[14:17]
	v_mfma_f32_16x16x32_bf16 v[66:69], v[142:145], v[202:205], v[66:69]
	v_mfma_f32_16x16x32_bf16 v[62:65], v[178:181], v[202:205], v[62:65]
	v_mfma_f32_16x16x32_bf16 v[50:53], v[142:145], v[210:213], v[50:53]
	v_mfma_f32_16x16x32_bf16 v[46:49], v[178:181], v[210:213], v[46:49]
	v_mfma_f32_16x16x32_bf16 v[34:37], v[142:145], v[224:227], v[34:37]
	v_mfma_f32_16x16x32_bf16 v[30:33], v[178:181], v[224:227], v[30:33]
	v_mfma_f32_16x16x32_bf16 v[18:21], v[142:145], v[232:235], v[18:21]
	v_mfma_f32_16x16x32_bf16 v[14:17], v[178:181], v[232:235], v[14:17]
	v_mfma_f32_16x16x32_bf16 v[58:61], v[182:185], v[198:201], v[58:61]
	v_mfma_f32_16x16x32_bf16 v[54:57], v[190:193], v[198:201], v[54:57]
	v_mfma_f32_16x16x32_bf16 v[42:45], v[182:185], v[206:209], v[42:45]
	v_mfma_f32_16x16x32_bf16 v[38:41], v[190:193], v[206:209], v[38:41]
	v_mfma_f32_16x16x32_bf16 v[26:29], v[182:185], v[220:223], v[26:29]
	v_mfma_f32_16x16x32_bf16 v[22:25], v[190:193], v[220:223], v[22:25]
	v_mfma_f32_16x16x32_bf16 v[10:13], v[182:185], v[228:231], v[10:13]
	v_mfma_f32_16x16x32_bf16 v[6:9], v[190:193], v[228:231], v[6:9]
	v_mfma_f32_16x16x32_bf16 v[58:61], v[186:189], v[202:205], v[58:61]
	v_mfma_f32_16x16x32_bf16 v[54:57], v[194:197], v[202:205], v[54:57]
	v_mfma_f32_16x16x32_bf16 v[42:45], v[186:189], v[210:213], v[42:45]
	v_mfma_f32_16x16x32_bf16 v[38:41], v[194:197], v[210:213], v[38:41]
	v_mfma_f32_16x16x32_bf16 v[26:29], v[186:189], v[224:227], v[26:29]
	v_mfma_f32_16x16x32_bf16 v[22:25], v[194:197], v[224:227], v[22:25]
	v_mfma_f32_16x16x32_bf16 v[10:13], v[186:189], v[232:235], v[10:13]
	v_mfma_f32_16x16x32_bf16 v[6:9], v[194:197], v[232:235], v[6:9]
	s_setprio 0
	s_barrier
	s_add_i32 s11, 0, 0x18000
	s_add_i32 s31, 0, 0x1c000
	v_add_u32_e32 v178, s11, v216
	v_add_u32_e32 v194, s31, v216
	ds_read_b128 v[138:141], v178
	ds_read_b128 v[142:145], v178 offset:1024
	ds_read_b128 v[146:149], v178 offset:2048
	ds_read_b128 v[178:181], v178 offset:3072
	ds_read_b128 v[182:185], v194
	ds_read_b128 v[186:189], v194 offset:1024
	ds_read_b128 v[190:193], v194 offset:2048
	ds_read_b128 v[194:197], v194 offset:3072
	v_lshl_add_u64 v[214:215], v[214:215], 0, s[12:13]
	s_mov_b32 m0, s36
	v_lshl_add_u64 v[248:249], v[214:215], 0, v[154:155]
	ds_read_b128 v[198:201], v218 offset:32768
	ds_read_b128 v[202:205], v218 offset:33792
	ds_read_b128 v[206:209], v218 offset:34816
	ds_read_b128 v[210:213], v218 offset:35840
	ds_read_b128 v[220:223], v218 offset:36864
	ds_read_b128 v[224:227], v218 offset:37888
	ds_read_b128 v[228:231], v218 offset:38912
	ds_read_b128 v[232:235], v218 offset:39936
	global_load_lds_dwordx4 v[248:249], off
	s_mov_b32 m0, s37
	v_lshl_add_u64 v[214:215], v[214:215], 0, v[160:161]
	global_load_lds_dwordx4 v[214:215], off
	s_waitcnt vmcnt(8) lgkmcnt(0)
	s_setprio 1
	s_barrier
; #define PG8_STAGE(bufoff, gbase, voff) do { _Pragma("unroll") for (int _i = 0; _i < 2; ++_i) \
;         __builtin_amdgcn_global_load_lds((const unsigned*)((const char*)(gbase) + (voff)[_i]), (PG8_LAS unsigned*)(lds + (bufoff) + ldsw + _i * 8192), 16, 0, 0); } while (0)
; #define PG8_LDA(dst, b, h) do { _Pragma("unroll") for (int m = 0; m < 4; ++m) _Pragma("unroll") for (int k = 0; k < 2; ++k) dst[m][k] = *(const PG8_LAS bf16x8*)(lds + PG8_SA(b, h) + aoff + m * 2048 + k * 1024); } while (0)
; #define PG8_MMA(ai, bj, At, Bt) do { __builtin_amdgcn_s_setprio(1); _Pragma("unroll") for (int m = 0; m < 4; ++m) _Pragma("unroll") for (int n = 0; n < 2; ++n) _Pragma("unroll") for (int k = 0; k < 2; ++k) \
;         acc[ai][bj][m][n] = __builtin_amdgcn_mfma_f32_16x16x32_bf16(Bt[n][k], At[m][k], acc[ai][bj][m][n], 0, 0, 0); __builtin_amdgcn_s_setprio(0); } while (0)
; #define PG8_WAIT_V(n) asm volatile("s_waitcnt vmcnt(" #n ")" ::: "memory")
; #define PG8_WAIT_L(n) asm volatile("s_waitcnt lgkmcnt(" #n ")" ::: "memory")
; #define PG8_BAR __builtin_amdgcn_s_barrier()
; #define PG8_SCHED __builtin_amdgcn_sched_barrier(0)
; template <class Epi, class Sched, bool ALIGN_EPI = false, bool SP2 = false>
; __device__ __forceinline__ void gemm_phase(PG8_LAS unsigned char* lds, const Gemm g, const Sched& S, const Epi& E) {
;     ...
;             PG8_WAIT_V(8); PG8_WAIT_L(0); PG8_BAR; PG8_MMA(0, 0, At, B0); PG8_MMA(0, 1, At, B1); PG8_BAR; PG8_SCHED;
;             PG8_LDA(At, 1, 1); PG8_STAGE(PG8_SB(1, 0), b3, voffB); PG8_STAGE(PG8_SB(1, 1), b3 + hstep, voffB); PG8_STAGE(PG8_SA(1, 0), a3, voffA);
;             PG8_WAIT_V(8); PG8_WAIT_L(0); PG8_BAR; PG8_MMA(1, 0, At, B0); PG8_MMA(1, 1, At, B1); PG8_BAR; PG8_SCHED;
	v_mfma_f32_16x16x32_bf16 v[130:133], v[138:141], v[198:201], v[130:133]
	v_mfma_f32_16x16x32_bf16 v[126:129], v[146:149], v[198:201], v[126:129]
	v_mfma_f32_16x16x32_bf16 v[114:117], v[138:141], v[206:209], v[114:117]
	v_mfma_f32_16x16x32_bf16 v[110:113], v[146:149], v[206:209], v[110:113]
	v_mfma_f32_16x16x32_bf16 v[98:101], v[138:141], v[220:223], v[98:101]
	v_mfma_f32_16x16x32_bf16 v[94:97], v[146:149], v[220:223], v[94:97]
	v_mfma_f32_16x16x32_bf16 v[82:85], v[138:141], v[228:231], v[82:85]
	v_mfma_f32_16x16x32_bf16 v[78:81], v[146:149], v[228:231], v[78:81]
	v_mfma_f32_16x16x32_bf16 v[130:133], v[142:145], v[202:205], v[130:133]
	v_mfma_f32_16x16x32_bf16 v[126:129], v[178:181], v[202:205], v[126:129]
	v_mfma_f32_16x16x32_bf16 v[114:117], v[142:145], v[210:213], v[114:117]
	v_mfma_f32_16x16x32_bf16 v[110:113], v[178:181], v[210:213], v[110:113]
	v_mfma_f32_16x16x32_bf16 v[98:101], v[142:145], v[224:227], v[98:101]
	v_mfma_f32_16x16x32_bf16 v[94:97], v[178:181], v[224:227], v[94:97]
	v_mfma_f32_16x16x32_bf16 v[82:85], v[142:145], v[232:235], v[82:85]
	v_mfma_f32_16x16x32_bf16 v[78:81], v[178:181], v[232:235], v[78:81]
	v_mfma_f32_16x16x32_bf16 v[122:125], v[182:185], v[198:201], v[122:125]
	v_mfma_f32_16x16x32_bf16 v[118:121], v[190:193], v[198:201], v[118:121]
	v_mfma_f32_16x16x32_bf16 v[106:109], v[182:185], v[206:209], v[106:109]
	v_mfma_f32_16x16x32_bf16 v[102:105], v[190:193], v[206:209], v[102:105]
	v_mfma_f32_16x16x32_bf16 v[90:93], v[182:185], v[220:223], v[90:93]
	v_mfma_f32_16x16x32_bf16 v[86:89], v[190:193], v[220:223], v[86:89]
	v_mfma_f32_16x16x32_bf16 v[74:77], v[182:185], v[228:231], v[74:77]
	v_mfma_f32_16x16x32_bf16 v[70:73], v[190:193], v[228:231], v[70:73]
	v_mfma_f32_16x16x32_bf16 v[122:125], v[186:189], v[202:205], v[122:125]
	v_mfma_f32_16x16x32_bf16 v[118:121], v[194:197], v[202:205], v[118:121]
	v_mfma_f32_16x16x32_bf16 v[106:109], v[186:189], v[210:213], v[106:109]
	v_mfma_f32_16x16x32_bf16 v[102:105], v[194:197], v[210:213], v[102:105]
	v_mfma_f32_16x16x32_bf16 v[90:93], v[186:189], v[224:227], v[90:93]
	v_mfma_f32_16x16x32_bf16 v[86:89], v[194:197], v[224:227], v[86:89]
	v_mfma_f32_16x16x32_bf16 v[74:77], v[186:189], v[232:235], v[74:77]
	v_mfma_f32_16x16x32_bf16 v[70:73], v[194:197], v[232:235], v[70:73]
	s_setprio 0
	s_barrier
	s_add_i32 s11, s11, s29
	s_add_i32 m0, s11, 0xffffff80
	ds_read_b128 v[198:201], v218 offset:49152
	ds_read_b128 v[202:205], v218 offset:50176
	ds_read_b128 v[206:209], v218 offset:51200
	ds_read_b128 v[210:213], v218 offset:52224
	global_load_lds_dwordx4 v[238:239], off offset:128
	s_add_i32 m0, s11, 0x1f80
	s_add_i32 s11, s31, s29
	global_load_lds_dwordx4 v[240:241], off offset:128
	s_add_i32 m0, s11, 0xffffff80
	ds_read_b128 v[232:235], v218 offset:56320
	global_load_lds_dwordx4 v[242:243], off offset:128
	s_add_i32 m0, s11, 0x1f80
	ds_read_b128 v[228:231], v218 offset:55296
	global_load_lds_dwordx4 v[236:237], off offset:128
	s_add_i32 m0, s41, 0xffffff80
	ds_read_b128 v[224:227], v218 offset:54272
	global_load_lds_dwordx4 v[244:245], off offset:128
	s_add_i32 m0, s44, 0xffffff80
	ds_read_b128 v[220:223], v218 offset:53248
	global_load_lds_dwordx4 v[246:247], off offset:128
	s_waitcnt vmcnt(8) lgkmcnt(0)
	s_setprio 1
	s_barrier
	v_mfma_f32_16x16x32_bf16 v[66:69], v[138:141], v[198:201], v[66:69]
	v_mfma_f32_16x16x32_bf16 v[62:65], v[146:149], v[198:201], v[62:65]
	v_mfma_f32_16x16x32_bf16 v[50:53], v[138:141], v[206:209], v[50:53]
	v_mfma_f32_16x16x32_bf16 v[46:49], v[146:149], v[206:209], v[46:49]
	v_mfma_f32_16x16x32_bf16 v[34:37], v[138:141], v[220:223], v[34:37]
	v_mfma_f32_16x16x32_bf16 v[30:33], v[146:149], v[220:223], v[30:33]
	v_mfma_f32_16x16x32_bf16 v[18:21], v[138:141], v[228:231], v[18:21]
	v_mfma_f32_16x16x32_bf16 v[14:17], v[146:149], v[228:231], v[14:17]
	v_mfma_f32_16x16x32_bf16 v[66:69], v[142:145], v[202:205], v[66:69]
	v_mfma_f32_16x16x32_bf16 v[62:65], v[178:181], v[202:205], v[62:65]
	v_mfma_f32_16x16x32_bf16 v[50:53], v[142:145], v[210:213], v[50:53]
	v_mfma_f32_16x16x32_bf16 v[46:49], v[178:181], v[210:213], v[46:49]
	v_mfma_f32_16x16x32_bf16 v[34:37], v[142:145], v[224:227], v[34:37]
	v_mfma_f32_16x16x32_bf16 v[30:33], v[178:181], v[224:227], v[30:33]
	v_mfma_f32_16x16x32_bf16 v[18:21], v[142:145], v[232:235], v[18:21]
	v_mfma_f32_16x16x32_bf16 v[14:17], v[178:181], v[232:235], v[14:17]
	v_mfma_f32_16x16x32_bf16 v[58:61], v[182:185], v[198:201], v[58:61]
	v_mfma_f32_16x16x32_bf16 v[54:57], v[190:193], v[198:201], v[54:57]
	v_mfma_f32_16x16x32_bf16 v[42:45], v[182:185], v[206:209], v[42:45]
	v_mfma_f32_16x16x32_bf16 v[38:41], v[190:193], v[206:209], v[38:41]
	v_mfma_f32_16x16x32_bf16 v[26:29], v[182:185], v[220:223], v[26:29]
	v_mfma_f32_16x16x32_bf16 v[22:25], v[190:193], v[220:223], v[22:25]
	v_mfma_f32_16x16x32_bf16 v[10:13], v[182:185], v[228:231], v[10:13]
	v_mfma_f32_16x16x32_bf16 v[6:9], v[190:193], v[228:231], v[6:9]
	v_mfma_f32_16x16x32_bf16 v[58:61], v[186:189], v[202:205], v[58:61]
	v_mfma_f32_16x16x32_bf16 v[54:57], v[194:197], v[202:205], v[54:57]
	v_mfma_f32_16x16x32_bf16 v[42:45], v[186:189], v[210:213], v[42:45]
	v_mfma_f32_16x16x32_bf16 v[38:41], v[194:197], v[210:213], v[38:41]
	v_mfma_f32_16x16x32_bf16 v[26:29], v[186:189], v[224:227], v[26:29]
	v_mfma_f32_16x16x32_bf16 v[22:25], v[194:197], v[224:227], v[22:25]
	v_mfma_f32_16x16x32_bf16 v[10:13], v[186:189], v[232:235], v[10:13]
	v_mfma_f32_16x16x32_bf16 v[6:9], v[194:197], v[232:235], v[6:9]
	s_setprio 0
	s_barrier
	v_lshl_add_u64 v[134:135], v[134:135], 0, s[26:27]
	s_cmp_ge_i32 s10, s46
	v_lshl_add_u64 v[136:137], v[136:137], 0, s[26:27]
	s_cbranch_scc0 .LBB0_1947
